# all s_setprio removed (GEMM K-loop MFMA-cluster priority toggles too): waves of a SIMD arbitrate at equal priority
# speedup vs baseline: 1.0113x; 1.0066x over previous
; #define STAGE(P_, BASE, br, kt) do { const u16* _gb = (BASE) + (long)(br) * K + (long)(kt) * BK; \
;     _Pragma("unroll") for (int _i = 0; _i < 2; ++_i) { \
;       __builtin_amdgcn_global_load_lds((const unsigned*)(_gb + (long)_i * 64 * K + lane_off), \
;         (unsigned*)((char*)(P_) + lds_wbase + _i * 8192), 16, 0, 0); } } while (0)
; #define LDA(dst, b, h) _Pragma("unroll") for (int m = 0; m < 4; ++m) _Pragma("unroll") for (int k = 0; k < 2; ++k) \
;     dst[m][k] = *reinterpret_cast<const bf16x8*>((char*)SA(b, h) + lds_byte(wr * 64 + m * 16 + fr, k * 32 + fq * 8))
; #define LDB(dst, b, h) _Pragma("unroll") for (int n = 0; n < 2; ++n) _Pragma("unroll") for (int k = 0; k < 2; ++k) \
;     dst[n][k] = *reinterpret_cast<const bf16x8*>((char*)SB(b, h) + lds_byte(wc * 32 + n * 16 + fr, k * 32 + fq * 8))
; #define MMA(ai, bj, At_, Bt_) do { __builtin_amdgcn_s_setprio(1); \
;     _Pragma("unroll") for (int m = 0; m < 4; ++m) _Pragma("unroll") for (int n = 0; n < 2; ++n) _Pragma("unroll") for (int k = 0; k < 2; ++k) \
;       acc[ai][bj][m][n] = __builtin_amdgcn_mfma_f32_16x16x32_bf16(At_[m][k], Bt_[n][k], acc[ai][bj][m][n], 0, 0, 0); \
;     __builtin_amdgcn_s_setprio(0); } while (0)
; #define WAIT_V(n) asm volatile("s_waitcnt vmcnt(" #n ")" ::: "memory")
; #define BAR __builtin_amdgcn_s_barrier()
; template <int PRE> ...
;     ...
;   for (int t = 0; t < nt; t += 2) {
;     LDB(B0, 0, 0); SCHED; LDA(At, 0, 0); STAGE(SA(1, 1), A, brow + HALF, t + 1);
;     WAIT_L(8); BAR; WAIT_L(0); MMA(0, 0, At, B0); BAR; SCHED;
;     LDB(B1, 0, 1); STAGEW(SB(0, 0), Bt, bcol, bcol_n, t + 2);
;     BAR; WAIT_L(0); MMA(0, 1, At, B1); BAR;
;     LDA(At, 0, 1); STAGEW(SA(0, 0), A, brow, brow_n, t + 2);
;     BAR; WAIT_L(0); MMA(1, 0, At, B0); BAR; SCHED;
;     STAGEW(SB(0, 1), Bt, bcol + HALF, bcol_n + HALF, t + 2);
;     WAIT_V(6); BAR; MMA(1, 1, At, B1); BAR;
;     LDB(B0, 1, 0); SCHED; LDA(At, 1, 0); STAGEW(SA(0, 1), A, brow + HALF, brow_n + HALF, t + 2);
;     WAIT_L(8); BAR; WAIT_L(0); MMA(0, 0, At, B0); BAR; SCHED;
;     LDB(B1, 1, 1); STAGEW(SB(1, 0), Bt, bcol, bcol_n, t + 3);
;     BAR; WAIT_L(0); MMA(0, 1, At, B1); BAR;
;     LDA(At, 1, 1); STAGEW(SA(1, 0), A, brow, brow_n, t + 3);
;     BAR; WAIT_L(0); MMA(1, 0, At, B0); BAR; SCHED;
;     STAGEW(SB(1, 1), Bt, bcol + HALF, bcol_n + HALF, t + 3);
;     WAIT_V(6); BAR; MMA(1, 1, At, B1); BAR;
;   }
.LBB0_181:
	v_add_u32_e32 v149, s81, v141
	ds_read_b128 v[136:139], v149
	ds_read_b128 v[150:153], v149 offset:1024
	ds_read_b128 v[154:157], v149 offset:2048
	ds_read_b128 v[158:161], v149 offset:3072
	s_add_i32 m0, s12, 0xc000
	ds_read_b128 v[168:171], v142
	ds_read_b128 v[172:175], v142 offset:1024
	ds_read_b128 v[176:179], v143
	ds_read_b128 v[180:183], v143 offset:1024
	ds_read_b128 v[184:187], v144
	ds_read_b128 v[188:191], v144 offset:1024
	ds_read_b128 v[192:195], v146
	ds_read_b128 v[210:213], v146 offset:1024
	global_load_lds_dwordx4 v[134:135], off
	v_lshl_add_u64 v[162:163], v[134:135], 0, s[86:87]
	s_add_i32 m0, s12, 0xe000
	s_nop 0
	global_load_lds_dwordx4 v[162:163], off
	s_waitcnt lgkmcnt(8)
	s_barrier
	s_waitcnt lgkmcnt(0)
	s_waitcnt lgkmcnt(0)
	v_mfma_f32_16x16x32_bf16 v[126:129], v[168:171], v[136:139], v[126:129]
	v_mfma_f32_16x16x32_bf16 v[122:125], v[168:171], v[154:157], v[122:125]
	v_mfma_f32_16x16x32_bf16 v[118:121], v[176:179], v[136:139], v[118:121]
	v_mfma_f32_16x16x32_bf16 v[114:117], v[176:179], v[154:157], v[114:117]
	v_mfma_f32_16x16x32_bf16 v[110:113], v[184:187], v[136:139], v[110:113]
	v_mfma_f32_16x16x32_bf16 v[106:109], v[184:187], v[154:157], v[106:109]
	v_mfma_f32_16x16x32_bf16 v[102:105], v[192:195], v[136:139], v[102:105]
	v_mfma_f32_16x16x32_bf16 v[98:101], v[192:195], v[154:157], v[98:101]
	v_mfma_f32_16x16x32_bf16 v[126:129], v[172:175], v[150:153], v[126:129]
	v_mfma_f32_16x16x32_bf16 v[122:125], v[172:175], v[158:161], v[122:125]
	v_mfma_f32_16x16x32_bf16 v[118:121], v[180:183], v[150:153], v[118:121]
	v_mfma_f32_16x16x32_bf16 v[114:117], v[180:183], v[158:161], v[114:117]
	v_mfma_f32_16x16x32_bf16 v[110:113], v[188:191], v[150:153], v[110:113]
	v_mfma_f32_16x16x32_bf16 v[106:109], v[188:191], v[158:161], v[106:109]
	v_mfma_f32_16x16x32_bf16 v[102:105], v[210:213], v[150:153], v[102:105]
	v_mfma_f32_16x16x32_bf16 v[98:101], v[210:213], v[158:161], v[98:101]
	s_barrier
	s_add_i32 s1, s38, 2
	s_cmp_lt_u32 s38, 30
	s_cselect_b64 s[2:3], -1, 0
	s_and_b64 vcc, s[2:3], exec
	s_cselect_b32 s6, s10, s11
	s_cselect_b32 s3, 0, 0xffffffe0
	s_cselect_b32 s40, s0, s31
	s_cselect_b32 s42, s36, s35
	s_cselect_b32 s2, s34, s37
	s_ashr_i32 s7, s6, 31
	s_lshl_b64 s[6:7], s[6:7], 12
	s_add_u32 s39, s52, s6
	s_addc_u32 s41, s53, s7
	s_add_i32 s18, s1, s3
	s_lshl_b64 s[6:7], s[18:19], 7
	s_add_u32 s44, s39, s6
	s_addc_u32 s45, s41, s7
	s_mov_b32 m0, s13
	v_add_u32_e32 v149, s82, v141
	v_lshl_add_u64 v[162:163], s[44:45], 0, v[130:131]
	ds_read_b128 v[214:217], v149
	ds_read_b128 v[218:221], v149 offset:1024
	ds_read_b128 v[222:225], v149 offset:2048
	ds_read_b128 v[226:229], v149 offset:3072
	global_load_lds_dwordx4 v[162:163], off
	v_lshl_add_u64 v[162:163], v[162:163], 0, s[86:87]
	s_mov_b32 m0, s14
	s_nop 0
	global_load_lds_dwordx4 v[162:163], off
	s_barrier
	s_waitcnt lgkmcnt(0)
	s_waitcnt lgkmcnt(0)
	v_mfma_f32_16x16x32_bf16 v[94:97], v[168:171], v[214:217], v[94:97]
	v_mfma_f32_16x16x32_bf16 v[90:93], v[168:171], v[222:225], v[90:93]
	v_mfma_f32_16x16x32_bf16 v[86:89], v[176:179], v[214:217], v[86:89]
	v_mfma_f32_16x16x32_bf16 v[82:85], v[176:179], v[222:225], v[82:85]
	v_mfma_f32_16x16x32_bf16 v[78:81], v[184:187], v[214:217], v[78:81]
	v_mfma_f32_16x16x32_bf16 v[74:77], v[184:187], v[222:225], v[74:77]
	v_mfma_f32_16x16x32_bf16 v[70:73], v[192:195], v[214:217], v[70:73]
	v_mfma_f32_16x16x32_bf16 v[64:67], v[192:195], v[222:225], v[64:67]
	v_mfma_f32_16x16x32_bf16 v[94:97], v[172:175], v[218:221], v[94:97]
	v_mfma_f32_16x16x32_bf16 v[90:93], v[172:175], v[226:229], v[90:93]
	v_mfma_f32_16x16x32_bf16 v[86:89], v[180:183], v[218:221], v[86:89]
	v_mfma_f32_16x16x32_bf16 v[82:85], v[180:183], v[226:229], v[82:85]
	v_mfma_f32_16x16x32_bf16 v[78:81], v[188:191], v[218:221], v[78:81]
	v_mfma_f32_16x16x32_bf16 v[74:77], v[188:191], v[226:229], v[74:77]
	v_mfma_f32_16x16x32_bf16 v[70:73], v[210:213], v[218:221], v[70:73]
	v_mfma_f32_16x16x32_bf16 v[64:67], v[210:213], v[226:229], v[64:67]
	s_ashr_i32 s41, s40, 31
	s_lshl_b64 s[40:41], s[40:41], 12
	s_add_u32 s3, s50, s40
	s_addc_u32 s18, s51, s41
	s_add_u32 s40, s3, s6
	s_addc_u32 s41, s18, s7
	s_mov_b32 m0, s12
	v_lshl_add_u64 v[162:163], s[40:41], 0, v[130:131]
	s_barrier
	ds_read_b128 v[168:171], v142 offset:16384
	ds_read_b128 v[172:175], v142 offset:17408
	ds_read_b128 v[176:179], v143 offset:16384
	ds_read_b128 v[180:183], v143 offset:17408
	ds_read_b128 v[184:187], v144 offset:16384
	ds_read_b128 v[188:191], v144 offset:17408
	ds_read_b128 v[192:195], v146 offset:16384
	ds_read_b128 v[210:213], v146 offset:17408
	global_load_lds_dwordx4 v[162:163], off
	v_lshl_add_u64 v[162:163], v[162:163], 0, s[86:87]
	s_mov_b32 m0, s15
	s_nop 0
	global_load_lds_dwordx4 v[162:163], off
	s_barrier
	s_waitcnt lgkmcnt(0)
	s_waitcnt lgkmcnt(0)
	v_mfma_f32_16x16x32_bf16 v[60:63], v[168:171], v[136:139], v[60:63]
	v_mfma_f32_16x16x32_bf16 v[56:59], v[168:171], v[154:157], v[56:59]
	v_mfma_f32_16x16x32_bf16 v[52:55], v[176:179], v[136:139], v[52:55]
	v_mfma_f32_16x16x32_bf16 v[48:51], v[176:179], v[154:157], v[48:51]
	v_mfma_f32_16x16x32_bf16 v[44:47], v[184:187], v[136:139], v[44:47]
	v_mfma_f32_16x16x32_bf16 v[40:43], v[184:187], v[154:157], v[40:43]
	v_mfma_f32_16x16x32_bf16 v[36:39], v[192:195], v[136:139], v[36:39]
	v_mfma_f32_16x16x32_bf16 v[32:35], v[192:195], v[154:157], v[32:35]
	v_mfma_f32_16x16x32_bf16 v[60:63], v[172:175], v[150:153], v[60:63]
	v_mfma_f32_16x16x32_bf16 v[56:59], v[172:175], v[158:161], v[56:59]
	v_mfma_f32_16x16x32_bf16 v[52:55], v[180:183], v[150:153], v[52:55]
	v_mfma_f32_16x16x32_bf16 v[48:51], v[180:183], v[158:161], v[48:51]
	v_mfma_f32_16x16x32_bf16 v[44:47], v[188:191], v[150:153], v[44:47]
	v_mfma_f32_16x16x32_bf16 v[40:43], v[188:191], v[158:161], v[40:43]
	v_mfma_f32_16x16x32_bf16 v[36:39], v[210:213], v[150:153], v[36:39]
	v_mfma_f32_16x16x32_bf16 v[32:35], v[210:213], v[158:161], v[32:35]
	s_barrier
; #define STAGE(P_, BASE, br, kt) do { const u16* _gb = (BASE) + (long)(br) * K + (long)(kt) * BK; \
;     _Pragma("unroll") for (int _i = 0; _i < 2; ++_i) { \
;       __builtin_amdgcn_global_load_lds((const unsigned*)(_gb + (long)_i * 64 * K + lane_off), \
;         (unsigned*)((char*)(P_) + lds_wbase + _i * 8192), 16, 0, 0); } } while (0)
; #define LDA(dst, b, h) _Pragma("unroll") for (int m = 0; m < 4; ++m) _Pragma("unroll") for (int k = 0; k < 2; ++k) \
;     dst[m][k] = *reinterpret_cast<const bf16x8*>((char*)SA(b, h) + lds_byte(wr * 64 + m * 16 + fr, k * 32 + fq * 8))
; #define LDB(dst, b, h) _Pragma("unroll") for (int n = 0; n < 2; ++n) _Pragma("unroll") for (int k = 0; k < 2; ++k) \
;     dst[n][k] = *reinterpret_cast<const bf16x8*>((char*)SB(b, h) + lds_byte(wc * 32 + n * 16 + fr, k * 32 + fq * 8))
; #define MMA(ai, bj, At_, Bt_) do { __builtin_amdgcn_s_setprio(1); \
;     _Pragma("unroll") for (int m = 0; m < 4; ++m) _Pragma("unroll") for (int n = 0; n < 2; ++n) _Pragma("unroll") for (int k = 0; k < 2; ++k) \
;       acc[ai][bj][m][n] = __builtin_amdgcn_mfma_f32_16x16x32_bf16(At_[m][k], Bt_[n][k], acc[ai][bj][m][n], 0, 0, 0); \
;     __builtin_amdgcn_s_setprio(0); } while (0)
; #define WAIT_V(n) asm volatile("s_waitcnt vmcnt(" #n ")" ::: "memory")
; #define BAR __builtin_amdgcn_s_barrier()
; template <int PRE> ...
;     ...
;   for (int t = 0; t < nt; t += 2) {
;     LDB(B0, 0, 0); SCHED; LDA(At, 0, 0); STAGE(SA(1, 1), A, brow + HALF, t + 1);
;     WAIT_L(8); BAR; WAIT_L(0); MMA(0, 0, At, B0); BAR; SCHED;
;     LDB(B1, 0, 1); STAGEW(SB(0, 0), Bt, bcol, bcol_n, t + 2);
;     BAR; WAIT_L(0); MMA(0, 1, At, B1); BAR;
;     LDA(At, 0, 1); STAGEW(SA(0, 0), A, brow, brow_n, t + 2);
;     BAR; WAIT_L(0); MMA(1, 0, At, B0); BAR; SCHED;
;     STAGEW(SB(0, 1), Bt, bcol + HALF, bcol_n + HALF, t + 2);
;     WAIT_V(6); BAR; MMA(1, 1, At, B1); BAR;
;     LDB(B0, 1, 0); SCHED; LDA(At, 1, 0); STAGEW(SA(0, 1), A, brow + HALF, brow_n + HALF, t + 2);
;     WAIT_L(8); BAR; WAIT_L(0); MMA(0, 0, At, B0); BAR; SCHED;
;     LDB(B1, 1, 1); STAGEW(SB(1, 0), Bt, bcol, bcol_n, t + 3);
;     BAR; WAIT_L(0); MMA(0, 1, At, B1); BAR;
;     LDA(At, 1, 1); STAGEW(SA(1, 0), A, brow, brow_n, t + 3);
;     BAR; WAIT_L(0); MMA(1, 0, At, B0); BAR; SCHED;
;     STAGEW(SB(1, 1), Bt, bcol + HALF, bcol_n + HALF, t + 3);
;     WAIT_V(6); BAR; MMA(1, 1, At, B1); BAR;
;   }
	s_ashr_i32 s43, s42, 31
	s_lshl_b64 s[40:41], s[42:43], 12
	s_add_u32 s3, s52, s40
	s_addc_u32 s18, s53, s41
	s_add_u32 s40, s3, s6
	s_addc_u32 s41, s18, s7
	s_mov_b32 m0, s16
	v_lshl_add_u64 v[136:137], s[40:41], 0, v[130:131]
	global_load_lds_dwordx4 v[136:137], off
	v_lshl_add_u64 v[136:137], v[136:137], 0, s[86:87]
	s_mov_b32 m0, s17
	s_nop 0
	global_load_lds_dwordx4 v[136:137], off
	s_waitcnt vmcnt(6)
	s_barrier
	v_mfma_f32_16x16x32_bf16 v[28:31], v[168:171], v[214:217], v[28:31]
	v_mfma_f32_16x16x32_bf16 v[24:27], v[168:171], v[222:225], v[24:27]
	v_mfma_f32_16x16x32_bf16 v[20:23], v[176:179], v[214:217], v[20:23]
	v_mfma_f32_16x16x32_bf16 v[16:19], v[176:179], v[222:225], v[16:19]
	v_mfma_f32_16x16x32_bf16 v[12:15], v[184:187], v[214:217], v[12:15]
	v_mfma_f32_16x16x32_bf16 v[8:11], v[184:187], v[222:225], v[8:11]
	v_mfma_f32_16x16x32_bf16 v[4:7], v[192:195], v[214:217], v[4:7]
	v_mfma_f32_16x16x32_bf16 v[0:3], v[192:195], v[222:225], v[0:3]
	v_mfma_f32_16x16x32_bf16 v[28:31], v[172:175], v[218:221], v[28:31]
	v_mfma_f32_16x16x32_bf16 v[24:27], v[172:175], v[226:229], v[24:27]
	v_mfma_f32_16x16x32_bf16 v[20:23], v[180:183], v[218:221], v[20:23]
	v_mfma_f32_16x16x32_bf16 v[16:19], v[180:183], v[226:229], v[16:19]
	v_mfma_f32_16x16x32_bf16 v[12:15], v[188:191], v[218:221], v[12:15]
	v_mfma_f32_16x16x32_bf16 v[8:11], v[188:191], v[226:229], v[8:11]
	v_mfma_f32_16x16x32_bf16 v[4:7], v[210:213], v[218:221], v[4:7]
	v_mfma_f32_16x16x32_bf16 v[0:3], v[210:213], v[226:229], v[0:3]
	v_add_u32_e32 v149, s83, v141
	s_barrier
	ds_read_b128 v[136:139], v149
	ds_read_b128 v[150:153], v149 offset:1024
	ds_read_b128 v[154:157], v149 offset:2048
	ds_read_b128 v[158:161], v149 offset:3072
	s_ashr_i32 s3, s2, 31
	s_lshl_b64 s[2:3], s[2:3], 12
	s_add_u32 s2, s50, s2
	s_addc_u32 s3, s51, s3
	s_add_u32 s2, s2, s6
	s_addc_u32 s3, s3, s7
	s_mov_b32 m0, s21
	v_lshl_add_u64 v[162:163], s[2:3], 0, v[130:131]
	ds_read_b128 v[168:171], v142 offset:32768
	ds_read_b128 v[172:175], v142 offset:33792
	ds_read_b128 v[176:179], v143 offset:32768
	ds_read_b128 v[180:183], v143 offset:33792
	ds_read_b128 v[184:187], v144 offset:32768
	ds_read_b128 v[188:191], v144 offset:33792
	ds_read_b128 v[192:195], v146 offset:32768
	ds_read_b128 v[210:213], v146 offset:33792
	global_load_lds_dwordx4 v[162:163], off
	v_lshl_add_u64 v[162:163], v[162:163], 0, s[86:87]
	s_mov_b32 m0, s22
	s_nop 0
	global_load_lds_dwordx4 v[162:163], off
	s_waitcnt lgkmcnt(8)
	s_barrier
	s_waitcnt lgkmcnt(0)
	s_waitcnt lgkmcnt(0)
	v_mfma_f32_16x16x32_bf16 v[126:129], v[168:171], v[136:139], v[126:129]
	v_mfma_f32_16x16x32_bf16 v[122:125], v[168:171], v[154:157], v[122:125]
	v_mfma_f32_16x16x32_bf16 v[118:121], v[176:179], v[136:139], v[118:121]
	v_mfma_f32_16x16x32_bf16 v[114:117], v[176:179], v[154:157], v[114:117]
	v_mfma_f32_16x16x32_bf16 v[110:113], v[184:187], v[136:139], v[110:113]
	v_mfma_f32_16x16x32_bf16 v[106:109], v[184:187], v[154:157], v[106:109]
	v_mfma_f32_16x16x32_bf16 v[102:105], v[192:195], v[136:139], v[102:105]
	v_mfma_f32_16x16x32_bf16 v[98:101], v[192:195], v[154:157], v[98:101]
	v_mfma_f32_16x16x32_bf16 v[126:129], v[172:175], v[150:153], v[126:129]
	v_mfma_f32_16x16x32_bf16 v[122:125], v[172:175], v[158:161], v[122:125]
	v_mfma_f32_16x16x32_bf16 v[118:121], v[180:183], v[150:153], v[118:121]
	v_mfma_f32_16x16x32_bf16 v[114:117], v[180:183], v[158:161], v[114:117]
	v_mfma_f32_16x16x32_bf16 v[110:113], v[188:191], v[150:153], v[110:113]
	v_mfma_f32_16x16x32_bf16 v[106:109], v[188:191], v[158:161], v[106:109]
	v_mfma_f32_16x16x32_bf16 v[102:105], v[210:213], v[150:153], v[102:105]
	v_mfma_f32_16x16x32_bf16 v[98:101], v[210:213], v[158:161], v[98:101]
	s_barrier
	s_cmp_lt_u32 s38, 29
	s_cselect_b32 s2, s10, s11
	s_cselect_b32 s7, 0, 0xffffffe0
	s_cselect_b32 s6, s0, s31
	s_cselect_b32 s40, s36, s35
	s_ashr_i32 s3, s2, 31
	s_lshl_b64 s[2:3], s[2:3], 12
	s_add_u32 s39, s52, s2
	s_addc_u32 s41, s53, s3
	s_add_i32 s2, s7, s38
	s_add_i32 s18, s2, 3
	s_lshl_b64 s[2:3], s[18:19], 7
	s_add_u32 s38, s39, s2
	s_addc_u32 s39, s41, s3
	s_mov_b32 m0, s23
	v_add_u32_e32 v149, s84, v141
	v_lshl_add_u64 v[162:163], s[38:39], 0, v[130:131]
	ds_read_b128 v[214:217], v149
	ds_read_b128 v[218:221], v149 offset:1024
	ds_read_b128 v[222:225], v149 offset:2048
	ds_read_b128 v[226:229], v149 offset:3072
	global_load_lds_dwordx4 v[162:163], off
	v_lshl_add_u64 v[162:163], v[162:163], 0, s[86:87]
	s_mov_b32 m0, s24
	s_nop 0
	global_load_lds_dwordx4 v[162:163], off
	s_barrier
; #define STAGE(P_, BASE, br, kt) do { const u16* _gb = (BASE) + (long)(br) * K + (long)(kt) * BK; \
;     _Pragma("unroll") for (int _i = 0; _i < 2; ++_i) { \
;       __builtin_amdgcn_global_load_lds((const unsigned*)(_gb + (long)_i * 64 * K + lane_off), \
;         (unsigned*)((char*)(P_) + lds_wbase + _i * 8192), 16, 0, 0); } } while (0)
; #define LDA(dst, b, h) _Pragma("unroll") for (int m = 0; m < 4; ++m) _Pragma("unroll") for (int k = 0; k < 2; ++k) \
;     dst[m][k] = *reinterpret_cast<const bf16x8*>((char*)SA(b, h) + lds_byte(wr * 64 + m * 16 + fr, k * 32 + fq * 8))
; #define LDB(dst, b, h) _Pragma("unroll") for (int n = 0; n < 2; ++n) _Pragma("unroll") for (int k = 0; k < 2; ++k) \
;     dst[n][k] = *reinterpret_cast<const bf16x8*>((char*)SB(b, h) + lds_byte(wc * 32 + n * 16 + fr, k * 32 + fq * 8))
; #define MMA(ai, bj, At_, Bt_) do { __builtin_amdgcn_s_setprio(1); \
;     _Pragma("unroll") for (int m = 0; m < 4; ++m) _Pragma("unroll") for (int n = 0; n < 2; ++n) _Pragma("unroll") for (int k = 0; k < 2; ++k) \
;       acc[ai][bj][m][n] = __builtin_amdgcn_mfma_f32_16x16x32_bf16(At_[m][k], Bt_[n][k], acc[ai][bj][m][n], 0, 0, 0); \
;     __builtin_amdgcn_s_setprio(0); } while (0)
; #define WAIT_V(n) asm volatile("s_waitcnt vmcnt(" #n ")" ::: "memory")
; #define BAR __builtin_amdgcn_s_barrier()
; template <int PRE> ...
;     ...
;   for (int t = 0; t < nt; t += 2) {
;     LDB(B0, 0, 0); SCHED; LDA(At, 0, 0); STAGE(SA(1, 1), A, brow + HALF, t + 1);
;     WAIT_L(8); BAR; WAIT_L(0); MMA(0, 0, At, B0); BAR; SCHED;
;     LDB(B1, 0, 1); STAGEW(SB(0, 0), Bt, bcol, bcol_n, t + 2);
;     BAR; WAIT_L(0); MMA(0, 1, At, B1); BAR;
;     LDA(At, 0, 1); STAGEW(SA(0, 0), A, brow, brow_n, t + 2);
;     BAR; WAIT_L(0); MMA(1, 0, At, B0); BAR; SCHED;
;     STAGEW(SB(0, 1), Bt, bcol + HALF, bcol_n + HALF, t + 2);
;     WAIT_V(6); BAR; MMA(1, 1, At, B1); BAR;
;     LDB(B0, 1, 0); SCHED; LDA(At, 1, 0); STAGEW(SA(0, 1), A, brow + HALF, brow_n + HALF, t + 2);
;     WAIT_L(8); BAR; WAIT_L(0); MMA(0, 0, At, B0); BAR; SCHED;
;     LDB(B1, 1, 1); STAGEW(SB(1, 0), Bt, bcol, bcol_n, t + 3);
;     BAR; WAIT_L(0); MMA(0, 1, At, B1); BAR;
;     LDA(At, 1, 1); STAGEW(SA(1, 0), A, brow, brow_n, t + 3);
;     BAR; WAIT_L(0); MMA(1, 0, At, B0); BAR; SCHED;
;     STAGEW(SB(1, 1), Bt, bcol + HALF, bcol_n + HALF, t + 3);
;     WAIT_V(6); BAR; MMA(1, 1, At, B1); BAR;
;   }
;   if (wr == 0) BAR;
	s_waitcnt lgkmcnt(0)
	s_waitcnt lgkmcnt(0)
	v_mfma_f32_16x16x32_bf16 v[94:97], v[168:171], v[214:217], v[94:97]
	v_mfma_f32_16x16x32_bf16 v[90:93], v[168:171], v[222:225], v[90:93]
	v_mfma_f32_16x16x32_bf16 v[86:89], v[176:179], v[214:217], v[86:89]
	v_mfma_f32_16x16x32_bf16 v[82:85], v[176:179], v[222:225], v[82:85]
	v_mfma_f32_16x16x32_bf16 v[78:81], v[184:187], v[214:217], v[78:81]
	v_mfma_f32_16x16x32_bf16 v[74:77], v[184:187], v[222:225], v[74:77]
	v_mfma_f32_16x16x32_bf16 v[70:73], v[192:195], v[214:217], v[70:73]
	v_mfma_f32_16x16x32_bf16 v[64:67], v[192:195], v[222:225], v[64:67]
	v_mfma_f32_16x16x32_bf16 v[94:97], v[172:175], v[218:221], v[94:97]
	v_mfma_f32_16x16x32_bf16 v[90:93], v[172:175], v[226:229], v[90:93]
	v_mfma_f32_16x16x32_bf16 v[86:89], v[180:183], v[218:221], v[86:89]
	v_mfma_f32_16x16x32_bf16 v[82:85], v[180:183], v[226:229], v[82:85]
	v_mfma_f32_16x16x32_bf16 v[78:81], v[188:191], v[218:221], v[78:81]
	v_mfma_f32_16x16x32_bf16 v[74:77], v[188:191], v[226:229], v[74:77]
	v_mfma_f32_16x16x32_bf16 v[70:73], v[210:213], v[218:221], v[70:73]
	v_mfma_f32_16x16x32_bf16 v[64:67], v[210:213], v[226:229], v[64:67]
	s_ashr_i32 s7, s6, 31
	s_lshl_b64 s[6:7], s[6:7], 12
	s_add_u32 s6, s50, s6
	s_addc_u32 s7, s51, s7
	s_add_u32 s6, s6, s2
	s_addc_u32 s7, s7, s3
	s_mov_b32 m0, s25
	v_lshl_add_u64 v[162:163], s[6:7], 0, v[130:131]
	s_barrier
	ds_read_b128 v[168:171], v142 offset:49152
	ds_read_b128 v[172:175], v142 offset:50176
	ds_read_b128 v[176:179], v143 offset:49152
	ds_read_b128 v[180:183], v143 offset:50176
	ds_read_b128 v[184:187], v144 offset:49152
	ds_read_b128 v[188:191], v144 offset:50176
	ds_read_b128 v[192:195], v146 offset:49152
	ds_read_b128 v[210:213], v146 offset:50176
	global_load_lds_dwordx4 v[162:163], off
	v_lshl_add_u64 v[162:163], v[162:163], 0, s[86:87]
	s_mov_b32 m0, s26
	s_nop 0
	global_load_lds_dwordx4 v[162:163], off
	s_barrier
	s_waitcnt lgkmcnt(0)
	s_waitcnt lgkmcnt(0)
	v_mfma_f32_16x16x32_bf16 v[60:63], v[168:171], v[136:139], v[60:63]
	v_mfma_f32_16x16x32_bf16 v[56:59], v[168:171], v[154:157], v[56:59]
	v_mfma_f32_16x16x32_bf16 v[52:55], v[176:179], v[136:139], v[52:55]
	v_mfma_f32_16x16x32_bf16 v[48:51], v[176:179], v[154:157], v[48:51]
	v_mfma_f32_16x16x32_bf16 v[44:47], v[184:187], v[136:139], v[44:47]
	v_mfma_f32_16x16x32_bf16 v[40:43], v[184:187], v[154:157], v[40:43]
	v_mfma_f32_16x16x32_bf16 v[36:39], v[192:195], v[136:139], v[36:39]
	v_mfma_f32_16x16x32_bf16 v[32:35], v[192:195], v[154:157], v[32:35]
	v_mfma_f32_16x16x32_bf16 v[60:63], v[172:175], v[150:153], v[60:63]
	v_mfma_f32_16x16x32_bf16 v[56:59], v[172:175], v[158:161], v[56:59]
	v_mfma_f32_16x16x32_bf16 v[52:55], v[180:183], v[150:153], v[52:55]
	v_mfma_f32_16x16x32_bf16 v[48:51], v[180:183], v[158:161], v[48:51]
	v_mfma_f32_16x16x32_bf16 v[44:47], v[188:191], v[150:153], v[44:47]
	v_mfma_f32_16x16x32_bf16 v[40:43], v[188:191], v[158:161], v[40:43]
	v_mfma_f32_16x16x32_bf16 v[36:39], v[210:213], v[150:153], v[36:39]
	v_mfma_f32_16x16x32_bf16 v[32:35], v[210:213], v[158:161], v[32:35]
	s_barrier
	s_ashr_i32 s41, s40, 31
	s_lshl_b64 s[6:7], s[40:41], 12
	s_add_u32 s6, s52, s6
	s_addc_u32 s7, s53, s7
	s_add_u32 s2, s6, s2
	s_addc_u32 s3, s7, s3
	s_mov_b32 m0, s27
	v_lshl_add_u64 v[136:137], s[2:3], 0, v[130:131]
	global_load_lds_dwordx4 v[136:137], off
	v_lshl_add_u64 v[136:137], v[136:137], 0, s[86:87]
	s_mov_b32 m0, s28
	s_nop 0
	global_load_lds_dwordx4 v[136:137], off
	s_waitcnt vmcnt(6)
	s_barrier
	v_mfma_f32_16x16x32_bf16 v[28:31], v[168:171], v[214:217], v[28:31]
	v_mfma_f32_16x16x32_bf16 v[24:27], v[168:171], v[222:225], v[24:27]
	v_mfma_f32_16x16x32_bf16 v[20:23], v[176:179], v[214:217], v[20:23]
	v_mfma_f32_16x16x32_bf16 v[16:19], v[176:179], v[222:225], v[16:19]
	v_mfma_f32_16x16x32_bf16 v[12:15], v[184:187], v[214:217], v[12:15]
	v_mfma_f32_16x16x32_bf16 v[8:11], v[184:187], v[222:225], v[8:11]
	v_mfma_f32_16x16x32_bf16 v[4:7], v[192:195], v[214:217], v[4:7]
	v_mfma_f32_16x16x32_bf16 v[0:3], v[192:195], v[222:225], v[0:3]
	v_mfma_f32_16x16x32_bf16 v[28:31], v[172:175], v[218:221], v[28:31]
	v_mfma_f32_16x16x32_bf16 v[24:27], v[172:175], v[226:229], v[24:27]
	v_mfma_f32_16x16x32_bf16 v[20:23], v[180:183], v[218:221], v[20:23]
	v_mfma_f32_16x16x32_bf16 v[16:19], v[180:183], v[226:229], v[16:19]
	v_mfma_f32_16x16x32_bf16 v[12:15], v[188:191], v[218:221], v[12:15]
	v_mfma_f32_16x16x32_bf16 v[8:11], v[188:191], v[226:229], v[8:11]
	v_mfma_f32_16x16x32_bf16 v[4:7], v[210:213], v[218:221], v[4:7]
	v_mfma_f32_16x16x32_bf16 v[0:3], v[210:213], v[226:229], v[0:3]
	v_lshl_add_u64 v[134:135], v[134:135], 0, s[46:47]
	s_mov_b32 s38, s1
	s_barrier
	s_cbranch_vccnz .LBB0_181
	s_andn2_b64 vcc, exec, s[58:59]
	s_cbranch_vccnz .LBB0_184
	s_barrier

; __device__ __forceinline__ void ssd_item(const Params& P, const int pass, const int item, const int wvi) {
;     ...
;   {
;     const int chp = dir ? 0 : (nch - 1);
;     const size_t tbp = (size_t)b * S + (size_t)chp * 128;
; #pragma unroll
;     for (int pt = 0; pt < 4; pt += 2) {
;       const uint2 ya = make_uint2(yp[pt][0], yp[pt][1]), yb2 = make_uint2(yp[pt + 1][0], yp[pt + 1][1]);
;       *(uint4*)(yout + (tbp + it * 16 + fr) * DI + h * 64 + (pt + (fq & 1)) * 16 + (fq & ~1) * 4) = swap_pair(ya, yb2);
;     }
;   }
;   __builtin_amdgcn_s_setprio(0);
;   __syncthreads();
.LBB0_438:
	s_and_b64 s[0:1], s[8:9], exec
	v_readlane_b32 s0, v243, 41
	s_cselect_b32 s18, s0, 0
	s_lshl_b64 s[0:1], s[18:19], 7
	s_add_u32 s0, s29, s0
	v_readlane_b32 s2, v242, 12
	s_addc_u32 s1, s2, s1
	s_waitcnt vmcnt(0)
	v_mov_b32_e32 v1, s1
	v_or_b32_e32 v0, s0, v210
	v_readlane_b32 s0, v242, 8
	v_lshlrev_b64 v[0:1], 13, v[0:1]
	v_readlane_b32 s1, v242, 9
	v_lshlrev_b32_e32 v144, 1, v164
	v_permlane16_swap_b32_e32 v96, v92
	v_lshl_add_u64 v[0:1], s[0:1], 0, v[0:1]
	v_readlane_b32 s0, v242, 10
	v_readlane_b32 s1, v242, 11
	s_mov_b32 s1, s19
	v_permlane16_swap_b32_e32 v97, v93
	v_lshl_add_u64 v[0:1], v[0:1], 0, s[0:1]
	v_lshl_add_u64 v[0:1], v[0:1], 0, v[144:145]
	v_lshlrev_b32_e32 v144, 1, v166
	v_lshl_add_u64 v[0:1], v[0:1], 0, v[144:145]
	v_mov_b32_e32 v98, v92
	v_mov_b32_e32 v99, v93
	v_permlane16_swap_b32_e32 v88, v90
	v_permlane16_swap_b32_e32 v89, v91
	global_store_dwordx4 v[0:1], v[96:99], off
	global_store_dwordx4 v[0:1], v[88:91], off offset:64
	v_readlane_b32 s50, v244, 57
	v_readlane_b32 s52, v244, 59
	v_readlane_b32 s56, v243, 0
	v_readlane_b32 s58, v243, 5
	v_readlane_b32 s62, v243, 7
	v_readlane_b32 s64, v243, 30
	v_readlane_b32 s66, v243, 9
	v_readlane_b32 s72, v243, 15
	v_readlane_b32 s76, v243, 19
	v_readlane_b32 s26, v243, 62
	v_readlane_b32 s48, v244, 56
	v_readlane_b32 s51, v244, 58
	v_readlane_b32 s53, v244, 60
	v_readlane_b32 s49, v244, 62
	v_readlane_b32 s54, v244, 63
	v_readlane_b32 s57, v243, 1
	v_readlane_b32 s59, v243, 6
	v_readlane_b32 s55, v243, 28
	v_readlane_b32 s60, v243, 29
	v_readlane_b32 s63, v243, 8
	v_readlane_b32 s65, v243, 31
	v_readlane_b32 s67, v243, 10
	v_readlane_b32 s61, v243, 11
	v_readlane_b32 s68, v243, 12
	v_readlane_b32 s69, v243, 13
	v_readlane_b32 s70, v243, 14
	v_readlane_b32 s73, v243, 16
	v_readlane_b32 s71, v243, 17
	v_readlane_b32 s74, v243, 18
	v_readlane_b32 s77, v243, 20
	v_readlane_b32 s75, v243, 21
	v_readlane_b32 s78, v243, 22
	v_readlane_b32 s79, v243, 23
	v_readlane_b32 s80, v243, 24
	v_readlane_b32 s81, v243, 25
	v_readlane_b32 s82, v243, 26
	v_readlane_b32 s83, v243, 27
	v_readlane_b32 s84, v243, 32
	s_movk_i32 s85, 0x3000
	s_mov_b32 s88, 0x800000
	s_movk_i32 s89, 0x2000
	s_movk_i32 s90, 0xd000
	s_movk_i32 s91, 0x1800
	s_mov_b32 s93, 0x32700000
	s_mov_b32 s96, 0x26700000
	s_movk_i32 s97, 0x101
	s_mov_b64 s[46:47], 0x100
	v_readlane_b32 s24, v243, 60
	v_readlane_b32 s25, v243, 61
	v_readlane_b32 s27, v243, 63
	s_barrier

; #define STAGE(P_, BASE, br, kt) do { const u16* _gb = (BASE) + (long)(br) * K + (long)(kt) * BK; \
;     _Pragma("unroll") for (int _i = 0; _i < 2; ++_i) { \
;       __builtin_amdgcn_global_load_lds((const unsigned*)(_gb + (long)_i * 64 * K + lane_off), \
;         (unsigned*)((char*)(P_) + lds_wbase + _i * 8192), 16, 0, 0); } } while (0)
; #define LDA(dst, b, h) _Pragma("unroll") for (int m = 0; m < 4; ++m) _Pragma("unroll") for (int k = 0; k < 2; ++k) \
;     dst[m][k] = *reinterpret_cast<const bf16x8*>((char*)SA(b, h) + lds_byte(wr * 64 + m * 16 + fr, k * 32 + fq * 8))
; #define LDB(dst, b, h) _Pragma("unroll") for (int n = 0; n < 2; ++n) _Pragma("unroll") for (int k = 0; k < 2; ++k) \
;     dst[n][k] = *reinterpret_cast<const bf16x8*>((char*)SB(b, h) + lds_byte(wc * 32 + n * 16 + fr, k * 32 + fq * 8))
; #define MMA(ai, bj, At_, Bt_) do { __builtin_amdgcn_s_setprio(1); \
;     _Pragma("unroll") for (int m = 0; m < 4; ++m) _Pragma("unroll") for (int n = 0; n < 2; ++n) _Pragma("unroll") for (int k = 0; k < 2; ++k) \
;       acc[ai][bj][m][n] = __builtin_amdgcn_mfma_f32_16x16x32_bf16(At_[m][k], Bt_[n][k], acc[ai][bj][m][n], 0, 0, 0); \
;     __builtin_amdgcn_s_setprio(0); } while (0)
; #define WAIT_V(n) asm volatile("s_waitcnt vmcnt(" #n ")" ::: "memory")
; #define BAR __builtin_amdgcn_s_barrier()
; template <int PRE> ...
;     ...
;   for (int t = 0; t < nt; t += 2) {
;     LDB(B0, 0, 0); SCHED; LDA(At, 0, 0); STAGE(SA(1, 1), A, brow + HALF, t + 1);
;     WAIT_L(8); BAR; WAIT_L(0); MMA(0, 0, At, B0); BAR; SCHED;
;     LDB(B1, 0, 1); STAGEW(SB(0, 0), Bt, bcol, bcol_n, t + 2);
;     BAR; WAIT_L(0); MMA(0, 1, At, B1); BAR;
;     LDA(At, 0, 1); STAGEW(SA(0, 0), A, brow, brow_n, t + 2);
;     BAR; WAIT_L(0); MMA(1, 0, At, B0); BAR; SCHED;
;     STAGEW(SB(0, 1), Bt, bcol + HALF, bcol_n + HALF, t + 2);
;     WAIT_V(6); BAR; MMA(1, 1, At, B1); BAR;
;     LDB(B0, 1, 0); SCHED; LDA(At, 1, 0); STAGEW(SA(0, 1), A, brow + HALF, brow_n + HALF, t + 2);
;     WAIT_L(8); BAR; WAIT_L(0); MMA(0, 0, At, B0); BAR; SCHED;
;     LDB(B1, 1, 1); STAGEW(SB(1, 0), Bt, bcol, bcol_n, t + 3);
;     BAR; WAIT_L(0); MMA(0, 1, At, B1); BAR;
;     LDA(At, 1, 1); STAGEW(SA(1, 0), A, brow, brow_n, t + 3);
;     BAR; WAIT_L(0); MMA(1, 0, At, B0); BAR; SCHED;
;     STAGEW(SB(1, 1), Bt, bcol + HALF, bcol_n + HALF, t + 3);
;     WAIT_V(6); BAR; MMA(1, 1, At, B1); BAR;
;   }
.LBB0_456:
	v_add_u32_e32 v136, s81, v139
	ds_read_b128 v[148:151], v136
	ds_read_b128 v[152:155], v136 offset:1024
	ds_read_b128 v[156:159], v136 offset:2048
	ds_read_b128 v[160:163], v136 offset:3072
	s_add_i32 m0, s14, 0xc000
	ds_read_b128 v[168:171], v140
	ds_read_b128 v[172:175], v140 offset:1024
	ds_read_b128 v[176:179], v141
	ds_read_b128 v[180:183], v141 offset:1024
	ds_read_b128 v[184:187], v142
	ds_read_b128 v[188:191], v142 offset:1024
	ds_read_b128 v[192:195], v143
	ds_read_b128 v[210:213], v143 offset:1024
	global_load_lds_dwordx4 v[134:135], off
	v_lshl_add_u64 v[136:137], v[134:135], 0, s[86:87]
	s_add_i32 m0, s14, 0xe000
	s_nop 0
	global_load_lds_dwordx4 v[136:137], off
	s_waitcnt lgkmcnt(8)
	s_barrier
	s_waitcnt lgkmcnt(0)
	s_waitcnt lgkmcnt(0)
	v_mfma_f32_16x16x32_bf16 v[126:129], v[168:171], v[148:151], v[126:129]
	v_mfma_f32_16x16x32_bf16 v[122:125], v[168:171], v[156:159], v[122:125]
	v_mfma_f32_16x16x32_bf16 v[118:121], v[176:179], v[148:151], v[118:121]
	v_mfma_f32_16x16x32_bf16 v[114:117], v[176:179], v[156:159], v[114:117]
	v_mfma_f32_16x16x32_bf16 v[110:113], v[184:187], v[148:151], v[110:113]
	v_mfma_f32_16x16x32_bf16 v[106:109], v[184:187], v[156:159], v[106:109]
	v_mfma_f32_16x16x32_bf16 v[102:105], v[192:195], v[148:151], v[102:105]
	v_mfma_f32_16x16x32_bf16 v[98:101], v[192:195], v[156:159], v[98:101]
	v_mfma_f32_16x16x32_bf16 v[126:129], v[172:175], v[152:155], v[126:129]
	v_mfma_f32_16x16x32_bf16 v[122:125], v[172:175], v[160:163], v[122:125]
	v_mfma_f32_16x16x32_bf16 v[118:121], v[180:183], v[152:155], v[118:121]
	v_mfma_f32_16x16x32_bf16 v[114:117], v[180:183], v[160:163], v[114:117]
	v_mfma_f32_16x16x32_bf16 v[110:113], v[188:191], v[152:155], v[110:113]
	v_mfma_f32_16x16x32_bf16 v[106:109], v[188:191], v[160:163], v[106:109]
	v_mfma_f32_16x16x32_bf16 v[102:105], v[210:213], v[152:155], v[102:105]
	v_mfma_f32_16x16x32_bf16 v[98:101], v[210:213], v[160:163], v[98:101]
	s_barrier
	s_add_i32 s41, s1, 2
	s_cmp_lt_u32 s1, 30
	s_cselect_b64 s[2:3], -1, 0
	s_and_b64 vcc, s[2:3], exec
	s_cselect_b32 s6, s8, s9
	s_cselect_b32 s3, 0, 0xffffffe0
	s_cselect_b32 s42, s0, s36
	s_cselect_b32 s44, s39, s38
	s_cselect_b32 s2, s37, s40
	s_ashr_i32 s7, s6, 31
	s_lshl_b64 s[6:7], s[6:7], 12
	s_add_u32 s43, s33, s6
	s_addc_u32 s45, s92, s7
	s_add_i32 s18, s41, s3
	s_lshl_b64 s[6:7], s[18:19], 7
	s_add_u32 s46, s43, s6
	v_add_u32_e32 v136, s82, v139
	s_addc_u32 s47, s45, s7
	s_mov_b32 m0, s15
	ds_read_b128 v[214:217], v136
	ds_read_b128 v[218:221], v136 offset:1024
	ds_read_b128 v[222:225], v136 offset:2048
	ds_read_b128 v[226:229], v136 offset:3072
	v_lshl_add_u64 v[136:137], s[46:47], 0, v[130:131]
	global_load_lds_dwordx4 v[136:137], off
	v_lshl_add_u64 v[136:137], v[136:137], 0, s[86:87]
	s_mov_b32 m0, s16
	s_mov_b64 s[46:47], 0x100
	global_load_lds_dwordx4 v[136:137], off
	s_barrier
	s_waitcnt lgkmcnt(0)
	s_waitcnt lgkmcnt(0)
	v_mfma_f32_16x16x32_bf16 v[94:97], v[168:171], v[214:217], v[94:97]
	v_mfma_f32_16x16x32_bf16 v[90:93], v[168:171], v[222:225], v[90:93]
	v_mfma_f32_16x16x32_bf16 v[86:89], v[176:179], v[214:217], v[86:89]
	v_mfma_f32_16x16x32_bf16 v[82:85], v[176:179], v[222:225], v[82:85]
	v_mfma_f32_16x16x32_bf16 v[78:81], v[184:187], v[214:217], v[78:81]
	v_mfma_f32_16x16x32_bf16 v[74:77], v[184:187], v[222:225], v[74:77]
	v_mfma_f32_16x16x32_bf16 v[70:73], v[192:195], v[214:217], v[70:73]
	v_mfma_f32_16x16x32_bf16 v[64:67], v[192:195], v[222:225], v[64:67]
	v_mfma_f32_16x16x32_bf16 v[94:97], v[172:175], v[218:221], v[94:97]
	v_mfma_f32_16x16x32_bf16 v[90:93], v[172:175], v[226:229], v[90:93]
	v_mfma_f32_16x16x32_bf16 v[86:89], v[180:183], v[218:221], v[86:89]
	v_mfma_f32_16x16x32_bf16 v[82:85], v[180:183], v[226:229], v[82:85]
	v_mfma_f32_16x16x32_bf16 v[78:81], v[188:191], v[218:221], v[78:81]
	v_mfma_f32_16x16x32_bf16 v[74:77], v[188:191], v[226:229], v[74:77]
	v_mfma_f32_16x16x32_bf16 v[70:73], v[210:213], v[218:221], v[70:73]
	v_mfma_f32_16x16x32_bf16 v[64:67], v[210:213], v[226:229], v[64:67]
	s_ashr_i32 s43, s42, 31
	s_lshl_b64 s[42:43], s[42:43], 12
	s_add_u32 s3, s94, s42
	s_addc_u32 s18, s95, s43
	s_add_u32 s42, s3, s6
	s_addc_u32 s43, s18, s7
	s_mov_b32 m0, s14
	v_lshl_add_u64 v[136:137], s[42:43], 0, v[130:131]
	s_barrier
	ds_read_b128 v[168:171], v140 offset:16384
	ds_read_b128 v[172:175], v140 offset:17408
	ds_read_b128 v[176:179], v141 offset:16384
	ds_read_b128 v[180:183], v141 offset:17408
	ds_read_b128 v[184:187], v142 offset:16384
	ds_read_b128 v[188:191], v142 offset:17408
	ds_read_b128 v[192:195], v143 offset:16384
	ds_read_b128 v[210:213], v143 offset:17408
	global_load_lds_dwordx4 v[136:137], off
	v_lshl_add_u64 v[136:137], v[136:137], 0, s[86:87]
	s_mov_b32 m0, s17
	s_nop 0
	global_load_lds_dwordx4 v[136:137], off
	s_barrier
	s_waitcnt lgkmcnt(0)
	s_waitcnt lgkmcnt(0)
	v_mfma_f32_16x16x32_bf16 v[60:63], v[168:171], v[148:151], v[60:63]
	v_mfma_f32_16x16x32_bf16 v[56:59], v[168:171], v[156:159], v[56:59]
	v_mfma_f32_16x16x32_bf16 v[52:55], v[176:179], v[148:151], v[52:55]
	v_mfma_f32_16x16x32_bf16 v[48:51], v[176:179], v[156:159], v[48:51]
	v_mfma_f32_16x16x32_bf16 v[44:47], v[184:187], v[148:151], v[44:47]
	v_mfma_f32_16x16x32_bf16 v[40:43], v[184:187], v[156:159], v[40:43]
	v_mfma_f32_16x16x32_bf16 v[36:39], v[192:195], v[148:151], v[36:39]
	v_mfma_f32_16x16x32_bf16 v[32:35], v[192:195], v[156:159], v[32:35]
	v_mfma_f32_16x16x32_bf16 v[60:63], v[172:175], v[152:155], v[60:63]
	v_mfma_f32_16x16x32_bf16 v[56:59], v[172:175], v[160:163], v[56:59]
	v_mfma_f32_16x16x32_bf16 v[52:55], v[180:183], v[152:155], v[52:55]
	v_mfma_f32_16x16x32_bf16 v[48:51], v[180:183], v[160:163], v[48:51]
	v_mfma_f32_16x16x32_bf16 v[44:47], v[188:191], v[152:155], v[44:47]
	v_mfma_f32_16x16x32_bf16 v[40:43], v[188:191], v[160:163], v[40:43]
	v_mfma_f32_16x16x32_bf16 v[36:39], v[210:213], v[152:155], v[36:39]
	v_mfma_f32_16x16x32_bf16 v[32:35], v[210:213], v[160:163], v[32:35]
	s_barrier
; #define STAGE(P_, BASE, br, kt) do { const u16* _gb = (BASE) + (long)(br) * K + (long)(kt) * BK; \
;     _Pragma("unroll") for (int _i = 0; _i < 2; ++_i) { \
;       __builtin_amdgcn_global_load_lds((const unsigned*)(_gb + (long)_i * 64 * K + lane_off), \
;         (unsigned*)((char*)(P_) + lds_wbase + _i * 8192), 16, 0, 0); } } while (0)
; #define LDA(dst, b, h) _Pragma("unroll") for (int m = 0; m < 4; ++m) _Pragma("unroll") for (int k = 0; k < 2; ++k) \
;     dst[m][k] = *reinterpret_cast<const bf16x8*>((char*)SA(b, h) + lds_byte(wr * 64 + m * 16 + fr, k * 32 + fq * 8))
; #define LDB(dst, b, h) _Pragma("unroll") for (int n = 0; n < 2; ++n) _Pragma("unroll") for (int k = 0; k < 2; ++k) \
;     dst[n][k] = *reinterpret_cast<const bf16x8*>((char*)SB(b, h) + lds_byte(wc * 32 + n * 16 + fr, k * 32 + fq * 8))
; #define MMA(ai, bj, At_, Bt_) do { __builtin_amdgcn_s_setprio(1); \
;     _Pragma("unroll") for (int m = 0; m < 4; ++m) _Pragma("unroll") for (int n = 0; n < 2; ++n) _Pragma("unroll") for (int k = 0; k < 2; ++k) \
;       acc[ai][bj][m][n] = __builtin_amdgcn_mfma_f32_16x16x32_bf16(At_[m][k], Bt_[n][k], acc[ai][bj][m][n], 0, 0, 0); \
;     __builtin_amdgcn_s_setprio(0); } while (0)
; #define WAIT_V(n) asm volatile("s_waitcnt vmcnt(" #n ")" ::: "memory")
; #define BAR __builtin_amdgcn_s_barrier()
; template <int PRE> ...
;     ...
;   for (int t = 0; t < nt; t += 2) {
;     LDB(B0, 0, 0); SCHED; LDA(At, 0, 0); STAGE(SA(1, 1), A, brow + HALF, t + 1);
;     WAIT_L(8); BAR; WAIT_L(0); MMA(0, 0, At, B0); BAR; SCHED;
;     LDB(B1, 0, 1); STAGEW(SB(0, 0), Bt, bcol, bcol_n, t + 2);
;     BAR; WAIT_L(0); MMA(0, 1, At, B1); BAR;
;     LDA(At, 0, 1); STAGEW(SA(0, 0), A, brow, brow_n, t + 2);
;     BAR; WAIT_L(0); MMA(1, 0, At, B0); BAR; SCHED;
;     STAGEW(SB(0, 1), Bt, bcol + HALF, bcol_n + HALF, t + 2);
;     WAIT_V(6); BAR; MMA(1, 1, At, B1); BAR;
;     LDB(B0, 1, 0); SCHED; LDA(At, 1, 0); STAGEW(SA(0, 1), A, brow + HALF, brow_n + HALF, t + 2);
;     WAIT_L(8); BAR; WAIT_L(0); MMA(0, 0, At, B0); BAR; SCHED;
;     LDB(B1, 1, 1); STAGEW(SB(1, 0), Bt, bcol, bcol_n, t + 3);
;     BAR; WAIT_L(0); MMA(0, 1, At, B1); BAR;
;     LDA(At, 1, 1); STAGEW(SA(1, 0), A, brow, brow_n, t + 3);
;     BAR; WAIT_L(0); MMA(1, 0, At, B0); BAR; SCHED;
;     STAGEW(SB(1, 1), Bt, bcol + HALF, bcol_n + HALF, t + 3);
;     WAIT_V(6); BAR; MMA(1, 1, At, B1); BAR;
;   }
	s_ashr_i32 s45, s44, 31
	s_lshl_b64 s[42:43], s[44:45], 12
	s_add_u32 s3, s33, s42
	s_addc_u32 s18, s92, s43
	s_add_u32 s42, s3, s6
	s_addc_u32 s43, s18, s7
	s_mov_b32 m0, s20
	v_lshl_add_u64 v[136:137], s[42:43], 0, v[130:131]
	global_load_lds_dwordx4 v[136:137], off
	v_lshl_add_u64 v[136:137], v[136:137], 0, s[86:87]
	s_mov_b32 m0, s21
	s_nop 0
	global_load_lds_dwordx4 v[136:137], off
	s_waitcnt vmcnt(6)
	s_barrier
	v_mfma_f32_16x16x32_bf16 v[28:31], v[168:171], v[214:217], v[28:31]
	v_mfma_f32_16x16x32_bf16 v[24:27], v[168:171], v[222:225], v[24:27]
	v_mfma_f32_16x16x32_bf16 v[20:23], v[176:179], v[214:217], v[20:23]
	v_mfma_f32_16x16x32_bf16 v[16:19], v[176:179], v[222:225], v[16:19]
	v_mfma_f32_16x16x32_bf16 v[12:15], v[184:187], v[214:217], v[12:15]
	v_mfma_f32_16x16x32_bf16 v[8:11], v[184:187], v[222:225], v[8:11]
	v_mfma_f32_16x16x32_bf16 v[4:7], v[192:195], v[214:217], v[4:7]
	v_mfma_f32_16x16x32_bf16 v[0:3], v[192:195], v[222:225], v[0:3]
	v_mfma_f32_16x16x32_bf16 v[28:31], v[172:175], v[218:221], v[28:31]
	v_mfma_f32_16x16x32_bf16 v[24:27], v[172:175], v[226:229], v[24:27]
	v_mfma_f32_16x16x32_bf16 v[20:23], v[180:183], v[218:221], v[20:23]
	v_mfma_f32_16x16x32_bf16 v[16:19], v[180:183], v[226:229], v[16:19]
	v_mfma_f32_16x16x32_bf16 v[12:15], v[188:191], v[218:221], v[12:15]
	v_mfma_f32_16x16x32_bf16 v[8:11], v[188:191], v[226:229], v[8:11]
	v_mfma_f32_16x16x32_bf16 v[4:7], v[210:213], v[218:221], v[4:7]
	v_mfma_f32_16x16x32_bf16 v[0:3], v[210:213], v[226:229], v[0:3]
	v_add_u32_e32 v136, s83, v139
	s_barrier
	ds_read_b128 v[148:151], v136
	ds_read_b128 v[152:155], v136 offset:1024
	ds_read_b128 v[156:159], v136 offset:2048
	ds_read_b128 v[160:163], v136 offset:3072
	s_ashr_i32 s3, s2, 31
	s_lshl_b64 s[2:3], s[2:3], 12
	s_add_u32 s2, s94, s2
	s_addc_u32 s3, s95, s3
	s_add_u32 s2, s2, s6
	s_addc_u32 s3, s3, s7
	s_mov_b32 m0, s22
	v_lshl_add_u64 v[136:137], s[2:3], 0, v[130:131]
	ds_read_b128 v[168:171], v140 offset:32768
	ds_read_b128 v[172:175], v140 offset:33792
	ds_read_b128 v[176:179], v141 offset:32768
	ds_read_b128 v[180:183], v141 offset:33792
	ds_read_b128 v[184:187], v142 offset:32768
	ds_read_b128 v[188:191], v142 offset:33792
	ds_read_b128 v[192:195], v143 offset:32768
	ds_read_b128 v[210:213], v143 offset:33792
	global_load_lds_dwordx4 v[136:137], off
	v_lshl_add_u64 v[136:137], v[136:137], 0, s[86:87]
	s_mov_b32 m0, s23
	s_nop 0
	global_load_lds_dwordx4 v[136:137], off
	s_waitcnt lgkmcnt(8)
	s_barrier
	s_waitcnt lgkmcnt(0)
	s_waitcnt lgkmcnt(0)
	v_mfma_f32_16x16x32_bf16 v[126:129], v[168:171], v[148:151], v[126:129]
	v_mfma_f32_16x16x32_bf16 v[122:125], v[168:171], v[156:159], v[122:125]
	v_mfma_f32_16x16x32_bf16 v[118:121], v[176:179], v[148:151], v[118:121]
	v_mfma_f32_16x16x32_bf16 v[114:117], v[176:179], v[156:159], v[114:117]
	v_mfma_f32_16x16x32_bf16 v[110:113], v[184:187], v[148:151], v[110:113]
	v_mfma_f32_16x16x32_bf16 v[106:109], v[184:187], v[156:159], v[106:109]
	v_mfma_f32_16x16x32_bf16 v[102:105], v[192:195], v[148:151], v[102:105]
	v_mfma_f32_16x16x32_bf16 v[98:101], v[192:195], v[156:159], v[98:101]
	v_mfma_f32_16x16x32_bf16 v[126:129], v[172:175], v[152:155], v[126:129]
	v_mfma_f32_16x16x32_bf16 v[122:125], v[172:175], v[160:163], v[122:125]
	v_mfma_f32_16x16x32_bf16 v[118:121], v[180:183], v[152:155], v[118:121]
	v_mfma_f32_16x16x32_bf16 v[114:117], v[180:183], v[160:163], v[114:117]
	v_mfma_f32_16x16x32_bf16 v[110:113], v[188:191], v[152:155], v[110:113]
	v_mfma_f32_16x16x32_bf16 v[106:109], v[188:191], v[160:163], v[106:109]
	v_mfma_f32_16x16x32_bf16 v[102:105], v[210:213], v[152:155], v[102:105]
	v_mfma_f32_16x16x32_bf16 v[98:101], v[210:213], v[160:163], v[98:101]
	s_barrier
	s_cmp_lt_u32 s1, 29
	s_cselect_b32 s2, s8, s9
	s_cselect_b32 s7, 0, 0xffffffe0
	s_cselect_b32 s6, s0, s36
	s_cselect_b32 s42, s39, s38
	s_ashr_i32 s3, s2, 31
	s_lshl_b64 s[2:3], s[2:3], 12
	s_add_u32 s43, s33, s2
	s_addc_u32 s45, s92, s3
	s_add_i32 s1, s7, s1
	s_add_i32 s18, s1, 3
	s_lshl_b64 s[2:3], s[18:19], 7
	s_add_u32 s44, s43, s2
	v_add_u32_e32 v136, s84, v139
	s_addc_u32 s45, s45, s3
	s_mov_b32 m0, s24
	ds_read_b128 v[214:217], v136
	ds_read_b128 v[218:221], v136 offset:1024
	ds_read_b128 v[222:225], v136 offset:2048
	ds_read_b128 v[226:229], v136 offset:3072
	v_lshl_add_u64 v[136:137], s[44:45], 0, v[130:131]
	global_load_lds_dwordx4 v[136:137], off
	v_lshl_add_u64 v[136:137], v[136:137], 0, s[86:87]
	s_mov_b32 m0, s25
	s_nop 0
	global_load_lds_dwordx4 v[136:137], off
	s_barrier
; #define STAGE(P_, BASE, br, kt) do { const u16* _gb = (BASE) + (long)(br) * K + (long)(kt) * BK; \
;     _Pragma("unroll") for (int _i = 0; _i < 2; ++_i) { \
;       __builtin_amdgcn_global_load_lds((const unsigned*)(_gb + (long)_i * 64 * K + lane_off), \
;         (unsigned*)((char*)(P_) + lds_wbase + _i * 8192), 16, 0, 0); } } while (0)
; #define LDA(dst, b, h) _Pragma("unroll") for (int m = 0; m < 4; ++m) _Pragma("unroll") for (int k = 0; k < 2; ++k) \
;     dst[m][k] = *reinterpret_cast<const bf16x8*>((char*)SA(b, h) + lds_byte(wr * 64 + m * 16 + fr, k * 32 + fq * 8))
; #define LDB(dst, b, h) _Pragma("unroll") for (int n = 0; n < 2; ++n) _Pragma("unroll") for (int k = 0; k < 2; ++k) \
;     dst[n][k] = *reinterpret_cast<const bf16x8*>((char*)SB(b, h) + lds_byte(wc * 32 + n * 16 + fr, k * 32 + fq * 8))
; #define MMA(ai, bj, At_, Bt_) do { __builtin_amdgcn_s_setprio(1); \
;     _Pragma("unroll") for (int m = 0; m < 4; ++m) _Pragma("unroll") for (int n = 0; n < 2; ++n) _Pragma("unroll") for (int k = 0; k < 2; ++k) \
;       acc[ai][bj][m][n] = __builtin_amdgcn_mfma_f32_16x16x32_bf16(At_[m][k], Bt_[n][k], acc[ai][bj][m][n], 0, 0, 0); \
;     __builtin_amdgcn_s_setprio(0); } while (0)
; #define WAIT_V(n) asm volatile("s_waitcnt vmcnt(" #n ")" ::: "memory")
; #define BAR __builtin_amdgcn_s_barrier()
; template <int PRE> ...
;     ...
;   for (int t = 0; t < nt; t += 2) {
;     LDB(B0, 0, 0); SCHED; LDA(At, 0, 0); STAGE(SA(1, 1), A, brow + HALF, t + 1);
;     WAIT_L(8); BAR; WAIT_L(0); MMA(0, 0, At, B0); BAR; SCHED;
;     LDB(B1, 0, 1); STAGEW(SB(0, 0), Bt, bcol, bcol_n, t + 2);
;     BAR; WAIT_L(0); MMA(0, 1, At, B1); BAR;
;     LDA(At, 0, 1); STAGEW(SA(0, 0), A, brow, brow_n, t + 2);
;     BAR; WAIT_L(0); MMA(1, 0, At, B0); BAR; SCHED;
;     STAGEW(SB(0, 1), Bt, bcol + HALF, bcol_n + HALF, t + 2);
;     WAIT_V(6); BAR; MMA(1, 1, At, B1); BAR;
;     LDB(B0, 1, 0); SCHED; LDA(At, 1, 0); STAGEW(SA(0, 1), A, brow + HALF, brow_n + HALF, t + 2);
;     WAIT_L(8); BAR; WAIT_L(0); MMA(0, 0, At, B0); BAR; SCHED;
;     LDB(B1, 1, 1); STAGEW(SB(1, 0), Bt, bcol, bcol_n, t + 3);
;     BAR; WAIT_L(0); MMA(0, 1, At, B1); BAR;
;     LDA(At, 1, 1); STAGEW(SA(1, 0), A, brow, brow_n, t + 3);
;     BAR; WAIT_L(0); MMA(1, 0, At, B0); BAR; SCHED;
;     STAGEW(SB(1, 1), Bt, bcol + HALF, bcol_n + HALF, t + 3);
;     WAIT_V(6); BAR; MMA(1, 1, At, B1); BAR;
;   }
;   if (wr == 0) BAR;
	s_waitcnt lgkmcnt(0)
	s_waitcnt lgkmcnt(0)
	v_mfma_f32_16x16x32_bf16 v[94:97], v[168:171], v[214:217], v[94:97]
	v_mfma_f32_16x16x32_bf16 v[90:93], v[168:171], v[222:225], v[90:93]
	v_mfma_f32_16x16x32_bf16 v[86:89], v[176:179], v[214:217], v[86:89]
	v_mfma_f32_16x16x32_bf16 v[82:85], v[176:179], v[222:225], v[82:85]
	v_mfma_f32_16x16x32_bf16 v[78:81], v[184:187], v[214:217], v[78:81]
	v_mfma_f32_16x16x32_bf16 v[74:77], v[184:187], v[222:225], v[74:77]
	v_mfma_f32_16x16x32_bf16 v[70:73], v[192:195], v[214:217], v[70:73]
	v_mfma_f32_16x16x32_bf16 v[64:67], v[192:195], v[222:225], v[64:67]
	v_mfma_f32_16x16x32_bf16 v[94:97], v[172:175], v[218:221], v[94:97]
	v_mfma_f32_16x16x32_bf16 v[90:93], v[172:175], v[226:229], v[90:93]
	v_mfma_f32_16x16x32_bf16 v[86:89], v[180:183], v[218:221], v[86:89]
	v_mfma_f32_16x16x32_bf16 v[82:85], v[180:183], v[226:229], v[82:85]
	v_mfma_f32_16x16x32_bf16 v[78:81], v[188:191], v[218:221], v[78:81]
	v_mfma_f32_16x16x32_bf16 v[74:77], v[188:191], v[226:229], v[74:77]
	v_mfma_f32_16x16x32_bf16 v[70:73], v[210:213], v[218:221], v[70:73]
	v_mfma_f32_16x16x32_bf16 v[64:67], v[210:213], v[226:229], v[64:67]
	s_ashr_i32 s7, s6, 31
	s_lshl_b64 s[6:7], s[6:7], 12
	s_add_u32 s1, s94, s6
	s_addc_u32 s7, s95, s7
	s_add_u32 s6, s1, s2
	s_addc_u32 s7, s7, s3
	s_mov_b32 m0, s26
	v_lshl_add_u64 v[136:137], s[6:7], 0, v[130:131]
	s_barrier
	ds_read_b128 v[168:171], v140 offset:49152
	ds_read_b128 v[172:175], v140 offset:50176
	ds_read_b128 v[176:179], v141 offset:49152
	ds_read_b128 v[180:183], v141 offset:50176
	ds_read_b128 v[184:187], v142 offset:49152
	ds_read_b128 v[188:191], v142 offset:50176
	ds_read_b128 v[192:195], v143 offset:49152
	ds_read_b128 v[210:213], v143 offset:50176
	global_load_lds_dwordx4 v[136:137], off
	v_lshl_add_u64 v[136:137], v[136:137], 0, s[86:87]
	s_mov_b32 m0, s27
	s_nop 0
	global_load_lds_dwordx4 v[136:137], off
	s_barrier
	s_waitcnt lgkmcnt(0)
	s_waitcnt lgkmcnt(0)
	v_mfma_f32_16x16x32_bf16 v[60:63], v[168:171], v[148:151], v[60:63]
	v_mfma_f32_16x16x32_bf16 v[56:59], v[168:171], v[156:159], v[56:59]
	v_mfma_f32_16x16x32_bf16 v[52:55], v[176:179], v[148:151], v[52:55]
	v_mfma_f32_16x16x32_bf16 v[48:51], v[176:179], v[156:159], v[48:51]
	v_mfma_f32_16x16x32_bf16 v[44:47], v[184:187], v[148:151], v[44:47]
	v_mfma_f32_16x16x32_bf16 v[40:43], v[184:187], v[156:159], v[40:43]
	v_mfma_f32_16x16x32_bf16 v[36:39], v[192:195], v[148:151], v[36:39]
	v_mfma_f32_16x16x32_bf16 v[32:35], v[192:195], v[156:159], v[32:35]
	v_mfma_f32_16x16x32_bf16 v[60:63], v[172:175], v[152:155], v[60:63]
	v_mfma_f32_16x16x32_bf16 v[56:59], v[172:175], v[160:163], v[56:59]
	v_mfma_f32_16x16x32_bf16 v[52:55], v[180:183], v[152:155], v[52:55]
	v_mfma_f32_16x16x32_bf16 v[48:51], v[180:183], v[160:163], v[48:51]
	v_mfma_f32_16x16x32_bf16 v[44:47], v[188:191], v[152:155], v[44:47]
	v_mfma_f32_16x16x32_bf16 v[40:43], v[188:191], v[160:163], v[40:43]
	v_mfma_f32_16x16x32_bf16 v[36:39], v[210:213], v[152:155], v[36:39]
	v_mfma_f32_16x16x32_bf16 v[32:35], v[210:213], v[160:163], v[32:35]
	s_barrier
	s_ashr_i32 s43, s42, 31
	s_lshl_b64 s[6:7], s[42:43], 12
	s_add_u32 s1, s33, s6
	s_addc_u32 s6, s92, s7
	s_add_u32 s2, s1, s2
	s_addc_u32 s3, s6, s3
	s_mov_b32 m0, s28
	v_lshl_add_u64 v[136:137], s[2:3], 0, v[130:131]
	global_load_lds_dwordx4 v[136:137], off
	v_lshl_add_u64 v[136:137], v[136:137], 0, s[86:87]
	s_mov_b32 m0, s29
	s_nop 0
	global_load_lds_dwordx4 v[136:137], off
	s_waitcnt vmcnt(6)
	s_barrier
	v_mfma_f32_16x16x32_bf16 v[28:31], v[168:171], v[214:217], v[28:31]
	v_mfma_f32_16x16x32_bf16 v[24:27], v[168:171], v[222:225], v[24:27]
	v_mfma_f32_16x16x32_bf16 v[20:23], v[176:179], v[214:217], v[20:23]
	v_mfma_f32_16x16x32_bf16 v[16:19], v[176:179], v[222:225], v[16:19]
	v_mfma_f32_16x16x32_bf16 v[12:15], v[184:187], v[214:217], v[12:15]
	v_mfma_f32_16x16x32_bf16 v[8:11], v[184:187], v[222:225], v[8:11]
	v_mfma_f32_16x16x32_bf16 v[4:7], v[192:195], v[214:217], v[4:7]
	v_mfma_f32_16x16x32_bf16 v[0:3], v[192:195], v[222:225], v[0:3]
	v_mfma_f32_16x16x32_bf16 v[28:31], v[172:175], v[218:221], v[28:31]
	v_mfma_f32_16x16x32_bf16 v[24:27], v[172:175], v[226:229], v[24:27]
	v_mfma_f32_16x16x32_bf16 v[20:23], v[180:183], v[218:221], v[20:23]
	v_mfma_f32_16x16x32_bf16 v[16:19], v[180:183], v[226:229], v[16:19]
	v_mfma_f32_16x16x32_bf16 v[12:15], v[188:191], v[218:221], v[12:15]
	v_mfma_f32_16x16x32_bf16 v[8:11], v[188:191], v[226:229], v[8:11]
	v_mfma_f32_16x16x32_bf16 v[4:7], v[210:213], v[218:221], v[4:7]
	v_mfma_f32_16x16x32_bf16 v[0:3], v[210:213], v[226:229], v[0:3]
	v_lshl_add_u64 v[134:135], v[134:135], 0, s[46:47]
	s_mov_b32 s1, s41
	s_barrier
	s_cbranch_vccnz .LBB0_456
	s_andn2_b64 vcc, exec, s[58:59]
	s_cbranch_vccnz .LBB0_459
	s_barrier

; #define STAGE(P_, BASE, br, kt) do { const u16* _gb = (BASE) + (long)(br) * K + (long)(kt) * BK; \
;     _Pragma("unroll") for (int _i = 0; _i < 2; ++_i) { \
;       __builtin_amdgcn_global_load_lds((const unsigned*)(_gb + (long)_i * 64 * K + lane_off), \
;         (unsigned*)((char*)(P_) + lds_wbase + _i * 8192), 16, 0, 0); } } while (0)
; #define LDA(dst, b, h) _Pragma("unroll") for (int m = 0; m < 4; ++m) _Pragma("unroll") for (int k = 0; k < 2; ++k) \
;     dst[m][k] = *reinterpret_cast<const bf16x8*>((char*)SA(b, h) + lds_byte(wr * 64 + m * 16 + fr, k * 32 + fq * 8))
; #define LDB(dst, b, h) _Pragma("unroll") for (int n = 0; n < 2; ++n) _Pragma("unroll") for (int k = 0; k < 2; ++k) \
;     dst[n][k] = *reinterpret_cast<const bf16x8*>((char*)SB(b, h) + lds_byte(wc * 32 + n * 16 + fr, k * 32 + fq * 8))
; #define MMA(ai, bj, At_, Bt_) do { __builtin_amdgcn_s_setprio(1); \
;     _Pragma("unroll") for (int m = 0; m < 4; ++m) _Pragma("unroll") for (int n = 0; n < 2; ++n) _Pragma("unroll") for (int k = 0; k < 2; ++k) \
;       acc[ai][bj][m][n] = __builtin_amdgcn_mfma_f32_16x16x32_bf16(At_[m][k], Bt_[n][k], acc[ai][bj][m][n], 0, 0, 0); \
;     __builtin_amdgcn_s_setprio(0); } while (0)
; #define WAIT_V(n) asm volatile("s_waitcnt vmcnt(" #n ")" ::: "memory")
; #define BAR __builtin_amdgcn_s_barrier()
; template <int PRE> ...
;     ...
;   for (int t = 0; t < nt; t += 2) {
;     LDB(B0, 0, 0); SCHED; LDA(At, 0, 0); STAGE(SA(1, 1), A, brow + HALF, t + 1);
;     WAIT_L(8); BAR; WAIT_L(0); MMA(0, 0, At, B0); BAR; SCHED;
;     LDB(B1, 0, 1); STAGEW(SB(0, 0), Bt, bcol, bcol_n, t + 2);
;     BAR; WAIT_L(0); MMA(0, 1, At, B1); BAR;
;     LDA(At, 0, 1); STAGEW(SA(0, 0), A, brow, brow_n, t + 2);
;     BAR; WAIT_L(0); MMA(1, 0, At, B0); BAR; SCHED;
;     STAGEW(SB(0, 1), Bt, bcol + HALF, bcol_n + HALF, t + 2);
;     WAIT_V(6); BAR; MMA(1, 1, At, B1); BAR;
;     LDB(B0, 1, 0); SCHED; LDA(At, 1, 0); STAGEW(SA(0, 1), A, brow + HALF, brow_n + HALF, t + 2);
;     WAIT_L(8); BAR; WAIT_L(0); MMA(0, 0, At, B0); BAR; SCHED;
;     LDB(B1, 1, 1); STAGEW(SB(1, 0), Bt, bcol, bcol_n, t + 3);
;     BAR; WAIT_L(0); MMA(0, 1, At, B1); BAR;
;     LDA(At, 1, 1); STAGEW(SA(1, 0), A, brow, brow_n, t + 3);
;     BAR; WAIT_L(0); MMA(1, 0, At, B0); BAR; SCHED;
;     STAGEW(SB(1, 1), Bt, bcol + HALF, bcol_n + HALF, t + 3);
;     WAIT_V(6); BAR; MMA(1, 1, At, B1); BAR;
;   }
.LBB0_550:
	v_add_u32_e32 v144, s81, v139
	ds_read_b128 v[146:149], v144
	ds_read_b128 v[150:153], v144 offset:1024
	ds_read_b128 v[154:157], v144 offset:2048
	ds_read_b128 v[158:161], v144 offset:3072
	s_add_i32 m0, s1, 0xc000
	ds_read_b128 v[168:171], v140
	ds_read_b128 v[172:175], v140 offset:1024
	ds_read_b128 v[176:179], v141
	ds_read_b128 v[180:183], v141 offset:1024
	ds_read_b128 v[184:187], v142
	ds_read_b128 v[188:191], v142 offset:1024
	ds_read_b128 v[192:195], v143
	ds_read_b128 v[210:213], v143 offset:1024
	global_load_lds_dwordx4 v[136:137], off
	v_lshl_add_u64 v[162:163], v[136:137], 0, s[86:87]
	s_add_i32 m0, s1, 0xe000
	s_nop 0
	global_load_lds_dwordx4 v[162:163], off
	s_waitcnt lgkmcnt(8)
	s_barrier
	s_waitcnt lgkmcnt(0)
	s_waitcnt lgkmcnt(0)
	v_mfma_f32_16x16x32_bf16 v[124:127], v[168:171], v[146:149], v[124:127]
	v_mfma_f32_16x16x32_bf16 v[120:123], v[168:171], v[154:157], v[120:123]
	v_mfma_f32_16x16x32_bf16 v[116:119], v[176:179], v[146:149], v[116:119]
	v_mfma_f32_16x16x32_bf16 v[112:115], v[176:179], v[154:157], v[112:115]
	v_mfma_f32_16x16x32_bf16 v[108:111], v[184:187], v[146:149], v[108:111]
	v_mfma_f32_16x16x32_bf16 v[104:107], v[184:187], v[154:157], v[104:107]
	v_mfma_f32_16x16x32_bf16 v[100:103], v[192:195], v[146:149], v[100:103]
	v_mfma_f32_16x16x32_bf16 v[96:99], v[192:195], v[154:157], v[96:99]
	v_mfma_f32_16x16x32_bf16 v[124:127], v[172:175], v[150:153], v[124:127]
	v_mfma_f32_16x16x32_bf16 v[120:123], v[172:175], v[158:161], v[120:123]
	v_mfma_f32_16x16x32_bf16 v[116:119], v[180:183], v[150:153], v[116:119]
	v_mfma_f32_16x16x32_bf16 v[112:115], v[180:183], v[158:161], v[112:115]
	v_mfma_f32_16x16x32_bf16 v[108:111], v[188:191], v[150:153], v[108:111]
	v_mfma_f32_16x16x32_bf16 v[104:107], v[188:191], v[158:161], v[104:107]
	v_mfma_f32_16x16x32_bf16 v[100:103], v[210:213], v[150:153], v[100:103]
	v_mfma_f32_16x16x32_bf16 v[96:99], v[210:213], v[158:161], v[96:99]
	s_barrier
	s_add_i32 s22, s21, 2
	s_cmp_lt_u32 s21, 30
	s_cselect_b64 s[4:5], -1, 0
	s_and_b64 vcc, s[4:5], exec
	s_cselect_b32 s4, 0, 0xffffffe0
	s_add_i32 s18, s22, s4
	s_lshl_b64 s[4:5], s[18:19], 7
	s_mov_b32 m0, s6
	v_add_u32_e32 v144, s82, v139
	v_lshl_add_u64 v[162:163], v[128:129], 0, s[4:5]
	ds_read_b128 v[214:217], v144
	ds_read_b128 v[218:221], v144 offset:1024
	ds_read_b128 v[222:225], v144 offset:2048
	ds_read_b128 v[226:229], v144 offset:3072
	global_load_lds_dwordx4 v[162:163], off
	v_lshl_add_u64 v[162:163], v[162:163], 0, s[86:87]
	s_mov_b32 m0, s7
	s_nop 0
	global_load_lds_dwordx4 v[162:163], off
	s_barrier
	s_waitcnt lgkmcnt(0)
	s_waitcnt lgkmcnt(0)
	v_mfma_f32_16x16x32_bf16 v[92:95], v[168:171], v[214:217], v[92:95]
	v_mfma_f32_16x16x32_bf16 v[88:91], v[168:171], v[222:225], v[88:91]
	v_mfma_f32_16x16x32_bf16 v[84:87], v[176:179], v[214:217], v[84:87]
	v_mfma_f32_16x16x32_bf16 v[80:83], v[176:179], v[222:225], v[80:83]
	v_mfma_f32_16x16x32_bf16 v[76:79], v[184:187], v[214:217], v[76:79]
	v_mfma_f32_16x16x32_bf16 v[72:75], v[184:187], v[222:225], v[72:75]
	v_mfma_f32_16x16x32_bf16 v[68:71], v[192:195], v[214:217], v[68:71]
	v_mfma_f32_16x16x32_bf16 v[64:67], v[192:195], v[222:225], v[64:67]
	v_mfma_f32_16x16x32_bf16 v[92:95], v[172:175], v[218:221], v[92:95]
	v_mfma_f32_16x16x32_bf16 v[88:91], v[172:175], v[226:229], v[88:91]
	v_mfma_f32_16x16x32_bf16 v[84:87], v[180:183], v[218:221], v[84:87]
	v_mfma_f32_16x16x32_bf16 v[80:83], v[180:183], v[226:229], v[80:83]
	v_mfma_f32_16x16x32_bf16 v[76:79], v[188:191], v[218:221], v[76:79]
	v_mfma_f32_16x16x32_bf16 v[72:75], v[188:191], v[226:229], v[72:75]
	v_mfma_f32_16x16x32_bf16 v[68:71], v[210:213], v[218:221], v[68:71]
	v_mfma_f32_16x16x32_bf16 v[64:67], v[210:213], v[226:229], v[64:67]
	s_mov_b32 m0, s1
	v_lshl_add_u64 v[162:163], v[130:131], 0, s[4:5]
	s_barrier
	ds_read_b128 v[168:171], v140 offset:16384
	ds_read_b128 v[172:175], v140 offset:17408
	ds_read_b128 v[176:179], v141 offset:16384
	ds_read_b128 v[180:183], v141 offset:17408
	ds_read_b128 v[184:187], v142 offset:16384
	ds_read_b128 v[188:191], v142 offset:17408
	ds_read_b128 v[192:195], v143 offset:16384
	ds_read_b128 v[210:213], v143 offset:17408
	global_load_lds_dwordx4 v[162:163], off
	v_lshl_add_u64 v[162:163], v[162:163], 0, s[86:87]
	s_mov_b32 m0, s3
	s_nop 0
	global_load_lds_dwordx4 v[162:163], off
	s_barrier
	s_waitcnt lgkmcnt(0)
	s_waitcnt lgkmcnt(0)
	v_mfma_f32_16x16x32_bf16 v[60:63], v[168:171], v[146:149], v[60:63]
	v_mfma_f32_16x16x32_bf16 v[56:59], v[168:171], v[154:157], v[56:59]
	v_mfma_f32_16x16x32_bf16 v[52:55], v[176:179], v[146:149], v[52:55]
	v_mfma_f32_16x16x32_bf16 v[48:51], v[176:179], v[154:157], v[48:51]
	v_mfma_f32_16x16x32_bf16 v[44:47], v[184:187], v[146:149], v[44:47]
	v_mfma_f32_16x16x32_bf16 v[40:43], v[184:187], v[154:157], v[40:43]
	v_mfma_f32_16x16x32_bf16 v[36:39], v[192:195], v[146:149], v[36:39]
	v_mfma_f32_16x16x32_bf16 v[32:35], v[192:195], v[154:157], v[32:35]
	v_mfma_f32_16x16x32_bf16 v[60:63], v[172:175], v[150:153], v[60:63]
	v_mfma_f32_16x16x32_bf16 v[56:59], v[172:175], v[158:161], v[56:59]
	v_mfma_f32_16x16x32_bf16 v[52:55], v[180:183], v[150:153], v[52:55]
	v_mfma_f32_16x16x32_bf16 v[48:51], v[180:183], v[158:161], v[48:51]
	v_mfma_f32_16x16x32_bf16 v[44:47], v[188:191], v[150:153], v[44:47]
	v_mfma_f32_16x16x32_bf16 v[40:43], v[188:191], v[158:161], v[40:43]
	v_mfma_f32_16x16x32_bf16 v[36:39], v[210:213], v[150:153], v[36:39]
	v_mfma_f32_16x16x32_bf16 v[32:35], v[210:213], v[158:161], v[32:35]
	s_barrier
	s_mov_b32 m0, s8
	v_lshl_add_u64 v[146:147], v[132:133], 0, s[4:5]
	global_load_lds_dwordx4 v[146:147], off
	v_lshl_add_u64 v[146:147], v[146:147], 0, s[86:87]
	s_mov_b32 m0, s9
	s_nop 0
	global_load_lds_dwordx4 v[146:147], off
	s_waitcnt vmcnt(6)
	s_barrier
; #define STAGE(P_, BASE, br, kt) do { const u16* _gb = (BASE) + (long)(br) * K + (long)(kt) * BK; \
;     _Pragma("unroll") for (int _i = 0; _i < 2; ++_i) { \
;       __builtin_amdgcn_global_load_lds((const unsigned*)(_gb + (long)_i * 64 * K + lane_off), \
;         (unsigned*)((char*)(P_) + lds_wbase + _i * 8192), 16, 0, 0); } } while (0)
; #define LDA(dst, b, h) _Pragma("unroll") for (int m = 0; m < 4; ++m) _Pragma("unroll") for (int k = 0; k < 2; ++k) \
;     dst[m][k] = *reinterpret_cast<const bf16x8*>((char*)SA(b, h) + lds_byte(wr * 64 + m * 16 + fr, k * 32 + fq * 8))
; #define LDB(dst, b, h) _Pragma("unroll") for (int n = 0; n < 2; ++n) _Pragma("unroll") for (int k = 0; k < 2; ++k) \
;     dst[n][k] = *reinterpret_cast<const bf16x8*>((char*)SB(b, h) + lds_byte(wc * 32 + n * 16 + fr, k * 32 + fq * 8))
; #define MMA(ai, bj, At_, Bt_) do { __builtin_amdgcn_s_setprio(1); \
;     _Pragma("unroll") for (int m = 0; m < 4; ++m) _Pragma("unroll") for (int n = 0; n < 2; ++n) _Pragma("unroll") for (int k = 0; k < 2; ++k) \
;       acc[ai][bj][m][n] = __builtin_amdgcn_mfma_f32_16x16x32_bf16(At_[m][k], Bt_[n][k], acc[ai][bj][m][n], 0, 0, 0); \
;     __builtin_amdgcn_s_setprio(0); } while (0)
; #define WAIT_V(n) asm volatile("s_waitcnt vmcnt(" #n ")" ::: "memory")
; #define BAR __builtin_amdgcn_s_barrier()
; template <int PRE> ...
;     ...
;   for (int t = 0; t < nt; t += 2) {
;     LDB(B0, 0, 0); SCHED; LDA(At, 0, 0); STAGE(SA(1, 1), A, brow + HALF, t + 1);
;     WAIT_L(8); BAR; WAIT_L(0); MMA(0, 0, At, B0); BAR; SCHED;
;     LDB(B1, 0, 1); STAGEW(SB(0, 0), Bt, bcol, bcol_n, t + 2);
;     BAR; WAIT_L(0); MMA(0, 1, At, B1); BAR;
;     LDA(At, 0, 1); STAGEW(SA(0, 0), A, brow, brow_n, t + 2);
;     BAR; WAIT_L(0); MMA(1, 0, At, B0); BAR; SCHED;
;     STAGEW(SB(0, 1), Bt, bcol + HALF, bcol_n + HALF, t + 2);
;     WAIT_V(6); BAR; MMA(1, 1, At, B1); BAR;
;     LDB(B0, 1, 0); SCHED; LDA(At, 1, 0); STAGEW(SA(0, 1), A, brow + HALF, brow_n + HALF, t + 2);
;     WAIT_L(8); BAR; WAIT_L(0); MMA(0, 0, At, B0); BAR; SCHED;
;     LDB(B1, 1, 1); STAGEW(SB(1, 0), Bt, bcol, bcol_n, t + 3);
;     BAR; WAIT_L(0); MMA(0, 1, At, B1); BAR;
;     LDA(At, 1, 1); STAGEW(SA(1, 0), A, brow, brow_n, t + 3);
;     BAR; WAIT_L(0); MMA(1, 0, At, B0); BAR; SCHED;
;     STAGEW(SB(1, 1), Bt, bcol + HALF, bcol_n + HALF, t + 3);
;     WAIT_V(6); BAR; MMA(1, 1, At, B1); BAR;
;   }
	v_mfma_f32_16x16x32_bf16 v[28:31], v[168:171], v[214:217], v[28:31]
	v_mfma_f32_16x16x32_bf16 v[24:27], v[168:171], v[222:225], v[24:27]
	v_mfma_f32_16x16x32_bf16 v[20:23], v[176:179], v[214:217], v[20:23]
	v_mfma_f32_16x16x32_bf16 v[16:19], v[176:179], v[222:225], v[16:19]
	v_mfma_f32_16x16x32_bf16 v[12:15], v[184:187], v[214:217], v[12:15]
	v_mfma_f32_16x16x32_bf16 v[8:11], v[184:187], v[222:225], v[8:11]
	v_mfma_f32_16x16x32_bf16 v[4:7], v[192:195], v[214:217], v[4:7]
	v_mfma_f32_16x16x32_bf16 v[0:3], v[192:195], v[222:225], v[0:3]
	v_mfma_f32_16x16x32_bf16 v[28:31], v[172:175], v[218:221], v[28:31]
	v_mfma_f32_16x16x32_bf16 v[24:27], v[172:175], v[226:229], v[24:27]
	v_mfma_f32_16x16x32_bf16 v[20:23], v[180:183], v[218:221], v[20:23]
	v_mfma_f32_16x16x32_bf16 v[16:19], v[180:183], v[226:229], v[16:19]
	v_mfma_f32_16x16x32_bf16 v[12:15], v[188:191], v[218:221], v[12:15]
	v_mfma_f32_16x16x32_bf16 v[8:11], v[188:191], v[226:229], v[8:11]
	v_mfma_f32_16x16x32_bf16 v[4:7], v[210:213], v[218:221], v[4:7]
	v_mfma_f32_16x16x32_bf16 v[0:3], v[210:213], v[226:229], v[0:3]
	v_add_u32_e32 v144, s83, v139
	s_barrier
	ds_read_b128 v[146:149], v144
	ds_read_b128 v[150:153], v144 offset:1024
	ds_read_b128 v[154:157], v144 offset:2048
	ds_read_b128 v[158:161], v144 offset:3072
	s_mov_b32 m0, s10
	v_lshl_add_u64 v[162:163], v[134:135], 0, s[4:5]
	ds_read_b128 v[168:171], v140 offset:32768
	ds_read_b128 v[172:175], v140 offset:33792
	ds_read_b128 v[176:179], v141 offset:32768
	ds_read_b128 v[180:183], v141 offset:33792
	ds_read_b128 v[184:187], v142 offset:32768
	ds_read_b128 v[188:191], v142 offset:33792
	ds_read_b128 v[192:195], v143 offset:32768
	ds_read_b128 v[210:213], v143 offset:33792
	global_load_lds_dwordx4 v[162:163], off
	v_lshl_add_u64 v[162:163], v[162:163], 0, s[86:87]
	s_mov_b32 m0, s11
	s_nop 0
	global_load_lds_dwordx4 v[162:163], off
	s_waitcnt lgkmcnt(8)
	s_barrier
	s_waitcnt lgkmcnt(0)
	s_waitcnt lgkmcnt(0)
	v_mfma_f32_16x16x32_bf16 v[124:127], v[168:171], v[146:149], v[124:127]
	v_mfma_f32_16x16x32_bf16 v[120:123], v[168:171], v[154:157], v[120:123]
	v_mfma_f32_16x16x32_bf16 v[116:119], v[176:179], v[146:149], v[116:119]
	v_mfma_f32_16x16x32_bf16 v[112:115], v[176:179], v[154:157], v[112:115]
	v_mfma_f32_16x16x32_bf16 v[108:111], v[184:187], v[146:149], v[108:111]
	v_mfma_f32_16x16x32_bf16 v[104:107], v[184:187], v[154:157], v[104:107]
	v_mfma_f32_16x16x32_bf16 v[100:103], v[192:195], v[146:149], v[100:103]
	v_mfma_f32_16x16x32_bf16 v[96:99], v[192:195], v[154:157], v[96:99]
	v_mfma_f32_16x16x32_bf16 v[124:127], v[172:175], v[150:153], v[124:127]
	v_mfma_f32_16x16x32_bf16 v[120:123], v[172:175], v[158:161], v[120:123]
	v_mfma_f32_16x16x32_bf16 v[116:119], v[180:183], v[150:153], v[116:119]
	v_mfma_f32_16x16x32_bf16 v[112:115], v[180:183], v[158:161], v[112:115]
	v_mfma_f32_16x16x32_bf16 v[108:111], v[188:191], v[150:153], v[108:111]
	v_mfma_f32_16x16x32_bf16 v[104:107], v[188:191], v[158:161], v[104:107]
	v_mfma_f32_16x16x32_bf16 v[100:103], v[210:213], v[150:153], v[100:103]
	v_mfma_f32_16x16x32_bf16 v[96:99], v[210:213], v[158:161], v[96:99]
	s_barrier
	s_cmp_lt_u32 s21, 29
	s_cselect_b32 s4, 0, 0xffffffe0
	s_add_i32 s4, s4, s21
	s_add_i32 s18, s4, 3
	s_lshl_b64 s[4:5], s[18:19], 7
	s_mov_b32 m0, s13
	v_add_u32_e32 v144, s84, v139
	v_lshl_add_u64 v[162:163], v[128:129], 0, s[4:5]
	ds_read_b128 v[214:217], v144
	ds_read_b128 v[218:221], v144 offset:1024
	ds_read_b128 v[222:225], v144 offset:2048
	ds_read_b128 v[226:229], v144 offset:3072
	global_load_lds_dwordx4 v[162:163], off
	v_lshl_add_u64 v[162:163], v[162:163], 0, s[86:87]
	s_mov_b32 m0, s14
	s_nop 0
	global_load_lds_dwordx4 v[162:163], off
	s_barrier
; #define STAGE(P_, BASE, br, kt) do { const u16* _gb = (BASE) + (long)(br) * K + (long)(kt) * BK; \
;     _Pragma("unroll") for (int _i = 0; _i < 2; ++_i) { \
;       __builtin_amdgcn_global_load_lds((const unsigned*)(_gb + (long)_i * 64 * K + lane_off), \
;         (unsigned*)((char*)(P_) + lds_wbase + _i * 8192), 16, 0, 0); } } while (0)
; #define LDA(dst, b, h) _Pragma("unroll") for (int m = 0; m < 4; ++m) _Pragma("unroll") for (int k = 0; k < 2; ++k) \
;     dst[m][k] = *reinterpret_cast<const bf16x8*>((char*)SA(b, h) + lds_byte(wr * 64 + m * 16 + fr, k * 32 + fq * 8))
; #define LDB(dst, b, h) _Pragma("unroll") for (int n = 0; n < 2; ++n) _Pragma("unroll") for (int k = 0; k < 2; ++k) \
;     dst[n][k] = *reinterpret_cast<const bf16x8*>((char*)SB(b, h) + lds_byte(wc * 32 + n * 16 + fr, k * 32 + fq * 8))
; #define MMA(ai, bj, At_, Bt_) do { __builtin_amdgcn_s_setprio(1); \
;     _Pragma("unroll") for (int m = 0; m < 4; ++m) _Pragma("unroll") for (int n = 0; n < 2; ++n) _Pragma("unroll") for (int k = 0; k < 2; ++k) \
;       acc[ai][bj][m][n] = __builtin_amdgcn_mfma_f32_16x16x32_bf16(At_[m][k], Bt_[n][k], acc[ai][bj][m][n], 0, 0, 0); \
;     __builtin_amdgcn_s_setprio(0); } while (0)
; #define WAIT_V(n) asm volatile("s_waitcnt vmcnt(" #n ")" ::: "memory")
; #define BAR __builtin_amdgcn_s_barrier()
; template <int PRE> ...
;     ...
;   for (int t = 0; t < nt; t += 2) {
;     LDB(B0, 0, 0); SCHED; LDA(At, 0, 0); STAGE(SA(1, 1), A, brow + HALF, t + 1);
;     WAIT_L(8); BAR; WAIT_L(0); MMA(0, 0, At, B0); BAR; SCHED;
;     LDB(B1, 0, 1); STAGEW(SB(0, 0), Bt, bcol, bcol_n, t + 2);
;     BAR; WAIT_L(0); MMA(0, 1, At, B1); BAR;
;     LDA(At, 0, 1); STAGEW(SA(0, 0), A, brow, brow_n, t + 2);
;     BAR; WAIT_L(0); MMA(1, 0, At, B0); BAR; SCHED;
;     STAGEW(SB(0, 1), Bt, bcol + HALF, bcol_n + HALF, t + 2);
;     WAIT_V(6); BAR; MMA(1, 1, At, B1); BAR;
;     LDB(B0, 1, 0); SCHED; LDA(At, 1, 0); STAGEW(SA(0, 1), A, brow + HALF, brow_n + HALF, t + 2);
;     WAIT_L(8); BAR; WAIT_L(0); MMA(0, 0, At, B0); BAR; SCHED;
;     LDB(B1, 1, 1); STAGEW(SB(1, 0), Bt, bcol, bcol_n, t + 3);
;     BAR; WAIT_L(0); MMA(0, 1, At, B1); BAR;
;     LDA(At, 1, 1); STAGEW(SA(1, 0), A, brow, brow_n, t + 3);
;     BAR; WAIT_L(0); MMA(1, 0, At, B0); BAR; SCHED;
;     STAGEW(SB(1, 1), Bt, bcol + HALF, bcol_n + HALF, t + 3);
;     WAIT_V(6); BAR; MMA(1, 1, At, B1); BAR;
;   }
;   if (wr == 0) BAR;
	s_waitcnt lgkmcnt(0)
	s_waitcnt lgkmcnt(0)
	v_mfma_f32_16x16x32_bf16 v[92:95], v[168:171], v[214:217], v[92:95]
	v_mfma_f32_16x16x32_bf16 v[88:91], v[168:171], v[222:225], v[88:91]
	v_mfma_f32_16x16x32_bf16 v[84:87], v[176:179], v[214:217], v[84:87]
	v_mfma_f32_16x16x32_bf16 v[80:83], v[176:179], v[222:225], v[80:83]
	v_mfma_f32_16x16x32_bf16 v[76:79], v[184:187], v[214:217], v[76:79]
	v_mfma_f32_16x16x32_bf16 v[72:75], v[184:187], v[222:225], v[72:75]
	v_mfma_f32_16x16x32_bf16 v[68:71], v[192:195], v[214:217], v[68:71]
	v_mfma_f32_16x16x32_bf16 v[64:67], v[192:195], v[222:225], v[64:67]
	v_mfma_f32_16x16x32_bf16 v[92:95], v[172:175], v[218:221], v[92:95]
	v_mfma_f32_16x16x32_bf16 v[88:91], v[172:175], v[226:229], v[88:91]
	v_mfma_f32_16x16x32_bf16 v[84:87], v[180:183], v[218:221], v[84:87]
	v_mfma_f32_16x16x32_bf16 v[80:83], v[180:183], v[226:229], v[80:83]
	v_mfma_f32_16x16x32_bf16 v[76:79], v[188:191], v[218:221], v[76:79]
	v_mfma_f32_16x16x32_bf16 v[72:75], v[188:191], v[226:229], v[72:75]
	v_mfma_f32_16x16x32_bf16 v[68:71], v[210:213], v[218:221], v[68:71]
	v_mfma_f32_16x16x32_bf16 v[64:67], v[210:213], v[226:229], v[64:67]
	s_mov_b32 m0, s15
	v_lshl_add_u64 v[162:163], v[130:131], 0, s[4:5]
	s_barrier
	ds_read_b128 v[168:171], v140 offset:49152
	ds_read_b128 v[172:175], v140 offset:50176
	ds_read_b128 v[176:179], v141 offset:49152
	ds_read_b128 v[180:183], v141 offset:50176
	ds_read_b128 v[184:187], v142 offset:49152
	ds_read_b128 v[188:191], v142 offset:50176
	ds_read_b128 v[192:195], v143 offset:49152
	ds_read_b128 v[210:213], v143 offset:50176
	global_load_lds_dwordx4 v[162:163], off
	v_lshl_add_u64 v[162:163], v[162:163], 0, s[86:87]
	s_mov_b32 m0, s16
	s_nop 0
	global_load_lds_dwordx4 v[162:163], off
	s_barrier
	s_waitcnt lgkmcnt(0)
	s_waitcnt lgkmcnt(0)
	v_mfma_f32_16x16x32_bf16 v[60:63], v[168:171], v[146:149], v[60:63]
	v_mfma_f32_16x16x32_bf16 v[56:59], v[168:171], v[154:157], v[56:59]
	v_mfma_f32_16x16x32_bf16 v[52:55], v[176:179], v[146:149], v[52:55]
	v_mfma_f32_16x16x32_bf16 v[48:51], v[176:179], v[154:157], v[48:51]
	v_mfma_f32_16x16x32_bf16 v[44:47], v[184:187], v[146:149], v[44:47]
	v_mfma_f32_16x16x32_bf16 v[40:43], v[184:187], v[154:157], v[40:43]
	v_mfma_f32_16x16x32_bf16 v[36:39], v[192:195], v[146:149], v[36:39]
	v_mfma_f32_16x16x32_bf16 v[32:35], v[192:195], v[154:157], v[32:35]
	v_mfma_f32_16x16x32_bf16 v[60:63], v[172:175], v[150:153], v[60:63]
	v_mfma_f32_16x16x32_bf16 v[56:59], v[172:175], v[158:161], v[56:59]
	v_mfma_f32_16x16x32_bf16 v[52:55], v[180:183], v[150:153], v[52:55]
	v_mfma_f32_16x16x32_bf16 v[48:51], v[180:183], v[158:161], v[48:51]
	v_mfma_f32_16x16x32_bf16 v[44:47], v[188:191], v[150:153], v[44:47]
	v_mfma_f32_16x16x32_bf16 v[40:43], v[188:191], v[158:161], v[40:43]
	v_mfma_f32_16x16x32_bf16 v[36:39], v[210:213], v[150:153], v[36:39]
	v_mfma_f32_16x16x32_bf16 v[32:35], v[210:213], v[158:161], v[32:35]
	s_barrier
	s_mov_b32 m0, s17
	v_lshl_add_u64 v[146:147], v[132:133], 0, s[4:5]
	global_load_lds_dwordx4 v[146:147], off
	v_lshl_add_u64 v[146:147], v[146:147], 0, s[86:87]
	s_mov_b32 m0, s20
	s_nop 0
	global_load_lds_dwordx4 v[146:147], off
	s_waitcnt vmcnt(6)
	s_barrier
	v_mfma_f32_16x16x32_bf16 v[28:31], v[168:171], v[214:217], v[28:31]
	v_mfma_f32_16x16x32_bf16 v[24:27], v[168:171], v[222:225], v[24:27]
	v_mfma_f32_16x16x32_bf16 v[20:23], v[176:179], v[214:217], v[20:23]
	v_mfma_f32_16x16x32_bf16 v[16:19], v[176:179], v[222:225], v[16:19]
	v_mfma_f32_16x16x32_bf16 v[12:15], v[184:187], v[214:217], v[12:15]
	v_mfma_f32_16x16x32_bf16 v[8:11], v[184:187], v[222:225], v[8:11]
	v_mfma_f32_16x16x32_bf16 v[4:7], v[192:195], v[214:217], v[4:7]
	v_mfma_f32_16x16x32_bf16 v[0:3], v[192:195], v[222:225], v[0:3]
	v_mfma_f32_16x16x32_bf16 v[28:31], v[172:175], v[218:221], v[28:31]
	v_mfma_f32_16x16x32_bf16 v[24:27], v[172:175], v[226:229], v[24:27]
	v_mfma_f32_16x16x32_bf16 v[20:23], v[180:183], v[218:221], v[20:23]
	v_mfma_f32_16x16x32_bf16 v[16:19], v[180:183], v[226:229], v[16:19]
	v_mfma_f32_16x16x32_bf16 v[12:15], v[188:191], v[218:221], v[12:15]
	v_mfma_f32_16x16x32_bf16 v[8:11], v[188:191], v[226:229], v[8:11]
	v_mfma_f32_16x16x32_bf16 v[4:7], v[210:213], v[218:221], v[4:7]
	v_mfma_f32_16x16x32_bf16 v[0:3], v[210:213], v[226:229], v[0:3]
	v_lshl_add_u64 v[136:137], v[136:137], 0, s[46:47]
	s_mov_b32 s21, s22
	s_barrier
	s_cbranch_vccnz .LBB0_550
	s_andn2_b64 vcc, exec, s[58:59]
	s_cbranch_vccnz .LBB0_553
	s_barrier

; __device__ __forceinline__ void attn_item(const Params& P, const int pass, const int item, const int wvi) {
;     ...
;   const float linv = 1.f / lrun;
; #pragma unroll
;   for (int d8 = 0; d8 < 8; d8 += 2) {
;     uint2 oa, ob;
;     oa.x = pk2(oacc[d8][0] * linv, oacc[d8][1] * linv); oa.y = pk2(oacc[d8][2] * linv, oacc[d8][3] * linv);
;     ob.x = pk2(oacc[d8 + 1][0] * linv, oacc[d8 + 1][1] * linv); ob.y = pk2(oacc[d8 + 1][2] * linv, oacc[d8 + 1][3] * linv);
;     *(uint4*)(qbuf + (size_t)(qb + w * 16 + fr) * DM + h * 128 + (d8 + (fq & 1)) * 16 + (fq & ~1) * 4) = swap_pair(oa, ob);
;   }
;   __builtin_amdgcn_s_setprio(0);
;   __syncthreads();
.LBB0_626:
	v_div_scale_f32 v0, s[0:1], v82, v82, 1.0
	v_rcp_f32_e32 v1, v0
	v_div_scale_f32 v2, vcc, 1.0, v82, 1.0
	v_fma_f32 v3, -v0, v1, 1.0
	v_fmac_f32_e32 v1, v3, v1
	v_mul_f32_e32 v3, v2, v1
	v_fma_f32 v4, -v0, v3, v2
	v_fmac_f32_e32 v3, v4, v1
	v_fma_f32 v0, -v0, v3, v2
	v_div_fmas_f32 v0, v0, v1, v3
	v_div_fixup_f32 v6, v0, v82, 1.0
	v_and_b32_e32 v0, 8, v89
	v_lshlrev_b32_e32 v144, 1, v0
	v_mul_f32_e32 v0, v6, v48
	v_mul_f32_e32 v1, v6, v49
	v_cvt_pk_bf16_f32 v0, v0, v1
	v_mul_f32_e32 v1, v6, v50
	v_mul_f32_e32 v2, v6, v51
	v_cvt_pk_bf16_f32 v1, v1, v2
	v_mul_f32_e32 v2, v6, v56
	v_mul_f32_e32 v3, v6, v57
	v_cvt_pk_bf16_f32 v2, v2, v3
	v_mul_f32_e32 v3, v6, v58
	v_mul_f32_e32 v7, v6, v59
	v_cvt_pk_bf16_f32 v3, v3, v7
	v_and_b32_e32 v7, 16, v100
	v_lshl_add_u64 v[4:5], v[84:85], 0, v[144:145]
	v_lshlrev_b32_e32 v144, 1, v7
	v_permlane16_swap_b32_e32 v0, v2
	v_permlane16_swap_b32_e32 v1, v3
	v_lshl_add_u64 v[4:5], v[4:5], 0, v[144:145]
	global_store_dwordx4 v[4:5], v[0:3], off
	v_mul_f32_e32 v7, v6, v63
	s_nop 0
	v_mul_f32_e32 v0, v6, v52
	v_mul_f32_e32 v1, v6, v53
	v_cvt_pk_bf16_f32 v0, v0, v1
	v_mul_f32_e32 v1, v6, v54
	v_mul_f32_e32 v2, v6, v55
	v_cvt_pk_bf16_f32 v1, v1, v2
	v_mul_f32_e32 v2, v6, v60
	v_mul_f32_e32 v3, v6, v61
	v_cvt_pk_bf16_f32 v2, v2, v3
	v_mul_f32_e32 v3, v6, v62
	v_cvt_pk_bf16_f32 v3, v3, v7
	v_permlane16_swap_b32_e32 v0, v2
	s_nop 0
	v_permlane16_swap_b32_e32 v1, v3
	global_store_dwordx4 v[4:5], v[0:3], off offset:64
	v_mul_f32_e32 v7, v6, v71
	s_nop 0
	v_mul_f32_e32 v0, v6, v64
	v_mul_f32_e32 v1, v6, v65
	v_cvt_pk_bf16_f32 v0, v0, v1
	v_mul_f32_e32 v1, v6, v66
	v_mul_f32_e32 v2, v6, v67
	v_cvt_pk_bf16_f32 v1, v1, v2
	v_mul_f32_e32 v2, v6, v68
	v_mul_f32_e32 v3, v6, v69
	v_cvt_pk_bf16_f32 v2, v2, v3
	v_mul_f32_e32 v3, v6, v70
	v_cvt_pk_bf16_f32 v3, v3, v7
	v_permlane16_swap_b32_e32 v0, v2
	s_nop 0
	v_permlane16_swap_b32_e32 v1, v3
	global_store_dwordx4 v[4:5], v[0:3], off offset:128
	s_nop 1
	v_mul_f32_e32 v0, v6, v72
	v_mul_f32_e32 v1, v6, v73
	v_cvt_pk_bf16_f32 v0, v0, v1
	v_mul_f32_e32 v1, v6, v74
	v_mul_f32_e32 v2, v6, v75
	v_cvt_pk_bf16_f32 v1, v1, v2
	v_mul_f32_e32 v2, v6, v76
	v_mul_f32_e32 v3, v6, v77
	v_cvt_pk_bf16_f32 v2, v2, v3
	v_mul_f32_e32 v3, v6, v78
	v_mul_f32_e32 v6, v6, v79
	v_cvt_pk_bf16_f32 v3, v3, v6
	v_permlane16_swap_b32_e32 v0, v2
	s_nop 0
	v_permlane16_swap_b32_e32 v1, v3
	global_store_dwordx4 v[4:5], v[0:3], off offset:192
	s_barrier

; #define STAGE(P_, BASE, br, kt) do { const u16* _gb = (BASE) + (long)(br) * K + (long)(kt) * BK; \
;     _Pragma("unroll") for (int _i = 0; _i < 2; ++_i) { \
;       __builtin_amdgcn_global_load_lds((const unsigned*)(_gb + (long)_i * 64 * K + lane_off), \
;         (unsigned*)((char*)(P_) + lds_wbase + _i * 8192), 16, 0, 0); } } while (0)
; #define LDA(dst, b, h) _Pragma("unroll") for (int m = 0; m < 4; ++m) _Pragma("unroll") for (int k = 0; k < 2; ++k) \
;     dst[m][k] = *reinterpret_cast<const bf16x8*>((char*)SA(b, h) + lds_byte(wr * 64 + m * 16 + fr, k * 32 + fq * 8))
; #define LDB(dst, b, h) _Pragma("unroll") for (int n = 0; n < 2; ++n) _Pragma("unroll") for (int k = 0; k < 2; ++k) \
;     dst[n][k] = *reinterpret_cast<const bf16x8*>((char*)SB(b, h) + lds_byte(wc * 32 + n * 16 + fr, k * 32 + fq * 8))
; #define MMA(ai, bj, At_, Bt_) do { __builtin_amdgcn_s_setprio(1); \
;     _Pragma("unroll") for (int m = 0; m < 4; ++m) _Pragma("unroll") for (int n = 0; n < 2; ++n) _Pragma("unroll") for (int k = 0; k < 2; ++k) \
;       acc[ai][bj][m][n] = __builtin_amdgcn_mfma_f32_16x16x32_bf16(At_[m][k], Bt_[n][k], acc[ai][bj][m][n], 0, 0, 0); \
;     __builtin_amdgcn_s_setprio(0); } while (0)
; #define WAIT_V(n) asm volatile("s_waitcnt vmcnt(" #n ")" ::: "memory")
; #define BAR __builtin_amdgcn_s_barrier()
; template <int PRE> ...
;     ...
;   for (int t = 0; t < nt; t += 2) {
;     LDB(B0, 0, 0); SCHED; LDA(At, 0, 0); STAGE(SA(1, 1), A, brow + HALF, t + 1);
;     WAIT_L(8); BAR; WAIT_L(0); MMA(0, 0, At, B0); BAR; SCHED;
;     LDB(B1, 0, 1); STAGEW(SB(0, 0), Bt, bcol, bcol_n, t + 2);
;     BAR; WAIT_L(0); MMA(0, 1, At, B1); BAR;
;     LDA(At, 0, 1); STAGEW(SA(0, 0), A, brow, brow_n, t + 2);
;     BAR; WAIT_L(0); MMA(1, 0, At, B0); BAR; SCHED;
;     STAGEW(SB(0, 1), Bt, bcol + HALF, bcol_n + HALF, t + 2);
;     WAIT_V(6); BAR; MMA(1, 1, At, B1); BAR;
;     LDB(B0, 1, 0); SCHED; LDA(At, 1, 0); STAGEW(SA(0, 1), A, brow + HALF, brow_n + HALF, t + 2);
;     WAIT_L(8); BAR; WAIT_L(0); MMA(0, 0, At, B0); BAR; SCHED;
;     LDB(B1, 1, 1); STAGEW(SB(1, 0), Bt, bcol, bcol_n, t + 3);
;     BAR; WAIT_L(0); MMA(0, 1, At, B1); BAR;
;     LDA(At, 1, 1); STAGEW(SA(1, 0), A, brow, brow_n, t + 3);
;     BAR; WAIT_L(0); MMA(1, 0, At, B0); BAR; SCHED;
;     STAGEW(SB(1, 1), Bt, bcol + HALF, bcol_n + HALF, t + 3);
;     WAIT_V(6); BAR; MMA(1, 1, At, B1); BAR;
;   }
.LBB0_810:
	v_add_u32_e32 v142, s81, v147
	ds_read_b128 v[134:137], v142
	ds_read_b128 v[138:141], v142 offset:1024
	ds_read_b128 v[152:155], v142 offset:2048
	ds_read_b128 v[156:159], v142 offset:3072
	s_add_i32 m0, s10, 0xc000
	ds_read_b128 v[160:163], v144
	ds_read_b128 v[168:171], v144 offset:1024
	ds_read_b128 v[172:175], v148
	ds_read_b128 v[176:179], v148 offset:1024
	ds_read_b128 v[180:183], v149
	ds_read_b128 v[184:187], v149 offset:1024
	ds_read_b128 v[188:191], v150
	ds_read_b128 v[192:195], v150 offset:1024
	global_load_lds_dwordx4 v[132:133], off
	v_lshl_add_u64 v[142:143], v[132:133], 0, s[44:45]
	s_add_i32 m0, s10, 0xe000
	s_nop 0
	global_load_lds_dwordx4 v[142:143], off
	s_waitcnt lgkmcnt(8)
	s_barrier
	s_waitcnt lgkmcnt(0)
	s_waitcnt lgkmcnt(0)
	v_mfma_f32_16x16x32_bf16 v[124:127], v[160:163], v[134:137], v[124:127]
	v_mfma_f32_16x16x32_bf16 v[120:123], v[160:163], v[152:155], v[120:123]
	v_mfma_f32_16x16x32_bf16 v[116:119], v[172:175], v[134:137], v[116:119]
	v_mfma_f32_16x16x32_bf16 v[112:115], v[172:175], v[152:155], v[112:115]
	v_mfma_f32_16x16x32_bf16 v[108:111], v[180:183], v[134:137], v[108:111]
	v_mfma_f32_16x16x32_bf16 v[104:107], v[180:183], v[152:155], v[104:107]
	v_mfma_f32_16x16x32_bf16 v[100:103], v[188:191], v[134:137], v[100:103]
	v_mfma_f32_16x16x32_bf16 v[96:99], v[188:191], v[152:155], v[96:99]
	v_mfma_f32_16x16x32_bf16 v[124:127], v[168:171], v[138:141], v[124:127]
	v_mfma_f32_16x16x32_bf16 v[120:123], v[168:171], v[156:159], v[120:123]
	v_mfma_f32_16x16x32_bf16 v[116:119], v[176:179], v[138:141], v[116:119]
	v_mfma_f32_16x16x32_bf16 v[112:115], v[176:179], v[156:159], v[112:115]
	v_mfma_f32_16x16x32_bf16 v[108:111], v[184:187], v[138:141], v[108:111]
	v_mfma_f32_16x16x32_bf16 v[104:107], v[184:187], v[156:159], v[104:107]
	v_mfma_f32_16x16x32_bf16 v[100:103], v[192:195], v[138:141], v[100:103]
	v_mfma_f32_16x16x32_bf16 v[96:99], v[192:195], v[156:159], v[96:99]
	s_barrier
	s_add_i32 s36, s1, 2
	s_cmp_lt_u32 s1, 62
	s_cselect_b64 s[2:3], -1, 0
	s_and_b64 vcc, s[2:3], exec
	s_cselect_b32 s4, s27, s29
	s_cselect_b32 s3, 0, 0xffffffc0
	s_cselect_b32 s38, s0, s28
	s_cselect_b32 s40, s34, s31
	s_cselect_b32 s2, s30, s35
	s_ashr_i32 s5, s4, 31
	s_lshl_b64 s[4:5], s[4:5], 13
	s_add_u32 s37, s66, s4
	s_addc_u32 s39, s67, s5
	s_add_i32 s18, s36, s3
	s_lshl_b64 s[4:5], s[18:19], 7
	s_add_u32 s42, s37, s4
	v_add_u32_e32 v142, s82, v147
	s_addc_u32 s43, s39, s5
	s_mov_b32 m0, s11
	ds_read_b128 v[210:213], v142
	ds_read_b128 v[214:217], v142 offset:1024
	ds_read_b128 v[218:221], v142 offset:2048
	ds_read_b128 v[222:225], v142 offset:3072
	v_lshl_add_u64 v[142:143], s[42:43], 0, v[128:129]
	global_load_lds_dwordx4 v[142:143], off
	v_lshl_add_u64 v[142:143], v[142:143], 0, s[44:45]
	s_mov_b32 m0, s12
	s_nop 0
	global_load_lds_dwordx4 v[142:143], off
	s_barrier
	s_waitcnt lgkmcnt(0)
	s_waitcnt lgkmcnt(0)
	v_mfma_f32_16x16x32_bf16 v[92:95], v[160:163], v[210:213], v[92:95]
	v_mfma_f32_16x16x32_bf16 v[88:91], v[160:163], v[218:221], v[88:91]
	v_mfma_f32_16x16x32_bf16 v[84:87], v[172:175], v[210:213], v[84:87]
	v_mfma_f32_16x16x32_bf16 v[80:83], v[172:175], v[218:221], v[80:83]
	v_mfma_f32_16x16x32_bf16 v[76:79], v[180:183], v[210:213], v[76:79]
	v_mfma_f32_16x16x32_bf16 v[72:75], v[180:183], v[218:221], v[72:75]
	v_mfma_f32_16x16x32_bf16 v[68:71], v[188:191], v[210:213], v[68:71]
	v_mfma_f32_16x16x32_bf16 v[64:67], v[188:191], v[218:221], v[64:67]
	v_mfma_f32_16x16x32_bf16 v[92:95], v[168:171], v[214:217], v[92:95]
	v_mfma_f32_16x16x32_bf16 v[88:91], v[168:171], v[222:225], v[88:91]
	v_mfma_f32_16x16x32_bf16 v[84:87], v[176:179], v[214:217], v[84:87]
	v_mfma_f32_16x16x32_bf16 v[80:83], v[176:179], v[222:225], v[80:83]
	v_mfma_f32_16x16x32_bf16 v[76:79], v[184:187], v[214:217], v[76:79]
	v_mfma_f32_16x16x32_bf16 v[72:75], v[184:187], v[222:225], v[72:75]
	v_mfma_f32_16x16x32_bf16 v[68:71], v[192:195], v[214:217], v[68:71]
	v_mfma_f32_16x16x32_bf16 v[64:67], v[192:195], v[222:225], v[64:67]
	s_ashr_i32 s39, s38, 31
	s_lshl_b64 s[38:39], s[38:39], 13
	s_add_u32 s3, s61, s38
	s_addc_u32 s18, s68, s39
	s_add_u32 s38, s3, s4
	s_addc_u32 s39, s18, s5
	s_mov_b32 m0, s10
	v_lshl_add_u64 v[142:143], s[38:39], 0, v[128:129]
	s_barrier
	ds_read_b128 v[160:163], v144 offset:16384
	ds_read_b128 v[168:171], v144 offset:17408
	ds_read_b128 v[172:175], v148 offset:16384
	ds_read_b128 v[176:179], v148 offset:17408
	ds_read_b128 v[180:183], v149 offset:16384
	ds_read_b128 v[184:187], v149 offset:17408
	ds_read_b128 v[188:191], v150 offset:16384
	ds_read_b128 v[192:195], v150 offset:17408
	global_load_lds_dwordx4 v[142:143], off
	v_lshl_add_u64 v[142:143], v[142:143], 0, s[44:45]
	s_mov_b32 m0, s13
	s_nop 0
	global_load_lds_dwordx4 v[142:143], off
	s_barrier
	s_waitcnt lgkmcnt(0)
	s_waitcnt lgkmcnt(0)
	v_mfma_f32_16x16x32_bf16 v[60:63], v[160:163], v[134:137], v[60:63]
	v_mfma_f32_16x16x32_bf16 v[56:59], v[160:163], v[152:155], v[56:59]
	v_mfma_f32_16x16x32_bf16 v[52:55], v[172:175], v[134:137], v[52:55]
	v_mfma_f32_16x16x32_bf16 v[48:51], v[172:175], v[152:155], v[48:51]
	v_mfma_f32_16x16x32_bf16 v[44:47], v[180:183], v[134:137], v[44:47]
	v_mfma_f32_16x16x32_bf16 v[40:43], v[180:183], v[152:155], v[40:43]
	v_mfma_f32_16x16x32_bf16 v[36:39], v[188:191], v[134:137], v[36:39]
	v_mfma_f32_16x16x32_bf16 v[32:35], v[188:191], v[152:155], v[32:35]
	v_mfma_f32_16x16x32_bf16 v[60:63], v[168:171], v[138:141], v[60:63]
	v_mfma_f32_16x16x32_bf16 v[56:59], v[168:171], v[156:159], v[56:59]
	v_mfma_f32_16x16x32_bf16 v[52:55], v[176:179], v[138:141], v[52:55]
	v_mfma_f32_16x16x32_bf16 v[48:51], v[176:179], v[156:159], v[48:51]
	v_mfma_f32_16x16x32_bf16 v[44:47], v[184:187], v[138:141], v[44:47]
	v_mfma_f32_16x16x32_bf16 v[40:43], v[184:187], v[156:159], v[40:43]
	v_mfma_f32_16x16x32_bf16 v[36:39], v[192:195], v[138:141], v[36:39]
	v_mfma_f32_16x16x32_bf16 v[32:35], v[192:195], v[156:159], v[32:35]
	s_barrier
; #define STAGE(P_, BASE, br, kt) do { const u16* _gb = (BASE) + (long)(br) * K + (long)(kt) * BK; \
;     _Pragma("unroll") for (int _i = 0; _i < 2; ++_i) { \
;       __builtin_amdgcn_global_load_lds((const unsigned*)(_gb + (long)_i * 64 * K + lane_off), \
;         (unsigned*)((char*)(P_) + lds_wbase + _i * 8192), 16, 0, 0); } } while (0)
; #define LDA(dst, b, h) _Pragma("unroll") for (int m = 0; m < 4; ++m) _Pragma("unroll") for (int k = 0; k < 2; ++k) \
;     dst[m][k] = *reinterpret_cast<const bf16x8*>((char*)SA(b, h) + lds_byte(wr * 64 + m * 16 + fr, k * 32 + fq * 8))
; #define LDB(dst, b, h) _Pragma("unroll") for (int n = 0; n < 2; ++n) _Pragma("unroll") for (int k = 0; k < 2; ++k) \
;     dst[n][k] = *reinterpret_cast<const bf16x8*>((char*)SB(b, h) + lds_byte(wc * 32 + n * 16 + fr, k * 32 + fq * 8))
; #define MMA(ai, bj, At_, Bt_) do { __builtin_amdgcn_s_setprio(1); \
;     _Pragma("unroll") for (int m = 0; m < 4; ++m) _Pragma("unroll") for (int n = 0; n < 2; ++n) _Pragma("unroll") for (int k = 0; k < 2; ++k) \
;       acc[ai][bj][m][n] = __builtin_amdgcn_mfma_f32_16x16x32_bf16(At_[m][k], Bt_[n][k], acc[ai][bj][m][n], 0, 0, 0); \
;     __builtin_amdgcn_s_setprio(0); } while (0)
; #define WAIT_V(n) asm volatile("s_waitcnt vmcnt(" #n ")" ::: "memory")
; #define BAR __builtin_amdgcn_s_barrier()
; template <int PRE> ...
;     ...
;   for (int t = 0; t < nt; t += 2) {
;     LDB(B0, 0, 0); SCHED; LDA(At, 0, 0); STAGE(SA(1, 1), A, brow + HALF, t + 1);
;     WAIT_L(8); BAR; WAIT_L(0); MMA(0, 0, At, B0); BAR; SCHED;
;     LDB(B1, 0, 1); STAGEW(SB(0, 0), Bt, bcol, bcol_n, t + 2);
;     BAR; WAIT_L(0); MMA(0, 1, At, B1); BAR;
;     LDA(At, 0, 1); STAGEW(SA(0, 0), A, brow, brow_n, t + 2);
;     BAR; WAIT_L(0); MMA(1, 0, At, B0); BAR; SCHED;
;     STAGEW(SB(0, 1), Bt, bcol + HALF, bcol_n + HALF, t + 2);
;     WAIT_V(6); BAR; MMA(1, 1, At, B1); BAR;
;     LDB(B0, 1, 0); SCHED; LDA(At, 1, 0); STAGEW(SA(0, 1), A, brow + HALF, brow_n + HALF, t + 2);
;     WAIT_L(8); BAR; WAIT_L(0); MMA(0, 0, At, B0); BAR; SCHED;
;     LDB(B1, 1, 1); STAGEW(SB(1, 0), Bt, bcol, bcol_n, t + 3);
;     BAR; WAIT_L(0); MMA(0, 1, At, B1); BAR;
;     LDA(At, 1, 1); STAGEW(SA(1, 0), A, brow, brow_n, t + 3);
;     BAR; WAIT_L(0); MMA(1, 0, At, B0); BAR; SCHED;
;     STAGEW(SB(1, 1), Bt, bcol + HALF, bcol_n + HALF, t + 3);
;     WAIT_V(6); BAR; MMA(1, 1, At, B1); BAR;
;   }
	s_ashr_i32 s41, s40, 31
	s_lshl_b64 s[38:39], s[40:41], 13
	s_add_u32 s3, s66, s38
	s_addc_u32 s18, s67, s39
	s_add_u32 s38, s3, s4
	s_addc_u32 s39, s18, s5
	s_mov_b32 m0, s14
	v_lshl_add_u64 v[134:135], s[38:39], 0, v[128:129]
	global_load_lds_dwordx4 v[134:135], off
	v_lshl_add_u64 v[134:135], v[134:135], 0, s[44:45]
	s_mov_b32 m0, s15
	s_nop 0
	global_load_lds_dwordx4 v[134:135], off
	s_waitcnt vmcnt(6)
	s_barrier
	v_mfma_f32_16x16x32_bf16 v[28:31], v[160:163], v[210:213], v[28:31]
	v_mfma_f32_16x16x32_bf16 v[24:27], v[160:163], v[218:221], v[24:27]
	v_mfma_f32_16x16x32_bf16 v[20:23], v[172:175], v[210:213], v[20:23]
	v_mfma_f32_16x16x32_bf16 v[16:19], v[172:175], v[218:221], v[16:19]
	v_mfma_f32_16x16x32_bf16 v[12:15], v[180:183], v[210:213], v[12:15]
	v_mfma_f32_16x16x32_bf16 v[8:11], v[180:183], v[218:221], v[8:11]
	v_mfma_f32_16x16x32_bf16 v[4:7], v[188:191], v[210:213], v[4:7]
	v_mfma_f32_16x16x32_bf16 v[0:3], v[188:191], v[218:221], v[0:3]
	v_mfma_f32_16x16x32_bf16 v[28:31], v[168:171], v[214:217], v[28:31]
	v_mfma_f32_16x16x32_bf16 v[24:27], v[168:171], v[222:225], v[24:27]
	v_mfma_f32_16x16x32_bf16 v[20:23], v[176:179], v[214:217], v[20:23]
	v_mfma_f32_16x16x32_bf16 v[16:19], v[176:179], v[222:225], v[16:19]
	v_mfma_f32_16x16x32_bf16 v[12:15], v[184:187], v[214:217], v[12:15]
	v_mfma_f32_16x16x32_bf16 v[8:11], v[184:187], v[222:225], v[8:11]
	v_mfma_f32_16x16x32_bf16 v[4:7], v[192:195], v[214:217], v[4:7]
	v_mfma_f32_16x16x32_bf16 v[0:3], v[192:195], v[222:225], v[0:3]
	v_add_u32_e32 v142, s83, v147
	s_barrier
	ds_read_b128 v[134:137], v142
	ds_read_b128 v[138:141], v142 offset:1024
	ds_read_b128 v[152:155], v142 offset:2048
	ds_read_b128 v[156:159], v142 offset:3072
	s_ashr_i32 s3, s2, 31
	s_lshl_b64 s[2:3], s[2:3], 13
	s_add_u32 s2, s61, s2
	s_addc_u32 s3, s68, s3
	s_add_u32 s2, s2, s4
	s_addc_u32 s3, s3, s5
	s_mov_b32 m0, s16
	v_lshl_add_u64 v[142:143], s[2:3], 0, v[128:129]
	ds_read_b128 v[160:163], v144 offset:32768
	ds_read_b128 v[168:171], v144 offset:33792
	ds_read_b128 v[172:175], v148 offset:32768
	ds_read_b128 v[176:179], v148 offset:33792
	ds_read_b128 v[180:183], v149 offset:32768
	ds_read_b128 v[184:187], v149 offset:33792
	ds_read_b128 v[188:191], v150 offset:32768
	ds_read_b128 v[192:195], v150 offset:33792
	global_load_lds_dwordx4 v[142:143], off
	v_lshl_add_u64 v[142:143], v[142:143], 0, s[44:45]
	s_mov_b32 m0, s17
	s_nop 0
	global_load_lds_dwordx4 v[142:143], off
	s_waitcnt lgkmcnt(8)
	s_barrier
	s_waitcnt lgkmcnt(0)
	s_waitcnt lgkmcnt(0)
	v_mfma_f32_16x16x32_bf16 v[124:127], v[160:163], v[134:137], v[124:127]
	v_mfma_f32_16x16x32_bf16 v[120:123], v[160:163], v[152:155], v[120:123]
	v_mfma_f32_16x16x32_bf16 v[116:119], v[172:175], v[134:137], v[116:119]
	v_mfma_f32_16x16x32_bf16 v[112:115], v[172:175], v[152:155], v[112:115]
	v_mfma_f32_16x16x32_bf16 v[108:111], v[180:183], v[134:137], v[108:111]
	v_mfma_f32_16x16x32_bf16 v[104:107], v[180:183], v[152:155], v[104:107]
	v_mfma_f32_16x16x32_bf16 v[100:103], v[188:191], v[134:137], v[100:103]
	v_mfma_f32_16x16x32_bf16 v[96:99], v[188:191], v[152:155], v[96:99]
	v_mfma_f32_16x16x32_bf16 v[124:127], v[168:171], v[138:141], v[124:127]
	v_mfma_f32_16x16x32_bf16 v[120:123], v[168:171], v[156:159], v[120:123]
	v_mfma_f32_16x16x32_bf16 v[116:119], v[176:179], v[138:141], v[116:119]
	v_mfma_f32_16x16x32_bf16 v[112:115], v[176:179], v[156:159], v[112:115]
	v_mfma_f32_16x16x32_bf16 v[108:111], v[184:187], v[138:141], v[108:111]
	v_mfma_f32_16x16x32_bf16 v[104:107], v[184:187], v[156:159], v[104:107]
	v_mfma_f32_16x16x32_bf16 v[100:103], v[192:195], v[138:141], v[100:103]
	v_mfma_f32_16x16x32_bf16 v[96:99], v[192:195], v[156:159], v[96:99]
	s_barrier
	s_cmp_lt_u32 s1, 61
	s_cselect_b32 s2, s27, s29
	s_cselect_b32 s5, 0, 0xffffffc0
	s_cselect_b32 s4, s0, s28
	s_cselect_b32 s38, s34, s31
	s_ashr_i32 s3, s2, 31
	s_lshl_b64 s[2:3], s[2:3], 13
	s_add_u32 s37, s66, s2
	s_addc_u32 s39, s67, s3
	s_add_i32 s1, s5, s1
	s_add_i32 s18, s1, 3
	s_lshl_b64 s[2:3], s[18:19], 7
	s_add_u32 s40, s37, s2
	v_add_u32_e32 v142, s84, v147
	s_addc_u32 s41, s39, s3
	s_mov_b32 m0, s20
	ds_read_b128 v[210:213], v142
	ds_read_b128 v[214:217], v142 offset:1024
	ds_read_b128 v[218:221], v142 offset:2048
	ds_read_b128 v[222:225], v142 offset:3072
	v_lshl_add_u64 v[142:143], s[40:41], 0, v[128:129]
	global_load_lds_dwordx4 v[142:143], off
	v_lshl_add_u64 v[142:143], v[142:143], 0, s[44:45]
	s_mov_b32 m0, s21
	s_nop 0
	global_load_lds_dwordx4 v[142:143], off
	s_barrier
; #define LDA(dst, b, h) _Pragma("unroll") for (int m = 0; m < 4; ++m) _Pragma("unroll") for (int k = 0; k < 2; ++k) \
;     dst[m][k] = *reinterpret_cast<const bf16x8*>((char*)SA(b, h) + lds_byte(wr * 64 + m * 16 + fr, k * 32 + fq * 8))
; #define LDB(dst, b, h) _Pragma("unroll") for (int n = 0; n < 2; ++n) _Pragma("unroll") for (int k = 0; k < 2; ++k) \
;     dst[n][k] = *reinterpret_cast<const bf16x8*>((char*)SB(b, h) + lds_byte(wc * 32 + n * 16 + fr, k * 32 + fq * 8))
; #define MMA(ai, bj, At_, Bt_) do { __builtin_amdgcn_s_setprio(1); \
;     _Pragma("unroll") for (int m = 0; m < 4; ++m) _Pragma("unroll") for (int n = 0; n < 2; ++n) _Pragma("unroll") for (int k = 0; k < 2; ++k) \
;       acc[ai][bj][m][n] = __builtin_amdgcn_mfma_f32_16x16x32_bf16(At_[m][k], Bt_[n][k], acc[ai][bj][m][n], 0, 0, 0); \
;     __builtin_amdgcn_s_setprio(0); } while (0)
; #define WAIT_V(n) asm volatile("s_waitcnt vmcnt(" #n ")" ::: "memory")
; #define WAIT_L(n) asm volatile("s_waitcnt lgkmcnt(" #n ")" ::: "memory")
; #define BAR __builtin_amdgcn_s_barrier()
; #define SCHED __builtin_amdgcn_sched_barrier(0)
; #define STAGEW(P_, BASE, cur, nxt, kt_) do { const bool _wr = (kt_) >= nt; \
;     STAGE(P_, BASE, (_wr ? (nxt) : (cur)), (_wr ? (kt_) - nt : (kt_))); } while (0)
; template <int PRE> ...
;     ...
;     LDB(B0, 1, 0); SCHED; LDA(At, 1, 0); STAGEW(SA(0, 1), A, brow + HALF, brow_n + HALF, t + 2);
;     WAIT_L(8); BAR; WAIT_L(0); MMA(0, 0, At, B0); BAR; SCHED;
;     LDB(B1, 1, 1); STAGEW(SB(1, 0), Bt, bcol, bcol_n, t + 3);
;     BAR; WAIT_L(0); MMA(0, 1, At, B1); BAR;
;     LDA(At, 1, 1); STAGEW(SA(1, 0), A, brow, brow_n, t + 3);
;     BAR; WAIT_L(0); MMA(1, 0, At, B0); BAR; SCHED;
;     STAGEW(SB(1, 1), Bt, bcol + HALF, bcol_n + HALF, t + 3);
;     WAIT_V(6); BAR; MMA(1, 1, At, B1); BAR;
;   }
;   if (wr == 0) BAR;
	s_waitcnt lgkmcnt(0)
	s_waitcnt lgkmcnt(0)
	v_mfma_f32_16x16x32_bf16 v[92:95], v[160:163], v[210:213], v[92:95]
	v_mfma_f32_16x16x32_bf16 v[88:91], v[160:163], v[218:221], v[88:91]
	v_mfma_f32_16x16x32_bf16 v[84:87], v[172:175], v[210:213], v[84:87]
	v_mfma_f32_16x16x32_bf16 v[80:83], v[172:175], v[218:221], v[80:83]
	v_mfma_f32_16x16x32_bf16 v[76:79], v[180:183], v[210:213], v[76:79]
	v_mfma_f32_16x16x32_bf16 v[72:75], v[180:183], v[218:221], v[72:75]
	v_mfma_f32_16x16x32_bf16 v[68:71], v[188:191], v[210:213], v[68:71]
	v_mfma_f32_16x16x32_bf16 v[64:67], v[188:191], v[218:221], v[64:67]
	v_mfma_f32_16x16x32_bf16 v[92:95], v[168:171], v[214:217], v[92:95]
	v_mfma_f32_16x16x32_bf16 v[88:91], v[168:171], v[222:225], v[88:91]
	v_mfma_f32_16x16x32_bf16 v[84:87], v[176:179], v[214:217], v[84:87]
	v_mfma_f32_16x16x32_bf16 v[80:83], v[176:179], v[222:225], v[80:83]
	v_mfma_f32_16x16x32_bf16 v[76:79], v[184:187], v[214:217], v[76:79]
	v_mfma_f32_16x16x32_bf16 v[72:75], v[184:187], v[222:225], v[72:75]
	v_mfma_f32_16x16x32_bf16 v[68:71], v[192:195], v[214:217], v[68:71]
	v_mfma_f32_16x16x32_bf16 v[64:67], v[192:195], v[222:225], v[64:67]
	s_ashr_i32 s5, s4, 31
	s_lshl_b64 s[4:5], s[4:5], 13
	s_add_u32 s1, s61, s4
	s_addc_u32 s5, s68, s5
	s_add_u32 s4, s1, s2
	s_addc_u32 s5, s5, s3
	s_mov_b32 m0, s22
	v_lshl_add_u64 v[142:143], s[4:5], 0, v[128:129]
	s_barrier
	ds_read_b128 v[160:163], v144 offset:49152
	ds_read_b128 v[168:171], v144 offset:50176
	ds_read_b128 v[172:175], v148 offset:49152
	ds_read_b128 v[176:179], v148 offset:50176
	ds_read_b128 v[180:183], v149 offset:49152
	ds_read_b128 v[184:187], v149 offset:50176
	ds_read_b128 v[188:191], v150 offset:49152
	ds_read_b128 v[192:195], v150 offset:50176
	global_load_lds_dwordx4 v[142:143], off
	v_lshl_add_u64 v[142:143], v[142:143], 0, s[44:45]
	s_mov_b32 m0, s23
	s_nop 0
	global_load_lds_dwordx4 v[142:143], off
	s_barrier
	s_waitcnt lgkmcnt(0)
	s_waitcnt lgkmcnt(0)
	v_mfma_f32_16x16x32_bf16 v[60:63], v[160:163], v[134:137], v[60:63]
	v_mfma_f32_16x16x32_bf16 v[56:59], v[160:163], v[152:155], v[56:59]
	v_mfma_f32_16x16x32_bf16 v[52:55], v[172:175], v[134:137], v[52:55]
	v_mfma_f32_16x16x32_bf16 v[48:51], v[172:175], v[152:155], v[48:51]
	v_mfma_f32_16x16x32_bf16 v[44:47], v[180:183], v[134:137], v[44:47]
	v_mfma_f32_16x16x32_bf16 v[40:43], v[180:183], v[152:155], v[40:43]
	v_mfma_f32_16x16x32_bf16 v[36:39], v[188:191], v[134:137], v[36:39]
	v_mfma_f32_16x16x32_bf16 v[32:35], v[188:191], v[152:155], v[32:35]
	v_mfma_f32_16x16x32_bf16 v[60:63], v[168:171], v[138:141], v[60:63]
	v_mfma_f32_16x16x32_bf16 v[56:59], v[168:171], v[156:159], v[56:59]
	v_mfma_f32_16x16x32_bf16 v[52:55], v[176:179], v[138:141], v[52:55]
	v_mfma_f32_16x16x32_bf16 v[48:51], v[176:179], v[156:159], v[48:51]
	v_mfma_f32_16x16x32_bf16 v[44:47], v[184:187], v[138:141], v[44:47]
	v_mfma_f32_16x16x32_bf16 v[40:43], v[184:187], v[156:159], v[40:43]
	v_mfma_f32_16x16x32_bf16 v[36:39], v[192:195], v[138:141], v[36:39]
	v_mfma_f32_16x16x32_bf16 v[32:35], v[192:195], v[156:159], v[32:35]
	s_barrier
	s_ashr_i32 s39, s38, 31
	s_lshl_b64 s[4:5], s[38:39], 13
	s_add_u32 s1, s66, s4
	s_addc_u32 s4, s67, s5
	s_add_u32 s2, s1, s2
	s_addc_u32 s3, s4, s3
	s_mov_b32 m0, s24
	v_lshl_add_u64 v[134:135], s[2:3], 0, v[128:129]
	global_load_lds_dwordx4 v[134:135], off
	v_lshl_add_u64 v[134:135], v[134:135], 0, s[44:45]
	s_mov_b32 m0, s25
	s_nop 0
	global_load_lds_dwordx4 v[134:135], off
	s_waitcnt vmcnt(6)
	s_barrier
	v_mfma_f32_16x16x32_bf16 v[28:31], v[160:163], v[210:213], v[28:31]
	v_mfma_f32_16x16x32_bf16 v[24:27], v[160:163], v[218:221], v[24:27]
	v_mfma_f32_16x16x32_bf16 v[20:23], v[172:175], v[210:213], v[20:23]
	v_mfma_f32_16x16x32_bf16 v[16:19], v[172:175], v[218:221], v[16:19]
	v_mfma_f32_16x16x32_bf16 v[12:15], v[180:183], v[210:213], v[12:15]
	v_mfma_f32_16x16x32_bf16 v[8:11], v[180:183], v[218:221], v[8:11]
	v_mfma_f32_16x16x32_bf16 v[4:7], v[188:191], v[210:213], v[4:7]
	v_mfma_f32_16x16x32_bf16 v[0:3], v[188:191], v[218:221], v[0:3]
	v_mfma_f32_16x16x32_bf16 v[28:31], v[168:171], v[214:217], v[28:31]
	v_mfma_f32_16x16x32_bf16 v[24:27], v[168:171], v[222:225], v[24:27]
	v_mfma_f32_16x16x32_bf16 v[20:23], v[176:179], v[214:217], v[20:23]
	v_mfma_f32_16x16x32_bf16 v[16:19], v[176:179], v[222:225], v[16:19]
	v_mfma_f32_16x16x32_bf16 v[12:15], v[184:187], v[214:217], v[12:15]
	v_mfma_f32_16x16x32_bf16 v[8:11], v[184:187], v[222:225], v[8:11]
	v_mfma_f32_16x16x32_bf16 v[4:7], v[192:195], v[214:217], v[4:7]
	v_mfma_f32_16x16x32_bf16 v[0:3], v[192:195], v[222:225], v[0:3]
	v_lshl_add_u64 v[132:133], v[132:133], 0, s[46:47]
	s_mov_b32 s1, s36
	s_barrier
	s_cbranch_vccnz .LBB0_810
	v_readlane_b32 s34, v243, 2
	s_andn2_b64 vcc, exec, s[58:59]
	v_readlane_b32 s31, v244, 61
	v_readlane_b32 s35, v243, 3
	s_cbranch_vccnz .LBB0_813
	s_barrier

; #define STAGE(P_, BASE, br, kt) do { const u16* _gb = (BASE) + (long)(br) * K + (long)(kt) * BK; \
;     _Pragma("unroll") for (int _i = 0; _i < 2; ++_i) { \
;       __builtin_amdgcn_global_load_lds((const unsigned*)(_gb + (long)_i * 64 * K + lane_off), \
;         (unsigned*)((char*)(P_) + lds_wbase + _i * 8192), 16, 0, 0); } } while (0)
; #define LDA(dst, b, h) _Pragma("unroll") for (int m = 0; m < 4; ++m) _Pragma("unroll") for (int k = 0; k < 2; ++k) \
;     dst[m][k] = *reinterpret_cast<const bf16x8*>((char*)SA(b, h) + lds_byte(wr * 64 + m * 16 + fr, k * 32 + fq * 8))
; #define LDB(dst, b, h) _Pragma("unroll") for (int n = 0; n < 2; ++n) _Pragma("unroll") for (int k = 0; k < 2; ++k) \
;     dst[n][k] = *reinterpret_cast<const bf16x8*>((char*)SB(b, h) + lds_byte(wc * 32 + n * 16 + fr, k * 32 + fq * 8))
; #define MMA(ai, bj, At_, Bt_) do { __builtin_amdgcn_s_setprio(1); \
;     _Pragma("unroll") for (int m = 0; m < 4; ++m) _Pragma("unroll") for (int n = 0; n < 2; ++n) _Pragma("unroll") for (int k = 0; k < 2; ++k) \
;       acc[ai][bj][m][n] = __builtin_amdgcn_mfma_f32_16x16x32_bf16(At_[m][k], Bt_[n][k], acc[ai][bj][m][n], 0, 0, 0); \
;     __builtin_amdgcn_s_setprio(0); } while (0)
; #define WAIT_V(n) asm volatile("s_waitcnt vmcnt(" #n ")" ::: "memory")
; #define WAIT_L(n) asm volatile("s_waitcnt lgkmcnt(" #n ")" ::: "memory")
; #define BAR __builtin_amdgcn_s_barrier()
; #define SCHED __builtin_amdgcn_sched_barrier(0)
; #define STAGEW(P_, BASE, cur, nxt, kt_) do { const bool _wr = (kt_) >= nt; \
;     STAGE(P_, BASE, (_wr ? (nxt) : (cur)), (_wr ? (kt_) - nt : (kt_))); } while (0)
; template <int PRE> ...
;     ...
;   for (int t = 0; t < nt; t += 2) {
;     LDB(B0, 0, 0); SCHED; LDA(At, 0, 0); STAGE(SA(1, 1), A, brow + HALF, t + 1);
;     WAIT_L(8); BAR; WAIT_L(0); MMA(0, 0, At, B0); BAR; SCHED;
;     LDB(B1, 0, 1); STAGEW(SB(0, 0), Bt, bcol, bcol_n, t + 2);
;     BAR; WAIT_L(0); MMA(0, 1, At, B1); BAR;
;     LDA(At, 0, 1); STAGEW(SA(0, 0), A, brow, brow_n, t + 2);
;     BAR; WAIT_L(0); MMA(1, 0, At, B0); BAR; SCHED;
;     STAGEW(SB(0, 1), Bt, bcol + HALF, bcol_n + HALF, t + 2);
;     WAIT_V(6); BAR; MMA(1, 1, At, B1); BAR;
.LBB0_825:
	v_add_u32_e32 v142, s81, v159
	ds_read_b128 v[134:137], v142
	ds_read_b128 v[138:141], v142 offset:1024
	ds_read_b128 v[146:149], v142 offset:2048
	ds_read_b128 v[150:153], v142 offset:3072
	s_add_i32 m0, s10, 0xc000
	ds_read_b128 v[154:157], v144
	ds_read_b128 v[168:171], v144 offset:1024
	ds_read_b128 v[172:175], v160
	ds_read_b128 v[176:179], v160 offset:1024
	ds_read_b128 v[180:183], v161
	ds_read_b128 v[184:187], v161 offset:1024
	ds_read_b128 v[188:191], v162
	ds_read_b128 v[192:195], v162 offset:1024
	global_load_lds_dwordx4 v[128:129], off
	v_lshl_add_u64 v[142:143], v[128:129], 0, s[86:87]
	s_add_i32 m0, s10, 0xe000
	s_nop 0
	global_load_lds_dwordx4 v[142:143], off
	s_waitcnt lgkmcnt(8)
	s_barrier
	s_waitcnt lgkmcnt(0)
	s_waitcnt lgkmcnt(0)
	v_mfma_f32_16x16x32_bf16 v[124:127], v[154:157], v[134:137], v[124:127]
	v_mfma_f32_16x16x32_bf16 v[120:123], v[154:157], v[146:149], v[120:123]
	v_mfma_f32_16x16x32_bf16 v[116:119], v[172:175], v[134:137], v[116:119]
	v_mfma_f32_16x16x32_bf16 v[112:115], v[172:175], v[146:149], v[112:115]
	v_mfma_f32_16x16x32_bf16 v[108:111], v[180:183], v[134:137], v[108:111]
	v_mfma_f32_16x16x32_bf16 v[104:107], v[180:183], v[146:149], v[104:107]
	v_mfma_f32_16x16x32_bf16 v[100:103], v[188:191], v[134:137], v[100:103]
	v_mfma_f32_16x16x32_bf16 v[96:99], v[188:191], v[146:149], v[96:99]
	v_mfma_f32_16x16x32_bf16 v[124:127], v[168:171], v[138:141], v[124:127]
	v_mfma_f32_16x16x32_bf16 v[120:123], v[168:171], v[150:153], v[120:123]
	v_mfma_f32_16x16x32_bf16 v[116:119], v[176:179], v[138:141], v[116:119]
	v_mfma_f32_16x16x32_bf16 v[112:115], v[176:179], v[150:153], v[112:115]
	v_mfma_f32_16x16x32_bf16 v[108:111], v[184:187], v[138:141], v[108:111]
	v_mfma_f32_16x16x32_bf16 v[104:107], v[184:187], v[150:153], v[104:107]
	v_mfma_f32_16x16x32_bf16 v[100:103], v[192:195], v[138:141], v[100:103]
	v_mfma_f32_16x16x32_bf16 v[96:99], v[192:195], v[150:153], v[96:99]
	s_barrier
	s_add_i32 s36, s1, 2
	s_cmp_lt_u32 s1, 30
	s_cselect_b64 s[2:3], -1, 0
	s_and_b64 vcc, s[2:3], exec
	s_cselect_b32 s4, s27, s29
	s_cselect_b32 s3, 0, 0xffffffe0
	s_cselect_b32 s38, s0, s28
	s_cselect_b32 s40, s34, s31
	s_cselect_b32 s2, s30, s35
	s_ashr_i32 s5, s4, 31
	s_lshl_b64 s[4:5], s[4:5], 12
	s_add_u32 s37, s62, s4
	s_addc_u32 s39, s63, s5
	s_add_i32 s18, s36, s3
	s_lshl_b64 s[4:5], s[18:19], 7
	s_add_u32 s42, s37, s4
	v_add_u32_e32 v142, s82, v159
	s_addc_u32 s43, s39, s5
	s_mov_b32 m0, s11
	ds_read_b128 v[210:213], v142
	ds_read_b128 v[214:217], v142 offset:1024
	ds_read_b128 v[218:221], v142 offset:2048
	ds_read_b128 v[222:225], v142 offset:3072
	v_lshl_add_u64 v[142:143], s[42:43], 0, v[130:131]
	global_load_lds_dwordx4 v[142:143], off
	v_lshl_add_u64 v[142:143], v[142:143], 0, s[86:87]
	s_mov_b32 m0, s12
	s_nop 0
	global_load_lds_dwordx4 v[142:143], off
	s_barrier
	s_waitcnt lgkmcnt(0)
	s_waitcnt lgkmcnt(0)
	v_mfma_f32_16x16x32_bf16 v[92:95], v[154:157], v[210:213], v[92:95]
	v_mfma_f32_16x16x32_bf16 v[88:91], v[154:157], v[218:221], v[88:91]
	v_mfma_f32_16x16x32_bf16 v[84:87], v[172:175], v[210:213], v[84:87]
	v_mfma_f32_16x16x32_bf16 v[80:83], v[172:175], v[218:221], v[80:83]
	v_mfma_f32_16x16x32_bf16 v[76:79], v[180:183], v[210:213], v[76:79]
	v_mfma_f32_16x16x32_bf16 v[72:75], v[180:183], v[218:221], v[72:75]
	v_mfma_f32_16x16x32_bf16 v[68:71], v[188:191], v[210:213], v[68:71]
	v_mfma_f32_16x16x32_bf16 v[64:67], v[188:191], v[218:221], v[64:67]
	v_mfma_f32_16x16x32_bf16 v[92:95], v[168:171], v[214:217], v[92:95]
	v_mfma_f32_16x16x32_bf16 v[88:91], v[168:171], v[222:225], v[88:91]
	v_mfma_f32_16x16x32_bf16 v[84:87], v[176:179], v[214:217], v[84:87]
	v_mfma_f32_16x16x32_bf16 v[80:83], v[176:179], v[222:225], v[80:83]
	v_mfma_f32_16x16x32_bf16 v[76:79], v[184:187], v[214:217], v[76:79]
	v_mfma_f32_16x16x32_bf16 v[72:75], v[184:187], v[222:225], v[72:75]
	v_mfma_f32_16x16x32_bf16 v[68:71], v[192:195], v[214:217], v[68:71]
	v_mfma_f32_16x16x32_bf16 v[64:67], v[192:195], v[222:225], v[64:67]
	s_ashr_i32 s39, s38, 31
	s_lshl_b64 s[38:39], s[38:39], 12
	s_add_u32 s3, s69, s38
	s_addc_u32 s18, s70, s39
	s_add_u32 s38, s3, s4
	s_addc_u32 s39, s18, s5
	s_mov_b32 m0, s10
	v_lshl_add_u64 v[142:143], s[38:39], 0, v[130:131]
	s_barrier
	ds_read_b128 v[154:157], v144 offset:16384
	ds_read_b128 v[168:171], v144 offset:17408
	ds_read_b128 v[172:175], v160 offset:16384
	ds_read_b128 v[176:179], v160 offset:17408
	ds_read_b128 v[180:183], v161 offset:16384
	ds_read_b128 v[184:187], v161 offset:17408
	ds_read_b128 v[188:191], v162 offset:16384
	ds_read_b128 v[192:195], v162 offset:17408
	global_load_lds_dwordx4 v[142:143], off
	v_lshl_add_u64 v[142:143], v[142:143], 0, s[86:87]
	s_mov_b32 m0, s13
	s_nop 0
	global_load_lds_dwordx4 v[142:143], off
	s_barrier
	s_waitcnt lgkmcnt(0)
	s_waitcnt lgkmcnt(0)
	v_mfma_f32_16x16x32_bf16 v[60:63], v[154:157], v[134:137], v[60:63]
	v_mfma_f32_16x16x32_bf16 v[56:59], v[154:157], v[146:149], v[56:59]
	v_mfma_f32_16x16x32_bf16 v[52:55], v[172:175], v[134:137], v[52:55]
	v_mfma_f32_16x16x32_bf16 v[48:51], v[172:175], v[146:149], v[48:51]
	v_mfma_f32_16x16x32_bf16 v[44:47], v[180:183], v[134:137], v[44:47]
	v_mfma_f32_16x16x32_bf16 v[40:43], v[180:183], v[146:149], v[40:43]
	v_mfma_f32_16x16x32_bf16 v[36:39], v[188:191], v[134:137], v[36:39]
	v_mfma_f32_16x16x32_bf16 v[32:35], v[188:191], v[146:149], v[32:35]
	v_mfma_f32_16x16x32_bf16 v[60:63], v[168:171], v[138:141], v[60:63]
	v_mfma_f32_16x16x32_bf16 v[56:59], v[168:171], v[150:153], v[56:59]
	v_mfma_f32_16x16x32_bf16 v[52:55], v[176:179], v[138:141], v[52:55]
	v_mfma_f32_16x16x32_bf16 v[48:51], v[176:179], v[150:153], v[48:51]
	v_mfma_f32_16x16x32_bf16 v[44:47], v[184:187], v[138:141], v[44:47]
	v_mfma_f32_16x16x32_bf16 v[40:43], v[184:187], v[150:153], v[40:43]
	v_mfma_f32_16x16x32_bf16 v[36:39], v[192:195], v[138:141], v[36:39]
	v_mfma_f32_16x16x32_bf16 v[32:35], v[192:195], v[150:153], v[32:35]
	s_barrier
; #define LDA(dst, b, h) _Pragma("unroll") for (int m = 0; m < 4; ++m) _Pragma("unroll") for (int k = 0; k < 2; ++k) \
;     dst[m][k] = *reinterpret_cast<const bf16x8*>((char*)SA(b, h) + lds_byte(wr * 64 + m * 16 + fr, k * 32 + fq * 8))
; #define LDB(dst, b, h) _Pragma("unroll") for (int n = 0; n < 2; ++n) _Pragma("unroll") for (int k = 0; k < 2; ++k) \
;     dst[n][k] = *reinterpret_cast<const bf16x8*>((char*)SB(b, h) + lds_byte(wc * 32 + n * 16 + fr, k * 32 + fq * 8))
; #define MMA(ai, bj, At_, Bt_) do { __builtin_amdgcn_s_setprio(1); \
;     _Pragma("unroll") for (int m = 0; m < 4; ++m) _Pragma("unroll") for (int n = 0; n < 2; ++n) _Pragma("unroll") for (int k = 0; k < 2; ++k) \
;       acc[ai][bj][m][n] = __builtin_amdgcn_mfma_f32_16x16x32_bf16(At_[m][k], Bt_[n][k], acc[ai][bj][m][n], 0, 0, 0); \
;     __builtin_amdgcn_s_setprio(0); } while (0)
; #define WAIT_V(n) asm volatile("s_waitcnt vmcnt(" #n ")" ::: "memory")
; #define WAIT_L(n) asm volatile("s_waitcnt lgkmcnt(" #n ")" ::: "memory")
; #define BAR __builtin_amdgcn_s_barrier()
; #define SCHED __builtin_amdgcn_sched_barrier(0)
; #define STAGEW(P_, BASE, cur, nxt, kt_) do { const bool _wr = (kt_) >= nt; \
;     STAGE(P_, BASE, (_wr ? (nxt) : (cur)), (_wr ? (kt_) - nt : (kt_))); } while (0)
; template <int PRE> ...
;     ...
;     STAGEW(SB(0, 1), Bt, bcol + HALF, bcol_n + HALF, t + 2);
;     WAIT_V(6); BAR; MMA(1, 1, At, B1); BAR;
;     LDB(B0, 1, 0); SCHED; LDA(At, 1, 0); STAGEW(SA(0, 1), A, brow + HALF, brow_n + HALF, t + 2);
;     WAIT_L(8); BAR; WAIT_L(0); MMA(0, 0, At, B0); BAR; SCHED;
;     LDB(B1, 1, 1); STAGEW(SB(1, 0), Bt, bcol, bcol_n, t + 3);
;     BAR; WAIT_L(0); MMA(0, 1, At, B1); BAR;
;     LDA(At, 1, 1); STAGEW(SA(1, 0), A, brow, brow_n, t + 3);
;     BAR; WAIT_L(0); MMA(1, 0, At, B0); BAR; SCHED;
;     STAGEW(SB(1, 1), Bt, bcol + HALF, bcol_n + HALF, t + 3);
	s_ashr_i32 s41, s40, 31
	s_lshl_b64 s[38:39], s[40:41], 12
	s_add_u32 s3, s62, s38
	s_addc_u32 s18, s63, s39
	s_add_u32 s38, s3, s4
	s_addc_u32 s39, s18, s5
	s_mov_b32 m0, s14
	v_lshl_add_u64 v[134:135], s[38:39], 0, v[130:131]
	global_load_lds_dwordx4 v[134:135], off
	v_lshl_add_u64 v[134:135], v[134:135], 0, s[86:87]
	s_mov_b32 m0, s15
	s_nop 0
	global_load_lds_dwordx4 v[134:135], off
	s_waitcnt vmcnt(6)
	s_barrier
	v_mfma_f32_16x16x32_bf16 v[28:31], v[154:157], v[210:213], v[28:31]
	v_mfma_f32_16x16x32_bf16 v[24:27], v[154:157], v[218:221], v[24:27]
	v_mfma_f32_16x16x32_bf16 v[20:23], v[172:175], v[210:213], v[20:23]
	v_mfma_f32_16x16x32_bf16 v[16:19], v[172:175], v[218:221], v[16:19]
	v_mfma_f32_16x16x32_bf16 v[12:15], v[180:183], v[210:213], v[12:15]
	v_mfma_f32_16x16x32_bf16 v[8:11], v[180:183], v[218:221], v[8:11]
	v_mfma_f32_16x16x32_bf16 v[4:7], v[188:191], v[210:213], v[4:7]
	v_mfma_f32_16x16x32_bf16 v[0:3], v[188:191], v[218:221], v[0:3]
	v_mfma_f32_16x16x32_bf16 v[28:31], v[168:171], v[214:217], v[28:31]
	v_mfma_f32_16x16x32_bf16 v[24:27], v[168:171], v[222:225], v[24:27]
	v_mfma_f32_16x16x32_bf16 v[20:23], v[176:179], v[214:217], v[20:23]
	v_mfma_f32_16x16x32_bf16 v[16:19], v[176:179], v[222:225], v[16:19]
	v_mfma_f32_16x16x32_bf16 v[12:15], v[184:187], v[214:217], v[12:15]
	v_mfma_f32_16x16x32_bf16 v[8:11], v[184:187], v[222:225], v[8:11]
	v_mfma_f32_16x16x32_bf16 v[4:7], v[192:195], v[214:217], v[4:7]
	v_mfma_f32_16x16x32_bf16 v[0:3], v[192:195], v[222:225], v[0:3]
	v_add_u32_e32 v142, s83, v159
	s_barrier
	ds_read_b128 v[134:137], v142
	ds_read_b128 v[138:141], v142 offset:1024
	ds_read_b128 v[146:149], v142 offset:2048
	ds_read_b128 v[150:153], v142 offset:3072
	s_ashr_i32 s3, s2, 31
	s_lshl_b64 s[2:3], s[2:3], 12
	s_add_u32 s2, s69, s2
	s_addc_u32 s3, s70, s3
	s_add_u32 s2, s2, s4
	s_addc_u32 s3, s3, s5
	s_mov_b32 m0, s16
	v_lshl_add_u64 v[142:143], s[2:3], 0, v[130:131]
	ds_read_b128 v[154:157], v144 offset:32768
	ds_read_b128 v[168:171], v144 offset:33792
	ds_read_b128 v[172:175], v160 offset:32768
	ds_read_b128 v[176:179], v160 offset:33792
	ds_read_b128 v[180:183], v161 offset:32768
	ds_read_b128 v[184:187], v161 offset:33792
	ds_read_b128 v[188:191], v162 offset:32768
	ds_read_b128 v[192:195], v162 offset:33792
	global_load_lds_dwordx4 v[142:143], off
	v_lshl_add_u64 v[142:143], v[142:143], 0, s[86:87]
	s_mov_b32 m0, s17
	s_nop 0
	global_load_lds_dwordx4 v[142:143], off
	s_waitcnt lgkmcnt(8)
	s_barrier
	s_waitcnt lgkmcnt(0)
	s_waitcnt lgkmcnt(0)
	v_mfma_f32_16x16x32_bf16 v[124:127], v[154:157], v[134:137], v[124:127]
	v_mfma_f32_16x16x32_bf16 v[120:123], v[154:157], v[146:149], v[120:123]
	v_mfma_f32_16x16x32_bf16 v[116:119], v[172:175], v[134:137], v[116:119]
	v_mfma_f32_16x16x32_bf16 v[112:115], v[172:175], v[146:149], v[112:115]
	v_mfma_f32_16x16x32_bf16 v[108:111], v[180:183], v[134:137], v[108:111]
	v_mfma_f32_16x16x32_bf16 v[104:107], v[180:183], v[146:149], v[104:107]
	v_mfma_f32_16x16x32_bf16 v[100:103], v[188:191], v[134:137], v[100:103]
	v_mfma_f32_16x16x32_bf16 v[96:99], v[188:191], v[146:149], v[96:99]
	v_mfma_f32_16x16x32_bf16 v[124:127], v[168:171], v[138:141], v[124:127]
	v_mfma_f32_16x16x32_bf16 v[120:123], v[168:171], v[150:153], v[120:123]
	v_mfma_f32_16x16x32_bf16 v[116:119], v[176:179], v[138:141], v[116:119]
	v_mfma_f32_16x16x32_bf16 v[112:115], v[176:179], v[150:153], v[112:115]
	v_mfma_f32_16x16x32_bf16 v[108:111], v[184:187], v[138:141], v[108:111]
	v_mfma_f32_16x16x32_bf16 v[104:107], v[184:187], v[150:153], v[104:107]
	v_mfma_f32_16x16x32_bf16 v[100:103], v[192:195], v[138:141], v[100:103]
	v_mfma_f32_16x16x32_bf16 v[96:99], v[192:195], v[150:153], v[96:99]
	s_barrier
	s_cmp_lt_u32 s1, 29
	s_cselect_b32 s2, s27, s29
	s_cselect_b32 s5, 0, 0xffffffe0
	s_cselect_b32 s4, s0, s28
	s_cselect_b32 s38, s34, s31
	s_ashr_i32 s3, s2, 31
	s_lshl_b64 s[2:3], s[2:3], 12
	s_add_u32 s37, s62, s2
	s_addc_u32 s39, s63, s3
	s_add_i32 s1, s5, s1
	s_add_i32 s18, s1, 3
	s_lshl_b64 s[2:3], s[18:19], 7
	s_add_u32 s40, s37, s2
	v_add_u32_e32 v142, s84, v159
	s_addc_u32 s41, s39, s3
	s_mov_b32 m0, s20
	ds_read_b128 v[210:213], v142
	ds_read_b128 v[214:217], v142 offset:1024
	ds_read_b128 v[218:221], v142 offset:2048
	ds_read_b128 v[222:225], v142 offset:3072
	v_lshl_add_u64 v[142:143], s[40:41], 0, v[130:131]
	global_load_lds_dwordx4 v[142:143], off
	v_lshl_add_u64 v[142:143], v[142:143], 0, s[86:87]
	s_mov_b32 m0, s21
	s_nop 0
	global_load_lds_dwordx4 v[142:143], off
	s_barrier
; #define LDA(dst, b, h) _Pragma("unroll") for (int m = 0; m < 4; ++m) _Pragma("unroll") for (int k = 0; k < 2; ++k) \
;     dst[m][k] = *reinterpret_cast<const bf16x8*>((char*)SA(b, h) + lds_byte(wr * 64 + m * 16 + fr, k * 32 + fq * 8))
; #define LDB(dst, b, h) _Pragma("unroll") for (int n = 0; n < 2; ++n) _Pragma("unroll") for (int k = 0; k < 2; ++k) \
;     dst[n][k] = *reinterpret_cast<const bf16x8*>((char*)SB(b, h) + lds_byte(wc * 32 + n * 16 + fr, k * 32 + fq * 8))
; #define MMA(ai, bj, At_, Bt_) do { __builtin_amdgcn_s_setprio(1); \
;     _Pragma("unroll") for (int m = 0; m < 4; ++m) _Pragma("unroll") for (int n = 0; n < 2; ++n) _Pragma("unroll") for (int k = 0; k < 2; ++k) \
;       acc[ai][bj][m][n] = __builtin_amdgcn_mfma_f32_16x16x32_bf16(At_[m][k], Bt_[n][k], acc[ai][bj][m][n], 0, 0, 0); \
;     __builtin_amdgcn_s_setprio(0); } while (0)
; #define WAIT_V(n) asm volatile("s_waitcnt vmcnt(" #n ")" ::: "memory")
; #define WAIT_L(n) asm volatile("s_waitcnt lgkmcnt(" #n ")" ::: "memory")
; #define BAR __builtin_amdgcn_s_barrier()
; #define SCHED __builtin_amdgcn_sched_barrier(0)
; #define STAGEW(P_, BASE, cur, nxt, kt_) do { const bool _wr = (kt_) >= nt; \
;     STAGE(P_, BASE, (_wr ? (nxt) : (cur)), (_wr ? (kt_) - nt : (kt_))); } while (0)
; template <int PRE> ...
;     ...
;     LDB(B1, 1, 1); STAGEW(SB(1, 0), Bt, bcol, bcol_n, t + 3);
;     BAR; WAIT_L(0); MMA(0, 1, At, B1); BAR;
;     LDA(At, 1, 1); STAGEW(SA(1, 0), A, brow, brow_n, t + 3);
;     BAR; WAIT_L(0); MMA(1, 0, At, B0); BAR; SCHED;
;     STAGEW(SB(1, 1), Bt, bcol + HALF, bcol_n + HALF, t + 3);
;     WAIT_V(6); BAR; MMA(1, 1, At, B1); BAR;
;   }
;   if (wr == 0) BAR;
	s_waitcnt lgkmcnt(0)
	s_waitcnt lgkmcnt(0)
	v_mfma_f32_16x16x32_bf16 v[92:95], v[154:157], v[210:213], v[92:95]
	v_mfma_f32_16x16x32_bf16 v[88:91], v[154:157], v[218:221], v[88:91]
	v_mfma_f32_16x16x32_bf16 v[84:87], v[172:175], v[210:213], v[84:87]
	v_mfma_f32_16x16x32_bf16 v[80:83], v[172:175], v[218:221], v[80:83]
	v_mfma_f32_16x16x32_bf16 v[76:79], v[180:183], v[210:213], v[76:79]
	v_mfma_f32_16x16x32_bf16 v[72:75], v[180:183], v[218:221], v[72:75]
	v_mfma_f32_16x16x32_bf16 v[68:71], v[188:191], v[210:213], v[68:71]
	v_mfma_f32_16x16x32_bf16 v[64:67], v[188:191], v[218:221], v[64:67]
	v_mfma_f32_16x16x32_bf16 v[92:95], v[168:171], v[214:217], v[92:95]
	v_mfma_f32_16x16x32_bf16 v[88:91], v[168:171], v[222:225], v[88:91]
	v_mfma_f32_16x16x32_bf16 v[84:87], v[176:179], v[214:217], v[84:87]
	v_mfma_f32_16x16x32_bf16 v[80:83], v[176:179], v[222:225], v[80:83]
	v_mfma_f32_16x16x32_bf16 v[76:79], v[184:187], v[214:217], v[76:79]
	v_mfma_f32_16x16x32_bf16 v[72:75], v[184:187], v[222:225], v[72:75]
	v_mfma_f32_16x16x32_bf16 v[68:71], v[192:195], v[214:217], v[68:71]
	v_mfma_f32_16x16x32_bf16 v[64:67], v[192:195], v[222:225], v[64:67]
	s_ashr_i32 s5, s4, 31
	s_lshl_b64 s[4:5], s[4:5], 12
	s_add_u32 s1, s69, s4
	s_addc_u32 s5, s70, s5
	s_add_u32 s4, s1, s2
	s_addc_u32 s5, s5, s3
	s_mov_b32 m0, s22
	v_lshl_add_u64 v[142:143], s[4:5], 0, v[130:131]
	s_barrier
	ds_read_b128 v[154:157], v144 offset:49152
	ds_read_b128 v[168:171], v144 offset:50176
	ds_read_b128 v[172:175], v160 offset:49152
	ds_read_b128 v[176:179], v160 offset:50176
	ds_read_b128 v[180:183], v161 offset:49152
	ds_read_b128 v[184:187], v161 offset:50176
	ds_read_b128 v[188:191], v162 offset:49152
	ds_read_b128 v[192:195], v162 offset:50176
	global_load_lds_dwordx4 v[142:143], off
	v_lshl_add_u64 v[142:143], v[142:143], 0, s[86:87]
	s_mov_b32 m0, s23
	s_nop 0
	global_load_lds_dwordx4 v[142:143], off
	s_barrier
	s_waitcnt lgkmcnt(0)
	s_waitcnt lgkmcnt(0)
	v_mfma_f32_16x16x32_bf16 v[60:63], v[154:157], v[134:137], v[60:63]
	v_mfma_f32_16x16x32_bf16 v[56:59], v[154:157], v[146:149], v[56:59]
	v_mfma_f32_16x16x32_bf16 v[52:55], v[172:175], v[134:137], v[52:55]
	v_mfma_f32_16x16x32_bf16 v[48:51], v[172:175], v[146:149], v[48:51]
	v_mfma_f32_16x16x32_bf16 v[44:47], v[180:183], v[134:137], v[44:47]
	v_mfma_f32_16x16x32_bf16 v[40:43], v[180:183], v[146:149], v[40:43]
	v_mfma_f32_16x16x32_bf16 v[36:39], v[188:191], v[134:137], v[36:39]
	v_mfma_f32_16x16x32_bf16 v[32:35], v[188:191], v[146:149], v[32:35]
	v_mfma_f32_16x16x32_bf16 v[60:63], v[168:171], v[138:141], v[60:63]
	v_mfma_f32_16x16x32_bf16 v[56:59], v[168:171], v[150:153], v[56:59]
	v_mfma_f32_16x16x32_bf16 v[52:55], v[176:179], v[138:141], v[52:55]
	v_mfma_f32_16x16x32_bf16 v[48:51], v[176:179], v[150:153], v[48:51]
	v_mfma_f32_16x16x32_bf16 v[44:47], v[184:187], v[138:141], v[44:47]
	v_mfma_f32_16x16x32_bf16 v[40:43], v[184:187], v[150:153], v[40:43]
	v_mfma_f32_16x16x32_bf16 v[36:39], v[192:195], v[138:141], v[36:39]
	v_mfma_f32_16x16x32_bf16 v[32:35], v[192:195], v[150:153], v[32:35]
	s_barrier
	s_ashr_i32 s39, s38, 31
	s_lshl_b64 s[4:5], s[38:39], 12
	s_add_u32 s1, s62, s4
	s_addc_u32 s4, s63, s5
	s_add_u32 s2, s1, s2
	s_addc_u32 s3, s4, s3
	s_mov_b32 m0, s24
	v_lshl_add_u64 v[134:135], s[2:3], 0, v[130:131]
	global_load_lds_dwordx4 v[134:135], off
	v_lshl_add_u64 v[134:135], v[134:135], 0, s[86:87]
	s_mov_b32 m0, s25
	s_nop 0
	global_load_lds_dwordx4 v[134:135], off
	s_waitcnt vmcnt(6)
	s_barrier
	v_mfma_f32_16x16x32_bf16 v[28:31], v[154:157], v[210:213], v[28:31]
	v_mfma_f32_16x16x32_bf16 v[24:27], v[154:157], v[218:221], v[24:27]
	v_mfma_f32_16x16x32_bf16 v[20:23], v[172:175], v[210:213], v[20:23]
	v_mfma_f32_16x16x32_bf16 v[16:19], v[172:175], v[218:221], v[16:19]
	v_mfma_f32_16x16x32_bf16 v[12:15], v[180:183], v[210:213], v[12:15]
	v_mfma_f32_16x16x32_bf16 v[8:11], v[180:183], v[218:221], v[8:11]
	v_mfma_f32_16x16x32_bf16 v[4:7], v[188:191], v[210:213], v[4:7]
	v_mfma_f32_16x16x32_bf16 v[0:3], v[188:191], v[218:221], v[0:3]
	v_mfma_f32_16x16x32_bf16 v[28:31], v[168:171], v[214:217], v[28:31]
	v_mfma_f32_16x16x32_bf16 v[24:27], v[168:171], v[222:225], v[24:27]
	v_mfma_f32_16x16x32_bf16 v[20:23], v[176:179], v[214:217], v[20:23]
	v_mfma_f32_16x16x32_bf16 v[16:19], v[176:179], v[222:225], v[16:19]
	v_mfma_f32_16x16x32_bf16 v[12:15], v[184:187], v[214:217], v[12:15]
	v_mfma_f32_16x16x32_bf16 v[8:11], v[184:187], v[222:225], v[8:11]
	v_mfma_f32_16x16x32_bf16 v[4:7], v[192:195], v[214:217], v[4:7]
	v_mfma_f32_16x16x32_bf16 v[0:3], v[192:195], v[222:225], v[0:3]
	v_lshl_add_u64 v[128:129], v[128:129], 0, s[46:47]
	s_mov_b32 s1, s36
	s_barrier
	s_cbranch_vccnz .LBB0_825
	v_readlane_b32 s34, v243, 2
	s_andn2_b64 vcc, exec, s[58:59]
	v_readlane_b32 s31, v244, 61
	v_readlane_b32 s35, v243, 3
	s_cbranch_vccnz .LBB0_828
	s_barrier

; #define STAGE(P_, BASE, br, kt) do { const u16* _gb = (BASE) + (long)(br) * K + (long)(kt) * BK; \
;     _Pragma("unroll") for (int _i = 0; _i < 2; ++_i) { \
;       __builtin_amdgcn_global_load_lds((const unsigned*)(_gb + (long)_i * 64 * K + lane_off), \
;         (unsigned*)((char*)(P_) + lds_wbase + _i * 8192), 16, 0, 0); } } while (0)
; #define LDA(dst, b, h) _Pragma("unroll") for (int m = 0; m < 4; ++m) _Pragma("unroll") for (int k = 0; k < 2; ++k) \
;     dst[m][k] = *reinterpret_cast<const bf16x8*>((char*)SA(b, h) + lds_byte(wr * 64 + m * 16 + fr, k * 32 + fq * 8))
; #define LDB(dst, b, h) _Pragma("unroll") for (int n = 0; n < 2; ++n) _Pragma("unroll") for (int k = 0; k < 2; ++k) \
;     dst[n][k] = *reinterpret_cast<const bf16x8*>((char*)SB(b, h) + lds_byte(wc * 32 + n * 16 + fr, k * 32 + fq * 8))
; #define MMA(ai, bj, At_, Bt_) do { __builtin_amdgcn_s_setprio(1); \
;     _Pragma("unroll") for (int m = 0; m < 4; ++m) _Pragma("unroll") for (int n = 0; n < 2; ++n) _Pragma("unroll") for (int k = 0; k < 2; ++k) \
;       acc[ai][bj][m][n] = __builtin_amdgcn_mfma_f32_16x16x32_bf16(At_[m][k], Bt_[n][k], acc[ai][bj][m][n], 0, 0, 0); \
;     __builtin_amdgcn_s_setprio(0); } while (0)
; #define WAIT_V(n) asm volatile("s_waitcnt vmcnt(" #n ")" ::: "memory")
; #define WAIT_L(n) asm volatile("s_waitcnt lgkmcnt(" #n ")" ::: "memory")
; #define BAR __builtin_amdgcn_s_barrier()
; #define SCHED __builtin_amdgcn_sched_barrier(0)
; #define STAGEW(P_, BASE, cur, nxt, kt_) do { const bool _wr = (kt_) >= nt; \
;     STAGE(P_, BASE, (_wr ? (nxt) : (cur)), (_wr ? (kt_) - nt : (kt_))); } while (0)
; template <int PRE> ...
;     ...
;   for (int t = 0; t < nt; t += 2) {
;     LDB(B0, 0, 0); SCHED; LDA(At, 0, 0); STAGE(SA(1, 1), A, brow + HALF, t + 1);
;     WAIT_L(8); BAR; WAIT_L(0); MMA(0, 0, At, B0); BAR; SCHED;
;     LDB(B1, 0, 1); STAGEW(SB(0, 0), Bt, bcol, bcol_n, t + 2);
;     BAR; WAIT_L(0); MMA(0, 1, At, B1); BAR;
;     LDA(At, 0, 1); STAGEW(SA(0, 0), A, brow, brow_n, t + 2);
;     BAR; WAIT_L(0); MMA(1, 0, At, B0); BAR; SCHED;
;     STAGEW(SB(0, 1), Bt, bcol + HALF, bcol_n + HALF, t + 2);
;     WAIT_V(6); BAR; MMA(1, 1, At, B1); BAR;
.LBB0_892:
	v_add_u32_e32 v142, s81, v147
	ds_read_b128 v[134:137], v142
	ds_read_b128 v[138:141], v142 offset:1024
	ds_read_b128 v[152:155], v142 offset:2048
	ds_read_b128 v[156:159], v142 offset:3072
	s_add_i32 m0, s12, 0xc000
	ds_read_b128 v[160:163], v144
	ds_read_b128 v[168:171], v144 offset:1024
	ds_read_b128 v[172:175], v148
	ds_read_b128 v[176:179], v148 offset:1024
	ds_read_b128 v[180:183], v149
	ds_read_b128 v[184:187], v149 offset:1024
	ds_read_b128 v[188:191], v150
	ds_read_b128 v[192:195], v150 offset:1024
	global_load_lds_dwordx4 v[132:133], off
	v_lshl_add_u64 v[142:143], v[132:133], 0, s[86:87]
	s_add_i32 m0, s12, 0xe000
	s_nop 0
	global_load_lds_dwordx4 v[142:143], off
	s_waitcnt lgkmcnt(8)
	s_barrier
	s_waitcnt lgkmcnt(0)
	s_waitcnt lgkmcnt(0)
	v_mfma_f32_16x16x32_bf16 v[124:127], v[160:163], v[134:137], v[124:127]
	v_mfma_f32_16x16x32_bf16 v[120:123], v[160:163], v[152:155], v[120:123]
	v_mfma_f32_16x16x32_bf16 v[116:119], v[172:175], v[134:137], v[116:119]
	v_mfma_f32_16x16x32_bf16 v[112:115], v[172:175], v[152:155], v[112:115]
	v_mfma_f32_16x16x32_bf16 v[108:111], v[180:183], v[134:137], v[108:111]
	v_mfma_f32_16x16x32_bf16 v[104:107], v[180:183], v[152:155], v[104:107]
	v_mfma_f32_16x16x32_bf16 v[100:103], v[188:191], v[134:137], v[100:103]
	v_mfma_f32_16x16x32_bf16 v[96:99], v[188:191], v[152:155], v[96:99]
	v_mfma_f32_16x16x32_bf16 v[124:127], v[168:171], v[138:141], v[124:127]
	v_mfma_f32_16x16x32_bf16 v[120:123], v[168:171], v[156:159], v[120:123]
	v_mfma_f32_16x16x32_bf16 v[116:119], v[176:179], v[138:141], v[116:119]
	v_mfma_f32_16x16x32_bf16 v[112:115], v[176:179], v[156:159], v[112:115]
	v_mfma_f32_16x16x32_bf16 v[108:111], v[184:187], v[138:141], v[108:111]
	v_mfma_f32_16x16x32_bf16 v[104:107], v[184:187], v[156:159], v[104:107]
	v_mfma_f32_16x16x32_bf16 v[100:103], v[192:195], v[138:141], v[100:103]
	v_mfma_f32_16x16x32_bf16 v[96:99], v[192:195], v[156:159], v[96:99]
	s_barrier
	s_add_i32 s38, s1, 2
	s_cmp_lt_u32 s1, 30
	s_cselect_b64 s[2:3], -1, 0
	s_and_b64 vcc, s[2:3], exec
	s_cselect_b32 s4, s29, s31
	s_cselect_b32 s3, 0, 0xffffffe0
	s_cselect_b32 s40, s0, s30
	s_cselect_b32 s42, s36, s35
	s_cselect_b32 s2, s34, s37
	s_ashr_i32 s5, s4, 31
	s_lshl_b64 s[4:5], s[4:5], 12
	s_add_u32 s39, s72, s4
	s_addc_u32 s41, s73, s5
	s_add_i32 s18, s38, s3
	s_lshl_b64 s[4:5], s[18:19], 7
	s_add_u32 s44, s39, s4
	v_add_u32_e32 v142, s82, v147
	s_addc_u32 s45, s41, s5
	s_mov_b32 m0, s13
	ds_read_b128 v[210:213], v142
	ds_read_b128 v[214:217], v142 offset:1024
	ds_read_b128 v[218:221], v142 offset:2048
	ds_read_b128 v[222:225], v142 offset:3072
	v_lshl_add_u64 v[142:143], s[44:45], 0, v[128:129]
	global_load_lds_dwordx4 v[142:143], off
	v_lshl_add_u64 v[142:143], v[142:143], 0, s[86:87]
	s_mov_b32 m0, s14
	s_nop 0
	global_load_lds_dwordx4 v[142:143], off
	s_barrier
	s_waitcnt lgkmcnt(0)
	s_waitcnt lgkmcnt(0)
	v_mfma_f32_16x16x32_bf16 v[92:95], v[160:163], v[210:213], v[92:95]
	v_mfma_f32_16x16x32_bf16 v[88:91], v[160:163], v[218:221], v[88:91]
	v_mfma_f32_16x16x32_bf16 v[84:87], v[172:175], v[210:213], v[84:87]
	v_mfma_f32_16x16x32_bf16 v[80:83], v[172:175], v[218:221], v[80:83]
	v_mfma_f32_16x16x32_bf16 v[76:79], v[180:183], v[210:213], v[76:79]
	v_mfma_f32_16x16x32_bf16 v[72:75], v[180:183], v[218:221], v[72:75]
	v_mfma_f32_16x16x32_bf16 v[68:71], v[188:191], v[210:213], v[68:71]
	v_mfma_f32_16x16x32_bf16 v[64:67], v[188:191], v[218:221], v[64:67]
	v_mfma_f32_16x16x32_bf16 v[92:95], v[168:171], v[214:217], v[92:95]
	v_mfma_f32_16x16x32_bf16 v[88:91], v[168:171], v[222:225], v[88:91]
	v_mfma_f32_16x16x32_bf16 v[84:87], v[176:179], v[214:217], v[84:87]
	v_mfma_f32_16x16x32_bf16 v[80:83], v[176:179], v[222:225], v[80:83]
	v_mfma_f32_16x16x32_bf16 v[76:79], v[184:187], v[214:217], v[76:79]
	v_mfma_f32_16x16x32_bf16 v[72:75], v[184:187], v[222:225], v[72:75]
	v_mfma_f32_16x16x32_bf16 v[68:71], v[192:195], v[214:217], v[68:71]
	v_mfma_f32_16x16x32_bf16 v[64:67], v[192:195], v[222:225], v[64:67]
	s_ashr_i32 s41, s40, 31
	s_lshl_b64 s[40:41], s[40:41], 12
	s_add_u32 s3, s71, s40
	s_addc_u32 s18, s74, s41
	s_add_u32 s40, s3, s4
	s_addc_u32 s41, s18, s5
	s_mov_b32 m0, s12
	v_lshl_add_u64 v[142:143], s[40:41], 0, v[128:129]
	s_barrier
	ds_read_b128 v[160:163], v144 offset:16384
	ds_read_b128 v[168:171], v144 offset:17408
	ds_read_b128 v[172:175], v148 offset:16384
	ds_read_b128 v[176:179], v148 offset:17408
	ds_read_b128 v[180:183], v149 offset:16384
	ds_read_b128 v[184:187], v149 offset:17408
	ds_read_b128 v[188:191], v150 offset:16384
	ds_read_b128 v[192:195], v150 offset:17408
	global_load_lds_dwordx4 v[142:143], off
	v_lshl_add_u64 v[142:143], v[142:143], 0, s[86:87]
	s_mov_b32 m0, s15
	s_nop 0
	global_load_lds_dwordx4 v[142:143], off
	s_barrier
	s_waitcnt lgkmcnt(0)
	s_waitcnt lgkmcnt(0)
	v_mfma_f32_16x16x32_bf16 v[60:63], v[160:163], v[134:137], v[60:63]
	v_mfma_f32_16x16x32_bf16 v[56:59], v[160:163], v[152:155], v[56:59]
	v_mfma_f32_16x16x32_bf16 v[52:55], v[172:175], v[134:137], v[52:55]
	v_mfma_f32_16x16x32_bf16 v[48:51], v[172:175], v[152:155], v[48:51]
	v_mfma_f32_16x16x32_bf16 v[44:47], v[180:183], v[134:137], v[44:47]
	v_mfma_f32_16x16x32_bf16 v[40:43], v[180:183], v[152:155], v[40:43]
	v_mfma_f32_16x16x32_bf16 v[36:39], v[188:191], v[134:137], v[36:39]
	v_mfma_f32_16x16x32_bf16 v[32:35], v[188:191], v[152:155], v[32:35]
	v_mfma_f32_16x16x32_bf16 v[60:63], v[168:171], v[138:141], v[60:63]
	v_mfma_f32_16x16x32_bf16 v[56:59], v[168:171], v[156:159], v[56:59]
	v_mfma_f32_16x16x32_bf16 v[52:55], v[176:179], v[138:141], v[52:55]
	v_mfma_f32_16x16x32_bf16 v[48:51], v[176:179], v[156:159], v[48:51]
	v_mfma_f32_16x16x32_bf16 v[44:47], v[184:187], v[138:141], v[44:47]
	v_mfma_f32_16x16x32_bf16 v[40:43], v[184:187], v[156:159], v[40:43]
	v_mfma_f32_16x16x32_bf16 v[36:39], v[192:195], v[138:141], v[36:39]
	v_mfma_f32_16x16x32_bf16 v[32:35], v[192:195], v[156:159], v[32:35]
	s_barrier
; #define LDA(dst, b, h) _Pragma("unroll") for (int m = 0; m < 4; ++m) _Pragma("unroll") for (int k = 0; k < 2; ++k) \
;     dst[m][k] = *reinterpret_cast<const bf16x8*>((char*)SA(b, h) + lds_byte(wr * 64 + m * 16 + fr, k * 32 + fq * 8))
; #define LDB(dst, b, h) _Pragma("unroll") for (int n = 0; n < 2; ++n) _Pragma("unroll") for (int k = 0; k < 2; ++k) \
;     dst[n][k] = *reinterpret_cast<const bf16x8*>((char*)SB(b, h) + lds_byte(wc * 32 + n * 16 + fr, k * 32 + fq * 8))
; #define MMA(ai, bj, At_, Bt_) do { __builtin_amdgcn_s_setprio(1); \
;     _Pragma("unroll") for (int m = 0; m < 4; ++m) _Pragma("unroll") for (int n = 0; n < 2; ++n) _Pragma("unroll") for (int k = 0; k < 2; ++k) \
;       acc[ai][bj][m][n] = __builtin_amdgcn_mfma_f32_16x16x32_bf16(At_[m][k], Bt_[n][k], acc[ai][bj][m][n], 0, 0, 0); \
;     __builtin_amdgcn_s_setprio(0); } while (0)
; #define WAIT_V(n) asm volatile("s_waitcnt vmcnt(" #n ")" ::: "memory")
; #define WAIT_L(n) asm volatile("s_waitcnt lgkmcnt(" #n ")" ::: "memory")
; #define BAR __builtin_amdgcn_s_barrier()
; #define SCHED __builtin_amdgcn_sched_barrier(0)
; #define STAGEW(P_, BASE, cur, nxt, kt_) do { const bool _wr = (kt_) >= nt; \
;     STAGE(P_, BASE, (_wr ? (nxt) : (cur)), (_wr ? (kt_) - nt : (kt_))); } while (0)
; template <int PRE> ...
;     ...
;     STAGEW(SB(0, 1), Bt, bcol + HALF, bcol_n + HALF, t + 2);
;     WAIT_V(6); BAR; MMA(1, 1, At, B1); BAR;
;     LDB(B0, 1, 0); SCHED; LDA(At, 1, 0); STAGEW(SA(0, 1), A, brow + HALF, brow_n + HALF, t + 2);
;     WAIT_L(8); BAR; WAIT_L(0); MMA(0, 0, At, B0); BAR; SCHED;
;     LDB(B1, 1, 1); STAGEW(SB(1, 0), Bt, bcol, bcol_n, t + 3);
;     BAR; WAIT_L(0); MMA(0, 1, At, B1); BAR;
;     LDA(At, 1, 1); STAGEW(SA(1, 0), A, brow, brow_n, t + 3);
;     BAR; WAIT_L(0); MMA(1, 0, At, B0); BAR; SCHED;
;     STAGEW(SB(1, 1), Bt, bcol + HALF, bcol_n + HALF, t + 3);
	s_ashr_i32 s43, s42, 31
	s_lshl_b64 s[40:41], s[42:43], 12
	s_add_u32 s3, s72, s40
	s_addc_u32 s18, s73, s41
	s_add_u32 s40, s3, s4
	s_addc_u32 s41, s18, s5
	s_mov_b32 m0, s16
	v_lshl_add_u64 v[134:135], s[40:41], 0, v[128:129]
	global_load_lds_dwordx4 v[134:135], off
	v_lshl_add_u64 v[134:135], v[134:135], 0, s[86:87]
	s_mov_b32 m0, s17
	s_nop 0
	global_load_lds_dwordx4 v[134:135], off
	s_waitcnt vmcnt(6)
	s_barrier
	v_mfma_f32_16x16x32_bf16 v[28:31], v[160:163], v[210:213], v[28:31]
	v_mfma_f32_16x16x32_bf16 v[24:27], v[160:163], v[218:221], v[24:27]
	v_mfma_f32_16x16x32_bf16 v[20:23], v[172:175], v[210:213], v[20:23]
	v_mfma_f32_16x16x32_bf16 v[16:19], v[172:175], v[218:221], v[16:19]
	v_mfma_f32_16x16x32_bf16 v[12:15], v[180:183], v[210:213], v[12:15]
	v_mfma_f32_16x16x32_bf16 v[8:11], v[180:183], v[218:221], v[8:11]
	v_mfma_f32_16x16x32_bf16 v[4:7], v[188:191], v[210:213], v[4:7]
	v_mfma_f32_16x16x32_bf16 v[0:3], v[188:191], v[218:221], v[0:3]
	v_mfma_f32_16x16x32_bf16 v[28:31], v[168:171], v[214:217], v[28:31]
	v_mfma_f32_16x16x32_bf16 v[24:27], v[168:171], v[222:225], v[24:27]
	v_mfma_f32_16x16x32_bf16 v[20:23], v[176:179], v[214:217], v[20:23]
	v_mfma_f32_16x16x32_bf16 v[16:19], v[176:179], v[222:225], v[16:19]
	v_mfma_f32_16x16x32_bf16 v[12:15], v[184:187], v[214:217], v[12:15]
	v_mfma_f32_16x16x32_bf16 v[8:11], v[184:187], v[222:225], v[8:11]
	v_mfma_f32_16x16x32_bf16 v[4:7], v[192:195], v[214:217], v[4:7]
	v_mfma_f32_16x16x32_bf16 v[0:3], v[192:195], v[222:225], v[0:3]
	v_add_u32_e32 v142, s83, v147
	s_barrier
	ds_read_b128 v[134:137], v142
	ds_read_b128 v[138:141], v142 offset:1024
	ds_read_b128 v[152:155], v142 offset:2048
	ds_read_b128 v[156:159], v142 offset:3072
	s_ashr_i32 s3, s2, 31
	s_lshl_b64 s[2:3], s[2:3], 12
	s_add_u32 s2, s71, s2
	s_addc_u32 s3, s74, s3
	s_add_u32 s2, s2, s4
	s_addc_u32 s3, s3, s5
	s_mov_b32 m0, s20
	v_lshl_add_u64 v[142:143], s[2:3], 0, v[128:129]
	ds_read_b128 v[160:163], v144 offset:32768
	ds_read_b128 v[168:171], v144 offset:33792
	ds_read_b128 v[172:175], v148 offset:32768
	ds_read_b128 v[176:179], v148 offset:33792
	ds_read_b128 v[180:183], v149 offset:32768
	ds_read_b128 v[184:187], v149 offset:33792
	ds_read_b128 v[188:191], v150 offset:32768
	ds_read_b128 v[192:195], v150 offset:33792
	global_load_lds_dwordx4 v[142:143], off
	v_lshl_add_u64 v[142:143], v[142:143], 0, s[86:87]
	s_mov_b32 m0, s21
	s_nop 0
	global_load_lds_dwordx4 v[142:143], off
	s_waitcnt lgkmcnt(8)
	s_barrier
	s_waitcnt lgkmcnt(0)
	s_waitcnt lgkmcnt(0)
	v_mfma_f32_16x16x32_bf16 v[124:127], v[160:163], v[134:137], v[124:127]
	v_mfma_f32_16x16x32_bf16 v[120:123], v[160:163], v[152:155], v[120:123]
	v_mfma_f32_16x16x32_bf16 v[116:119], v[172:175], v[134:137], v[116:119]
	v_mfma_f32_16x16x32_bf16 v[112:115], v[172:175], v[152:155], v[112:115]
	v_mfma_f32_16x16x32_bf16 v[108:111], v[180:183], v[134:137], v[108:111]
	v_mfma_f32_16x16x32_bf16 v[104:107], v[180:183], v[152:155], v[104:107]
	v_mfma_f32_16x16x32_bf16 v[100:103], v[188:191], v[134:137], v[100:103]
	v_mfma_f32_16x16x32_bf16 v[96:99], v[188:191], v[152:155], v[96:99]
	v_mfma_f32_16x16x32_bf16 v[124:127], v[168:171], v[138:141], v[124:127]
	v_mfma_f32_16x16x32_bf16 v[120:123], v[168:171], v[156:159], v[120:123]
	v_mfma_f32_16x16x32_bf16 v[116:119], v[176:179], v[138:141], v[116:119]
	v_mfma_f32_16x16x32_bf16 v[112:115], v[176:179], v[156:159], v[112:115]
	v_mfma_f32_16x16x32_bf16 v[108:111], v[184:187], v[138:141], v[108:111]
	v_mfma_f32_16x16x32_bf16 v[104:107], v[184:187], v[156:159], v[104:107]
	v_mfma_f32_16x16x32_bf16 v[100:103], v[192:195], v[138:141], v[100:103]
	v_mfma_f32_16x16x32_bf16 v[96:99], v[192:195], v[156:159], v[96:99]
	s_barrier
	s_cmp_lt_u32 s1, 29
	s_cselect_b32 s2, s29, s31
	s_cselect_b32 s5, 0, 0xffffffe0
	s_cselect_b32 s4, s0, s30
	s_cselect_b32 s40, s36, s35
	s_ashr_i32 s3, s2, 31
	s_lshl_b64 s[2:3], s[2:3], 12
	s_add_u32 s39, s72, s2
	s_addc_u32 s41, s73, s3
	s_add_i32 s1, s5, s1
	s_add_i32 s18, s1, 3
	s_lshl_b64 s[2:3], s[18:19], 7
	s_add_u32 s42, s39, s2
	v_add_u32_e32 v142, s84, v147
	s_addc_u32 s43, s41, s3
	s_mov_b32 m0, s22
	ds_read_b128 v[210:213], v142
	ds_read_b128 v[214:217], v142 offset:1024
	ds_read_b128 v[218:221], v142 offset:2048
	ds_read_b128 v[222:225], v142 offset:3072
	v_lshl_add_u64 v[142:143], s[42:43], 0, v[128:129]
	global_load_lds_dwordx4 v[142:143], off
	v_lshl_add_u64 v[142:143], v[142:143], 0, s[86:87]
	s_mov_b32 m0, s23
	s_nop 0
	global_load_lds_dwordx4 v[142:143], off
	s_barrier
; #define LDA(dst, b, h) _Pragma("unroll") for (int m = 0; m < 4; ++m) _Pragma("unroll") for (int k = 0; k < 2; ++k) \
;     dst[m][k] = *reinterpret_cast<const bf16x8*>((char*)SA(b, h) + lds_byte(wr * 64 + m * 16 + fr, k * 32 + fq * 8))
; #define LDB(dst, b, h) _Pragma("unroll") for (int n = 0; n < 2; ++n) _Pragma("unroll") for (int k = 0; k < 2; ++k) \
;     dst[n][k] = *reinterpret_cast<const bf16x8*>((char*)SB(b, h) + lds_byte(wc * 32 + n * 16 + fr, k * 32 + fq * 8))
; #define MMA(ai, bj, At_, Bt_) do { __builtin_amdgcn_s_setprio(1); \
;     _Pragma("unroll") for (int m = 0; m < 4; ++m) _Pragma("unroll") for (int n = 0; n < 2; ++n) _Pragma("unroll") for (int k = 0; k < 2; ++k) \
;       acc[ai][bj][m][n] = __builtin_amdgcn_mfma_f32_16x16x32_bf16(At_[m][k], Bt_[n][k], acc[ai][bj][m][n], 0, 0, 0); \
;     __builtin_amdgcn_s_setprio(0); } while (0)
; #define WAIT_V(n) asm volatile("s_waitcnt vmcnt(" #n ")" ::: "memory")
; #define WAIT_L(n) asm volatile("s_waitcnt lgkmcnt(" #n ")" ::: "memory")
; #define BAR __builtin_amdgcn_s_barrier()
; #define SCHED __builtin_amdgcn_sched_barrier(0)
; #define STAGEW(P_, BASE, cur, nxt, kt_) do { const bool _wr = (kt_) >= nt; \
;     STAGE(P_, BASE, (_wr ? (nxt) : (cur)), (_wr ? (kt_) - nt : (kt_))); } while (0)
; template <int PRE> ...
;     ...
;     LDB(B1, 1, 1); STAGEW(SB(1, 0), Bt, bcol, bcol_n, t + 3);
;     BAR; WAIT_L(0); MMA(0, 1, At, B1); BAR;
;     LDA(At, 1, 1); STAGEW(SA(1, 0), A, brow, brow_n, t + 3);
;     BAR; WAIT_L(0); MMA(1, 0, At, B0); BAR; SCHED;
;     STAGEW(SB(1, 1), Bt, bcol + HALF, bcol_n + HALF, t + 3);
;     WAIT_V(6); BAR; MMA(1, 1, At, B1); BAR;
;   }
;   if (wr == 0) BAR;
	s_waitcnt lgkmcnt(0)
	s_waitcnt lgkmcnt(0)
	v_mfma_f32_16x16x32_bf16 v[92:95], v[160:163], v[210:213], v[92:95]
	v_mfma_f32_16x16x32_bf16 v[88:91], v[160:163], v[218:221], v[88:91]
	v_mfma_f32_16x16x32_bf16 v[84:87], v[172:175], v[210:213], v[84:87]
	v_mfma_f32_16x16x32_bf16 v[80:83], v[172:175], v[218:221], v[80:83]
	v_mfma_f32_16x16x32_bf16 v[76:79], v[180:183], v[210:213], v[76:79]
	v_mfma_f32_16x16x32_bf16 v[72:75], v[180:183], v[218:221], v[72:75]
	v_mfma_f32_16x16x32_bf16 v[68:71], v[188:191], v[210:213], v[68:71]
	v_mfma_f32_16x16x32_bf16 v[64:67], v[188:191], v[218:221], v[64:67]
	v_mfma_f32_16x16x32_bf16 v[92:95], v[168:171], v[214:217], v[92:95]
	v_mfma_f32_16x16x32_bf16 v[88:91], v[168:171], v[222:225], v[88:91]
	v_mfma_f32_16x16x32_bf16 v[84:87], v[176:179], v[214:217], v[84:87]
	v_mfma_f32_16x16x32_bf16 v[80:83], v[176:179], v[222:225], v[80:83]
	v_mfma_f32_16x16x32_bf16 v[76:79], v[184:187], v[214:217], v[76:79]
	v_mfma_f32_16x16x32_bf16 v[72:75], v[184:187], v[222:225], v[72:75]
	v_mfma_f32_16x16x32_bf16 v[68:71], v[192:195], v[214:217], v[68:71]
	v_mfma_f32_16x16x32_bf16 v[64:67], v[192:195], v[222:225], v[64:67]
	s_ashr_i32 s5, s4, 31
	s_lshl_b64 s[4:5], s[4:5], 12
	s_add_u32 s1, s71, s4
	s_addc_u32 s5, s74, s5
	s_add_u32 s4, s1, s2
	s_addc_u32 s5, s5, s3
	s_mov_b32 m0, s24
	v_lshl_add_u64 v[142:143], s[4:5], 0, v[128:129]
	s_barrier
	ds_read_b128 v[160:163], v144 offset:49152
	ds_read_b128 v[168:171], v144 offset:50176
	ds_read_b128 v[172:175], v148 offset:49152
	ds_read_b128 v[176:179], v148 offset:50176
	ds_read_b128 v[180:183], v149 offset:49152
	ds_read_b128 v[184:187], v149 offset:50176
	ds_read_b128 v[188:191], v150 offset:49152
	ds_read_b128 v[192:195], v150 offset:50176
	global_load_lds_dwordx4 v[142:143], off
	v_lshl_add_u64 v[142:143], v[142:143], 0, s[86:87]
	s_mov_b32 m0, s25
	s_nop 0
	global_load_lds_dwordx4 v[142:143], off
	s_barrier
	s_waitcnt lgkmcnt(0)
	s_waitcnt lgkmcnt(0)
	v_mfma_f32_16x16x32_bf16 v[60:63], v[160:163], v[134:137], v[60:63]
	v_mfma_f32_16x16x32_bf16 v[56:59], v[160:163], v[152:155], v[56:59]
	v_mfma_f32_16x16x32_bf16 v[52:55], v[172:175], v[134:137], v[52:55]
	v_mfma_f32_16x16x32_bf16 v[48:51], v[172:175], v[152:155], v[48:51]
	v_mfma_f32_16x16x32_bf16 v[44:47], v[180:183], v[134:137], v[44:47]
	v_mfma_f32_16x16x32_bf16 v[40:43], v[180:183], v[152:155], v[40:43]
	v_mfma_f32_16x16x32_bf16 v[36:39], v[188:191], v[134:137], v[36:39]
	v_mfma_f32_16x16x32_bf16 v[32:35], v[188:191], v[152:155], v[32:35]
	v_mfma_f32_16x16x32_bf16 v[60:63], v[168:171], v[138:141], v[60:63]
	v_mfma_f32_16x16x32_bf16 v[56:59], v[168:171], v[156:159], v[56:59]
	v_mfma_f32_16x16x32_bf16 v[52:55], v[176:179], v[138:141], v[52:55]
	v_mfma_f32_16x16x32_bf16 v[48:51], v[176:179], v[156:159], v[48:51]
	v_mfma_f32_16x16x32_bf16 v[44:47], v[184:187], v[138:141], v[44:47]
	v_mfma_f32_16x16x32_bf16 v[40:43], v[184:187], v[156:159], v[40:43]
	v_mfma_f32_16x16x32_bf16 v[36:39], v[192:195], v[138:141], v[36:39]
	v_mfma_f32_16x16x32_bf16 v[32:35], v[192:195], v[156:159], v[32:35]
	s_barrier
	s_ashr_i32 s41, s40, 31
	s_lshl_b64 s[4:5], s[40:41], 12
	s_add_u32 s1, s72, s4
	s_addc_u32 s4, s73, s5
	s_add_u32 s2, s1, s2
	s_addc_u32 s3, s4, s3
	s_mov_b32 m0, s26
	v_lshl_add_u64 v[134:135], s[2:3], 0, v[128:129]
	global_load_lds_dwordx4 v[134:135], off
	v_lshl_add_u64 v[134:135], v[134:135], 0, s[86:87]
	s_mov_b32 m0, s27
	s_nop 0
	global_load_lds_dwordx4 v[134:135], off
	s_waitcnt vmcnt(6)
	s_barrier
	v_mfma_f32_16x16x32_bf16 v[28:31], v[160:163], v[210:213], v[28:31]
	v_mfma_f32_16x16x32_bf16 v[24:27], v[160:163], v[218:221], v[24:27]
	v_mfma_f32_16x16x32_bf16 v[20:23], v[172:175], v[210:213], v[20:23]
	v_mfma_f32_16x16x32_bf16 v[16:19], v[172:175], v[218:221], v[16:19]
	v_mfma_f32_16x16x32_bf16 v[12:15], v[180:183], v[210:213], v[12:15]
	v_mfma_f32_16x16x32_bf16 v[8:11], v[180:183], v[218:221], v[8:11]
	v_mfma_f32_16x16x32_bf16 v[4:7], v[188:191], v[210:213], v[4:7]
	v_mfma_f32_16x16x32_bf16 v[0:3], v[188:191], v[218:221], v[0:3]
	v_mfma_f32_16x16x32_bf16 v[28:31], v[168:171], v[214:217], v[28:31]
	v_mfma_f32_16x16x32_bf16 v[24:27], v[168:171], v[222:225], v[24:27]
	v_mfma_f32_16x16x32_bf16 v[20:23], v[176:179], v[214:217], v[20:23]
	v_mfma_f32_16x16x32_bf16 v[16:19], v[176:179], v[222:225], v[16:19]
	v_mfma_f32_16x16x32_bf16 v[12:15], v[184:187], v[214:217], v[12:15]
	v_mfma_f32_16x16x32_bf16 v[8:11], v[184:187], v[222:225], v[8:11]
	v_mfma_f32_16x16x32_bf16 v[4:7], v[192:195], v[214:217], v[4:7]
	v_mfma_f32_16x16x32_bf16 v[0:3], v[192:195], v[222:225], v[0:3]
	v_lshl_add_u64 v[132:133], v[132:133], 0, s[46:47]
	s_mov_b32 s1, s38
	s_barrier
	s_cbranch_vccnz .LBB0_892
	v_readlane_b32 s34, v243, 2
	s_andn2_b64 vcc, exec, s[58:59]
	v_readlane_b32 s31, v244, 61
	v_readlane_b32 s35, v243, 3
	s_cbranch_vccnz .LBB0_895
	s_barrier

; #define STAGE(P_, BASE, br, kt) do { const u16* _gb = (BASE) + (long)(br) * K + (long)(kt) * BK; \
;     _Pragma("unroll") for (int _i = 0; _i < 2; ++_i) { \
;       __builtin_amdgcn_global_load_lds((const unsigned*)(_gb + (long)_i * 64 * K + lane_off), \
;         (unsigned*)((char*)(P_) + lds_wbase + _i * 8192), 16, 0, 0); } } while (0)
; #define LDA(dst, b, h) _Pragma("unroll") for (int m = 0; m < 4; ++m) _Pragma("unroll") for (int k = 0; k < 2; ++k) \
;     dst[m][k] = *reinterpret_cast<const bf16x8*>((char*)SA(b, h) + lds_byte(wr * 64 + m * 16 + fr, k * 32 + fq * 8))
; #define LDB(dst, b, h) _Pragma("unroll") for (int n = 0; n < 2; ++n) _Pragma("unroll") for (int k = 0; k < 2; ++k) \
;     dst[n][k] = *reinterpret_cast<const bf16x8*>((char*)SB(b, h) + lds_byte(wc * 32 + n * 16 + fr, k * 32 + fq * 8))
; #define MMA(ai, bj, At_, Bt_) do { __builtin_amdgcn_s_setprio(1); \
;     _Pragma("unroll") for (int m = 0; m < 4; ++m) _Pragma("unroll") for (int n = 0; n < 2; ++n) _Pragma("unroll") for (int k = 0; k < 2; ++k) \
;       acc[ai][bj][m][n] = __builtin_amdgcn_mfma_f32_16x16x32_bf16(At_[m][k], Bt_[n][k], acc[ai][bj][m][n], 0, 0, 0); \
;     __builtin_amdgcn_s_setprio(0); } while (0)
; #define WAIT_V(n) asm volatile("s_waitcnt vmcnt(" #n ")" ::: "memory")
; #define WAIT_L(n) asm volatile("s_waitcnt lgkmcnt(" #n ")" ::: "memory")
; #define BAR __builtin_amdgcn_s_barrier()
; #define SCHED __builtin_amdgcn_sched_barrier(0)
; #define STAGEW(P_, BASE, cur, nxt, kt_) do { const bool _wr = (kt_) >= nt; \
;     STAGE(P_, BASE, (_wr ? (nxt) : (cur)), (_wr ? (kt_) - nt : (kt_))); } while (0)
; template <int PRE> ...
;     ...
;   for (int t = 0; t < nt; t += 2) {
;     LDB(B0, 0, 0); SCHED; LDA(At, 0, 0); STAGE(SA(1, 1), A, brow + HALF, t + 1);
;     WAIT_L(8); BAR; WAIT_L(0); MMA(0, 0, At, B0); BAR; SCHED;
;     LDB(B1, 0, 1); STAGEW(SB(0, 0), Bt, bcol, bcol_n, t + 2);
;     BAR; WAIT_L(0); MMA(0, 1, At, B1); BAR;
;     LDA(At, 0, 1); STAGEW(SA(0, 0), A, brow, brow_n, t + 2);
;     BAR; WAIT_L(0); MMA(1, 0, At, B0); BAR; SCHED;
;     STAGEW(SB(0, 1), Bt, bcol + HALF, bcol_n + HALF, t + 2);
;     WAIT_V(6); BAR; MMA(1, 1, At, B1); BAR;
.LBB0_1015:
	v_add_u32_e32 v144, s81, v135
	ds_read_b128 v[140:143], v144
	ds_read_b128 v[146:149], v144 offset:1024
	ds_read_b128 v[150:153], v144 offset:2048
	ds_read_b128 v[154:157], v144 offset:3072
	s_add_i32 m0, s10, 0xc000
	ds_read_b128 v[158:161], v136
	ds_read_b128 v[168:171], v136 offset:1024
	ds_read_b128 v[172:175], v137
	ds_read_b128 v[176:179], v137 offset:1024
	ds_read_b128 v[180:183], v138
	ds_read_b128 v[184:187], v138 offset:1024
	ds_read_b128 v[188:191], v139
	ds_read_b128 v[192:195], v139 offset:1024
	global_load_lds_dwordx4 v[132:133], off
	v_lshl_add_u64 v[162:163], v[132:133], 0, s[86:87]
	s_add_i32 m0, s10, 0xe000
	s_nop 0
	global_load_lds_dwordx4 v[162:163], off
	s_waitcnt lgkmcnt(8)
	s_barrier
	s_waitcnt lgkmcnt(0)
	s_waitcnt lgkmcnt(0)
	v_mfma_f32_16x16x32_bf16 v[124:127], v[158:161], v[140:143], v[124:127]
	v_mfma_f32_16x16x32_bf16 v[116:119], v[158:161], v[150:153], v[116:119]
	v_mfma_f32_16x16x32_bf16 v[108:111], v[172:175], v[140:143], v[108:111]
	v_mfma_f32_16x16x32_bf16 v[100:103], v[172:175], v[150:153], v[100:103]
	v_mfma_f32_16x16x32_bf16 v[92:95], v[180:183], v[140:143], v[92:95]
	v_mfma_f32_16x16x32_bf16 v[84:87], v[180:183], v[150:153], v[84:87]
	v_mfma_f32_16x16x32_bf16 v[76:79], v[188:191], v[140:143], v[76:79]
	v_mfma_f32_16x16x32_bf16 v[68:71], v[188:191], v[150:153], v[68:71]
	v_mfma_f32_16x16x32_bf16 v[124:127], v[168:171], v[146:149], v[124:127]
	v_mfma_f32_16x16x32_bf16 v[116:119], v[168:171], v[154:157], v[116:119]
	v_mfma_f32_16x16x32_bf16 v[108:111], v[176:179], v[146:149], v[108:111]
	v_mfma_f32_16x16x32_bf16 v[100:103], v[176:179], v[154:157], v[100:103]
	v_mfma_f32_16x16x32_bf16 v[92:95], v[184:187], v[146:149], v[92:95]
	v_mfma_f32_16x16x32_bf16 v[84:87], v[184:187], v[154:157], v[84:87]
	v_mfma_f32_16x16x32_bf16 v[76:79], v[192:195], v[146:149], v[76:79]
	v_mfma_f32_16x16x32_bf16 v[68:71], v[192:195], v[154:157], v[68:71]
	s_barrier
	s_add_i32 s37, s1, 2
	s_cmp_lt_u32 s1, 30
	s_cselect_b64 s[2:3], -1, 0
	s_and_b64 vcc, s[2:3], exec
	s_cselect_b32 s4, s27, s30
	s_cselect_b32 s3, 0, 0xffffffe0
	s_cselect_b32 s38, s0, s29
	s_cselect_b32 s40, s35, s34
	s_cselect_b32 s2, s31, s36
	s_ashr_i32 s5, s4, 31
	s_lshl_b64 s[4:5], s[4:5], 12
	s_add_u32 s39, s76, s4
	s_addc_u32 s41, s77, s5
	s_add_i32 s18, s37, s3
	s_lshl_b64 s[4:5], s[18:19], 7
	s_add_u32 s42, s39, s4
	s_addc_u32 s43, s41, s5
	s_mov_b32 m0, s11
	v_add_u32_e32 v144, s82, v135
	v_lshl_add_u64 v[162:163], s[42:43], 0, v[128:129]
	ds_read_b128 v[210:213], v144
	ds_read_b128 v[214:217], v144 offset:1024
	ds_read_b128 v[218:221], v144 offset:2048
	ds_read_b128 v[222:225], v144 offset:3072
	global_load_lds_dwordx4 v[162:163], off
	v_lshl_add_u64 v[162:163], v[162:163], 0, s[86:87]
	s_mov_b32 m0, s12
	s_nop 0
	global_load_lds_dwordx4 v[162:163], off
	s_barrier
	s_waitcnt lgkmcnt(0)
	s_waitcnt lgkmcnt(0)
	v_mfma_f32_16x16x32_bf16 v[60:63], v[158:161], v[210:213], v[60:63]
	v_mfma_f32_16x16x32_bf16 v[52:55], v[158:161], v[218:221], v[52:55]
	v_mfma_f32_16x16x32_bf16 v[44:47], v[172:175], v[210:213], v[44:47]
	v_mfma_f32_16x16x32_bf16 v[36:39], v[172:175], v[218:221], v[36:39]
	v_mfma_f32_16x16x32_bf16 v[28:31], v[180:183], v[210:213], v[28:31]
	v_mfma_f32_16x16x32_bf16 v[20:23], v[180:183], v[218:221], v[20:23]
	v_mfma_f32_16x16x32_bf16 v[12:15], v[188:191], v[210:213], v[12:15]
	v_mfma_f32_16x16x32_bf16 v[4:7], v[188:191], v[218:221], v[4:7]
	v_mfma_f32_16x16x32_bf16 v[60:63], v[168:171], v[214:217], v[60:63]
	v_mfma_f32_16x16x32_bf16 v[52:55], v[168:171], v[222:225], v[52:55]
	v_mfma_f32_16x16x32_bf16 v[44:47], v[176:179], v[214:217], v[44:47]
	v_mfma_f32_16x16x32_bf16 v[36:39], v[176:179], v[222:225], v[36:39]
	v_mfma_f32_16x16x32_bf16 v[28:31], v[184:187], v[214:217], v[28:31]
	v_mfma_f32_16x16x32_bf16 v[20:23], v[184:187], v[222:225], v[20:23]
	v_mfma_f32_16x16x32_bf16 v[12:15], v[192:195], v[214:217], v[12:15]
	v_mfma_f32_16x16x32_bf16 v[4:7], v[192:195], v[222:225], v[4:7]
	s_ashr_i32 s39, s38, 31
	s_lshl_b64 s[38:39], s[38:39], 12
	s_add_u32 s3, s75, s38
	s_addc_u32 s18, s78, s39
	s_add_u32 s38, s3, s4
	s_addc_u32 s39, s18, s5
	s_mov_b32 m0, s10
	v_lshl_add_u64 v[162:163], s[38:39], 0, v[128:129]
	s_barrier
	ds_read_b128 v[158:161], v136 offset:16384
	ds_read_b128 v[168:171], v136 offset:17408
	ds_read_b128 v[172:175], v137 offset:16384
	ds_read_b128 v[176:179], v137 offset:17408
	ds_read_b128 v[180:183], v138 offset:16384
	ds_read_b128 v[184:187], v138 offset:17408
	ds_read_b128 v[188:191], v139 offset:16384
	ds_read_b128 v[192:195], v139 offset:17408
	global_load_lds_dwordx4 v[162:163], off
	v_lshl_add_u64 v[162:163], v[162:163], 0, s[86:87]
	s_mov_b32 m0, s13
	s_nop 0
	global_load_lds_dwordx4 v[162:163], off
	s_barrier
	s_waitcnt lgkmcnt(0)
	s_waitcnt lgkmcnt(0)
	v_mfma_f32_16x16x32_bf16 v[120:123], v[158:161], v[140:143], v[120:123]
	v_mfma_f32_16x16x32_bf16 v[112:115], v[158:161], v[150:153], v[112:115]
	v_mfma_f32_16x16x32_bf16 v[104:107], v[172:175], v[140:143], v[104:107]
	v_mfma_f32_16x16x32_bf16 v[96:99], v[172:175], v[150:153], v[96:99]
	v_mfma_f32_16x16x32_bf16 v[88:91], v[180:183], v[140:143], v[88:91]
	v_mfma_f32_16x16x32_bf16 v[80:83], v[180:183], v[150:153], v[80:83]
	v_mfma_f32_16x16x32_bf16 v[72:75], v[188:191], v[140:143], v[72:75]
	v_mfma_f32_16x16x32_bf16 v[64:67], v[188:191], v[150:153], v[64:67]
	v_mfma_f32_16x16x32_bf16 v[120:123], v[168:171], v[146:149], v[120:123]
	v_mfma_f32_16x16x32_bf16 v[112:115], v[168:171], v[154:157], v[112:115]
	v_mfma_f32_16x16x32_bf16 v[104:107], v[176:179], v[146:149], v[104:107]
	v_mfma_f32_16x16x32_bf16 v[96:99], v[176:179], v[154:157], v[96:99]
	v_mfma_f32_16x16x32_bf16 v[88:91], v[184:187], v[146:149], v[88:91]
	v_mfma_f32_16x16x32_bf16 v[80:83], v[184:187], v[154:157], v[80:83]
	v_mfma_f32_16x16x32_bf16 v[72:75], v[192:195], v[146:149], v[72:75]
	v_mfma_f32_16x16x32_bf16 v[64:67], v[192:195], v[154:157], v[64:67]
	s_barrier
; #define LDA(dst, b, h) _Pragma("unroll") for (int m = 0; m < 4; ++m) _Pragma("unroll") for (int k = 0; k < 2; ++k) \
;     dst[m][k] = *reinterpret_cast<const bf16x8*>((char*)SA(b, h) + lds_byte(wr * 64 + m * 16 + fr, k * 32 + fq * 8))
; #define LDB(dst, b, h) _Pragma("unroll") for (int n = 0; n < 2; ++n) _Pragma("unroll") for (int k = 0; k < 2; ++k) \
;     dst[n][k] = *reinterpret_cast<const bf16x8*>((char*)SB(b, h) + lds_byte(wc * 32 + n * 16 + fr, k * 32 + fq * 8))
; #define MMA(ai, bj, At_, Bt_) do { __builtin_amdgcn_s_setprio(1); \
;     _Pragma("unroll") for (int m = 0; m < 4; ++m) _Pragma("unroll") for (int n = 0; n < 2; ++n) _Pragma("unroll") for (int k = 0; k < 2; ++k) \
;       acc[ai][bj][m][n] = __builtin_amdgcn_mfma_f32_16x16x32_bf16(At_[m][k], Bt_[n][k], acc[ai][bj][m][n], 0, 0, 0); \
;     __builtin_amdgcn_s_setprio(0); } while (0)
; #define WAIT_V(n) asm volatile("s_waitcnt vmcnt(" #n ")" ::: "memory")
; #define WAIT_L(n) asm volatile("s_waitcnt lgkmcnt(" #n ")" ::: "memory")
; #define BAR __builtin_amdgcn_s_barrier()
; #define SCHED __builtin_amdgcn_sched_barrier(0)
; #define STAGEW(P_, BASE, cur, nxt, kt_) do { const bool _wr = (kt_) >= nt; \
;     STAGE(P_, BASE, (_wr ? (nxt) : (cur)), (_wr ? (kt_) - nt : (kt_))); } while (0)
; template <int PRE> ...
;     ...
;     STAGEW(SB(0, 1), Bt, bcol + HALF, bcol_n + HALF, t + 2);
;     WAIT_V(6); BAR; MMA(1, 1, At, B1); BAR;
;     LDB(B0, 1, 0); SCHED; LDA(At, 1, 0); STAGEW(SA(0, 1), A, brow + HALF, brow_n + HALF, t + 2);
;     WAIT_L(8); BAR; WAIT_L(0); MMA(0, 0, At, B0); BAR; SCHED;
;     LDB(B1, 1, 1); STAGEW(SB(1, 0), Bt, bcol, bcol_n, t + 3);
;     BAR; WAIT_L(0); MMA(0, 1, At, B1); BAR;
;     LDA(At, 1, 1); STAGEW(SA(1, 0), A, brow, brow_n, t + 3);
;     BAR; WAIT_L(0); MMA(1, 0, At, B0); BAR; SCHED;
;     STAGEW(SB(1, 1), Bt, bcol + HALF, bcol_n + HALF, t + 3);
	s_ashr_i32 s41, s40, 31
	s_lshl_b64 s[38:39], s[40:41], 12
	s_add_u32 s3, s76, s38
	s_addc_u32 s18, s77, s39
	s_add_u32 s38, s3, s4
	s_addc_u32 s39, s18, s5
	s_mov_b32 m0, s14
	v_lshl_add_u64 v[140:141], s[38:39], 0, v[128:129]
	global_load_lds_dwordx4 v[140:141], off
	v_lshl_add_u64 v[140:141], v[140:141], 0, s[86:87]
	s_mov_b32 m0, s15
	s_nop 0
	global_load_lds_dwordx4 v[140:141], off
	s_waitcnt vmcnt(6)
	s_barrier
	v_mfma_f32_16x16x32_bf16 v[56:59], v[158:161], v[210:213], v[56:59]
	v_mfma_f32_16x16x32_bf16 v[48:51], v[158:161], v[218:221], v[48:51]
	v_mfma_f32_16x16x32_bf16 v[40:43], v[172:175], v[210:213], v[40:43]
	v_mfma_f32_16x16x32_bf16 v[32:35], v[172:175], v[218:221], v[32:35]
	v_mfma_f32_16x16x32_bf16 v[24:27], v[180:183], v[210:213], v[24:27]
	v_mfma_f32_16x16x32_bf16 v[16:19], v[180:183], v[218:221], v[16:19]
	v_mfma_f32_16x16x32_bf16 v[8:11], v[188:191], v[210:213], v[8:11]
	v_mfma_f32_16x16x32_bf16 v[0:3], v[188:191], v[218:221], v[0:3]
	v_mfma_f32_16x16x32_bf16 v[56:59], v[168:171], v[214:217], v[56:59]
	v_mfma_f32_16x16x32_bf16 v[48:51], v[168:171], v[222:225], v[48:51]
	v_mfma_f32_16x16x32_bf16 v[40:43], v[176:179], v[214:217], v[40:43]
	v_mfma_f32_16x16x32_bf16 v[32:35], v[176:179], v[222:225], v[32:35]
	v_mfma_f32_16x16x32_bf16 v[24:27], v[184:187], v[214:217], v[24:27]
	v_mfma_f32_16x16x32_bf16 v[16:19], v[184:187], v[222:225], v[16:19]
	v_mfma_f32_16x16x32_bf16 v[8:11], v[192:195], v[214:217], v[8:11]
	v_mfma_f32_16x16x32_bf16 v[0:3], v[192:195], v[222:225], v[0:3]
	v_add_u32_e32 v144, s83, v135
	s_barrier
	ds_read_b128 v[140:143], v144
	ds_read_b128 v[146:149], v144 offset:1024
	ds_read_b128 v[150:153], v144 offset:2048
	ds_read_b128 v[154:157], v144 offset:3072
	s_ashr_i32 s3, s2, 31
	s_lshl_b64 s[2:3], s[2:3], 12
	s_add_u32 s2, s75, s2
	s_addc_u32 s3, s78, s3
	s_add_u32 s2, s2, s4
	s_addc_u32 s3, s3, s5
	s_mov_b32 m0, s16
	v_lshl_add_u64 v[162:163], s[2:3], 0, v[128:129]
	ds_read_b128 v[158:161], v136 offset:32768
	ds_read_b128 v[168:171], v136 offset:33792
	ds_read_b128 v[172:175], v137 offset:32768
	ds_read_b128 v[176:179], v137 offset:33792
	ds_read_b128 v[180:183], v138 offset:32768
	ds_read_b128 v[184:187], v138 offset:33792
	ds_read_b128 v[188:191], v139 offset:32768
	ds_read_b128 v[192:195], v139 offset:33792
	global_load_lds_dwordx4 v[162:163], off
	v_lshl_add_u64 v[162:163], v[162:163], 0, s[86:87]
	s_mov_b32 m0, s17
	s_nop 0
	global_load_lds_dwordx4 v[162:163], off
	s_waitcnt lgkmcnt(8)
	s_barrier
	s_waitcnt lgkmcnt(0)
	s_waitcnt lgkmcnt(0)
	v_mfma_f32_16x16x32_bf16 v[124:127], v[158:161], v[140:143], v[124:127]
	v_mfma_f32_16x16x32_bf16 v[116:119], v[158:161], v[150:153], v[116:119]
	v_mfma_f32_16x16x32_bf16 v[108:111], v[172:175], v[140:143], v[108:111]
	v_mfma_f32_16x16x32_bf16 v[100:103], v[172:175], v[150:153], v[100:103]
	v_mfma_f32_16x16x32_bf16 v[92:95], v[180:183], v[140:143], v[92:95]
	v_mfma_f32_16x16x32_bf16 v[84:87], v[180:183], v[150:153], v[84:87]
	v_mfma_f32_16x16x32_bf16 v[76:79], v[188:191], v[140:143], v[76:79]
	v_mfma_f32_16x16x32_bf16 v[68:71], v[188:191], v[150:153], v[68:71]
	v_mfma_f32_16x16x32_bf16 v[124:127], v[168:171], v[146:149], v[124:127]
	v_mfma_f32_16x16x32_bf16 v[116:119], v[168:171], v[154:157], v[116:119]
	v_mfma_f32_16x16x32_bf16 v[108:111], v[176:179], v[146:149], v[108:111]
	v_mfma_f32_16x16x32_bf16 v[100:103], v[176:179], v[154:157], v[100:103]
	v_mfma_f32_16x16x32_bf16 v[92:95], v[184:187], v[146:149], v[92:95]
	v_mfma_f32_16x16x32_bf16 v[84:87], v[184:187], v[154:157], v[84:87]
	v_mfma_f32_16x16x32_bf16 v[76:79], v[192:195], v[146:149], v[76:79]
	v_mfma_f32_16x16x32_bf16 v[68:71], v[192:195], v[154:157], v[68:71]
	s_barrier
	s_cmp_lt_u32 s1, 29
	s_cselect_b32 s2, s27, s30
	s_cselect_b32 s5, 0, 0xffffffe0
	s_cselect_b32 s4, s0, s29
	s_cselect_b32 s38, s35, s34
	s_ashr_i32 s3, s2, 31
	s_lshl_b64 s[2:3], s[2:3], 12
	s_add_u32 s39, s76, s2
	s_addc_u32 s41, s77, s3
	s_add_i32 s1, s5, s1
	s_add_i32 s18, s1, 3
	s_lshl_b64 s[2:3], s[18:19], 7
	s_add_u32 s40, s39, s2
	s_addc_u32 s41, s41, s3
	s_mov_b32 m0, s20
	v_add_u32_e32 v144, s84, v135
	v_lshl_add_u64 v[162:163], s[40:41], 0, v[128:129]
	ds_read_b128 v[210:213], v144
	ds_read_b128 v[214:217], v144 offset:1024
	ds_read_b128 v[218:221], v144 offset:2048
	ds_read_b128 v[222:225], v144 offset:3072
	global_load_lds_dwordx4 v[162:163], off
	v_lshl_add_u64 v[162:163], v[162:163], 0, s[86:87]
	s_mov_b32 m0, s21
	s_nop 0
	global_load_lds_dwordx4 v[162:163], off
	s_barrier
; #define LDA(dst, b, h) _Pragma("unroll") for (int m = 0; m < 4; ++m) _Pragma("unroll") for (int k = 0; k < 2; ++k) \
;     dst[m][k] = *reinterpret_cast<const bf16x8*>((char*)SA(b, h) + lds_byte(wr * 64 + m * 16 + fr, k * 32 + fq * 8))
; #define LDB(dst, b, h) _Pragma("unroll") for (int n = 0; n < 2; ++n) _Pragma("unroll") for (int k = 0; k < 2; ++k) \
;     dst[n][k] = *reinterpret_cast<const bf16x8*>((char*)SB(b, h) + lds_byte(wc * 32 + n * 16 + fr, k * 32 + fq * 8))
; #define MMA(ai, bj, At_, Bt_) do { __builtin_amdgcn_s_setprio(1); \
;     _Pragma("unroll") for (int m = 0; m < 4; ++m) _Pragma("unroll") for (int n = 0; n < 2; ++n) _Pragma("unroll") for (int k = 0; k < 2; ++k) \
;       acc[ai][bj][m][n] = __builtin_amdgcn_mfma_f32_16x16x32_bf16(At_[m][k], Bt_[n][k], acc[ai][bj][m][n], 0, 0, 0); \
;     __builtin_amdgcn_s_setprio(0); } while (0)
; #define WAIT_V(n) asm volatile("s_waitcnt vmcnt(" #n ")" ::: "memory")
; #define WAIT_L(n) asm volatile("s_waitcnt lgkmcnt(" #n ")" ::: "memory")
; #define BAR __builtin_amdgcn_s_barrier()
; #define SCHED __builtin_amdgcn_sched_barrier(0)
; #define STAGEW(P_, BASE, cur, nxt, kt_) do { const bool _wr = (kt_) >= nt; \
;     STAGE(P_, BASE, (_wr ? (nxt) : (cur)), (_wr ? (kt_) - nt : (kt_))); } while (0)
; template <int PRE> ...
;     ...
;     LDB(B1, 1, 1); STAGEW(SB(1, 0), Bt, bcol, bcol_n, t + 3);
;     BAR; WAIT_L(0); MMA(0, 1, At, B1); BAR;
;     LDA(At, 1, 1); STAGEW(SA(1, 0), A, brow, brow_n, t + 3);
;     BAR; WAIT_L(0); MMA(1, 0, At, B0); BAR; SCHED;
;     STAGEW(SB(1, 1), Bt, bcol + HALF, bcol_n + HALF, t + 3);
;     WAIT_V(6); BAR; MMA(1, 1, At, B1); BAR;
;   }
;   if (wr == 0) BAR;
	s_waitcnt lgkmcnt(0)
	s_waitcnt lgkmcnt(0)
	v_mfma_f32_16x16x32_bf16 v[60:63], v[158:161], v[210:213], v[60:63]
	v_mfma_f32_16x16x32_bf16 v[52:55], v[158:161], v[218:221], v[52:55]
	v_mfma_f32_16x16x32_bf16 v[44:47], v[172:175], v[210:213], v[44:47]
	v_mfma_f32_16x16x32_bf16 v[36:39], v[172:175], v[218:221], v[36:39]
	v_mfma_f32_16x16x32_bf16 v[28:31], v[180:183], v[210:213], v[28:31]
	v_mfma_f32_16x16x32_bf16 v[20:23], v[180:183], v[218:221], v[20:23]
	v_mfma_f32_16x16x32_bf16 v[12:15], v[188:191], v[210:213], v[12:15]
	v_mfma_f32_16x16x32_bf16 v[4:7], v[188:191], v[218:221], v[4:7]
	v_mfma_f32_16x16x32_bf16 v[60:63], v[168:171], v[214:217], v[60:63]
	v_mfma_f32_16x16x32_bf16 v[52:55], v[168:171], v[222:225], v[52:55]
	v_mfma_f32_16x16x32_bf16 v[44:47], v[176:179], v[214:217], v[44:47]
	v_mfma_f32_16x16x32_bf16 v[36:39], v[176:179], v[222:225], v[36:39]
	v_mfma_f32_16x16x32_bf16 v[28:31], v[184:187], v[214:217], v[28:31]
	v_mfma_f32_16x16x32_bf16 v[20:23], v[184:187], v[222:225], v[20:23]
	v_mfma_f32_16x16x32_bf16 v[12:15], v[192:195], v[214:217], v[12:15]
	v_mfma_f32_16x16x32_bf16 v[4:7], v[192:195], v[222:225], v[4:7]
	s_ashr_i32 s5, s4, 31
	s_lshl_b64 s[4:5], s[4:5], 12
	s_add_u32 s1, s75, s4
	s_addc_u32 s5, s78, s5
	s_add_u32 s4, s1, s2
	s_addc_u32 s5, s5, s3
	s_mov_b32 m0, s22
	v_lshl_add_u64 v[162:163], s[4:5], 0, v[128:129]
	s_barrier
	ds_read_b128 v[158:161], v136 offset:49152
	ds_read_b128 v[168:171], v136 offset:50176
	ds_read_b128 v[172:175], v137 offset:49152
	ds_read_b128 v[176:179], v137 offset:50176
	ds_read_b128 v[180:183], v138 offset:49152
	ds_read_b128 v[184:187], v138 offset:50176
	ds_read_b128 v[188:191], v139 offset:49152
	ds_read_b128 v[192:195], v139 offset:50176
	global_load_lds_dwordx4 v[162:163], off
	v_lshl_add_u64 v[162:163], v[162:163], 0, s[86:87]
	s_mov_b32 m0, s23
	s_nop 0
	global_load_lds_dwordx4 v[162:163], off
	s_barrier
	s_waitcnt lgkmcnt(0)
	s_waitcnt lgkmcnt(0)
	v_mfma_f32_16x16x32_bf16 v[120:123], v[158:161], v[140:143], v[120:123]
	v_mfma_f32_16x16x32_bf16 v[112:115], v[158:161], v[150:153], v[112:115]
	v_mfma_f32_16x16x32_bf16 v[104:107], v[172:175], v[140:143], v[104:107]
	v_mfma_f32_16x16x32_bf16 v[96:99], v[172:175], v[150:153], v[96:99]
	v_mfma_f32_16x16x32_bf16 v[88:91], v[180:183], v[140:143], v[88:91]
	v_mfma_f32_16x16x32_bf16 v[80:83], v[180:183], v[150:153], v[80:83]
	v_mfma_f32_16x16x32_bf16 v[72:75], v[188:191], v[140:143], v[72:75]
	v_mfma_f32_16x16x32_bf16 v[64:67], v[188:191], v[150:153], v[64:67]
	v_mfma_f32_16x16x32_bf16 v[120:123], v[168:171], v[146:149], v[120:123]
	v_mfma_f32_16x16x32_bf16 v[112:115], v[168:171], v[154:157], v[112:115]
	v_mfma_f32_16x16x32_bf16 v[104:107], v[176:179], v[146:149], v[104:107]
	v_mfma_f32_16x16x32_bf16 v[96:99], v[176:179], v[154:157], v[96:99]
	v_mfma_f32_16x16x32_bf16 v[88:91], v[184:187], v[146:149], v[88:91]
	v_mfma_f32_16x16x32_bf16 v[80:83], v[184:187], v[154:157], v[80:83]
	v_mfma_f32_16x16x32_bf16 v[72:75], v[192:195], v[146:149], v[72:75]
	v_mfma_f32_16x16x32_bf16 v[64:67], v[192:195], v[154:157], v[64:67]
	s_barrier
	s_ashr_i32 s39, s38, 31
	s_lshl_b64 s[4:5], s[38:39], 12
	s_add_u32 s1, s76, s4
	s_addc_u32 s4, s77, s5
	s_add_u32 s2, s1, s2
	s_addc_u32 s3, s4, s3
	s_mov_b32 m0, s24
	v_lshl_add_u64 v[140:141], s[2:3], 0, v[128:129]
	global_load_lds_dwordx4 v[140:141], off
	v_lshl_add_u64 v[140:141], v[140:141], 0, s[86:87]
	s_mov_b32 m0, s25
	s_nop 0
	global_load_lds_dwordx4 v[140:141], off
	s_waitcnt vmcnt(6)
	s_barrier
	v_mfma_f32_16x16x32_bf16 v[56:59], v[158:161], v[210:213], v[56:59]
	v_mfma_f32_16x16x32_bf16 v[48:51], v[158:161], v[218:221], v[48:51]
	v_mfma_f32_16x16x32_bf16 v[40:43], v[172:175], v[210:213], v[40:43]
	v_mfma_f32_16x16x32_bf16 v[32:35], v[172:175], v[218:221], v[32:35]
	v_mfma_f32_16x16x32_bf16 v[24:27], v[180:183], v[210:213], v[24:27]
	v_mfma_f32_16x16x32_bf16 v[16:19], v[180:183], v[218:221], v[16:19]
	v_mfma_f32_16x16x32_bf16 v[8:11], v[188:191], v[210:213], v[8:11]
	v_mfma_f32_16x16x32_bf16 v[0:3], v[188:191], v[218:221], v[0:3]
	v_mfma_f32_16x16x32_bf16 v[56:59], v[168:171], v[214:217], v[56:59]
	v_mfma_f32_16x16x32_bf16 v[48:51], v[168:171], v[222:225], v[48:51]
	v_mfma_f32_16x16x32_bf16 v[40:43], v[176:179], v[214:217], v[40:43]
	v_mfma_f32_16x16x32_bf16 v[32:35], v[176:179], v[222:225], v[32:35]
	v_mfma_f32_16x16x32_bf16 v[24:27], v[184:187], v[214:217], v[24:27]
	v_mfma_f32_16x16x32_bf16 v[16:19], v[184:187], v[222:225], v[16:19]
	v_mfma_f32_16x16x32_bf16 v[8:11], v[192:195], v[214:217], v[8:11]
	v_mfma_f32_16x16x32_bf16 v[0:3], v[192:195], v[222:225], v[0:3]
	v_lshl_add_u64 v[132:133], v[132:133], 0, s[46:47]
	s_mov_b32 s1, s37
	s_barrier
	s_cbranch_vccnz .LBB0_1015
	v_readlane_b32 s34, v243, 2
	s_andn2_b64 vcc, exec, s[58:59]
	v_readlane_b32 s31, v244, 61
	v_readlane_b32 s35, v243, 3
	s_cbranch_vccnz .LBB0_1018
	s_barrier

; #define STAGE(P_, BASE, br, kt) do { const u16* _gb = (BASE) + (long)(br) * K + (long)(kt) * BK; \
;     _Pragma("unroll") for (int _i = 0; _i < 2; ++_i) { \
;       __builtin_amdgcn_global_load_lds((const unsigned*)(_gb + (long)_i * 64 * K + lane_off), \
;         (unsigned*)((char*)(P_) + lds_wbase + _i * 8192), 16, 0, 0); } } while (0)
; #define LDA(dst, b, h) _Pragma("unroll") for (int m = 0; m < 4; ++m) _Pragma("unroll") for (int k = 0; k < 2; ++k) \
;     dst[m][k] = *reinterpret_cast<const bf16x8*>((char*)SA(b, h) + lds_byte(wr * 64 + m * 16 + fr, k * 32 + fq * 8))
; #define LDB(dst, b, h) _Pragma("unroll") for (int n = 0; n < 2; ++n) _Pragma("unroll") for (int k = 0; k < 2; ++k) \
;     dst[n][k] = *reinterpret_cast<const bf16x8*>((char*)SB(b, h) + lds_byte(wc * 32 + n * 16 + fr, k * 32 + fq * 8))
; #define MMA(ai, bj, At_, Bt_) do { __builtin_amdgcn_s_setprio(1); \
;     _Pragma("unroll") for (int m = 0; m < 4; ++m) _Pragma("unroll") for (int n = 0; n < 2; ++n) _Pragma("unroll") for (int k = 0; k < 2; ++k) \
;       acc[ai][bj][m][n] = __builtin_amdgcn_mfma_f32_16x16x32_bf16(At_[m][k], Bt_[n][k], acc[ai][bj][m][n], 0, 0, 0); \
;     __builtin_amdgcn_s_setprio(0); } while (0)
; #define WAIT_V(n) asm volatile("s_waitcnt vmcnt(" #n ")" ::: "memory")
; #define WAIT_L(n) asm volatile("s_waitcnt lgkmcnt(" #n ")" ::: "memory")
; #define BAR __builtin_amdgcn_s_barrier()
; #define SCHED __builtin_amdgcn_sched_barrier(0)
; #define STAGEW(P_, BASE, cur, nxt, kt_) do { const bool _wr = (kt_) >= nt; \
;     STAGE(P_, BASE, (_wr ? (nxt) : (cur)), (_wr ? (kt_) - nt : (kt_))); } while (0)
; template <int PRE> ...
;     ...
;   for (int t = 0; t < nt; t += 2) {
;     LDB(B0, 0, 0); SCHED; LDA(At, 0, 0); STAGE(SA(1, 1), A, brow + HALF, t + 1);
;     WAIT_L(8); BAR; WAIT_L(0); MMA(0, 0, At, B0); BAR; SCHED;
;     LDB(B1, 0, 1); STAGEW(SB(0, 0), Bt, bcol, bcol_n, t + 2);
;     BAR; WAIT_L(0); MMA(0, 1, At, B1); BAR;
;     LDA(At, 0, 1); STAGEW(SA(0, 0), A, brow, brow_n, t + 2);
;     BAR; WAIT_L(0); MMA(1, 0, At, B0); BAR; SCHED;
;     STAGEW(SB(0, 1), Bt, bcol + HALF, bcol_n + HALF, t + 2);
;     WAIT_V(6); BAR; MMA(1, 1, At, B1); BAR;
.LBB0_1083:
	v_add_u32_e32 v142, s81, v151
	ds_read_b128 v[134:137], v142
	ds_read_b128 v[138:141], v142 offset:1024
	ds_read_b128 v[146:149], v142 offset:2048
	ds_read_b128 v[156:159], v142 offset:3072
	s_add_i32 m0, s2, 0xc000
	ds_read_b128 v[160:163], v144
	ds_read_b128 v[168:171], v144 offset:1024
	ds_read_b128 v[172:175], v152
	ds_read_b128 v[176:179], v152 offset:1024
	ds_read_b128 v[180:183], v153
	ds_read_b128 v[184:187], v153 offset:1024
	ds_read_b128 v[188:191], v154
	ds_read_b128 v[192:195], v154 offset:1024
	global_load_lds_dwordx4 v[128:129], off
	v_lshl_add_u64 v[142:143], v[128:129], 0, s[40:41]
	s_add_i32 m0, s2, 0xe000
	s_nop 0
	global_load_lds_dwordx4 v[142:143], off
	s_waitcnt lgkmcnt(8)
	s_barrier
	s_waitcnt lgkmcnt(0)
	s_waitcnt lgkmcnt(0)
	v_mfma_f32_16x16x32_bf16 v[124:127], v[160:163], v[134:137], v[124:127]
	v_mfma_f32_16x16x32_bf16 v[120:123], v[160:163], v[146:149], v[120:123]
	v_mfma_f32_16x16x32_bf16 v[116:119], v[172:175], v[134:137], v[116:119]
	v_mfma_f32_16x16x32_bf16 v[112:115], v[172:175], v[146:149], v[112:115]
	v_mfma_f32_16x16x32_bf16 v[108:111], v[180:183], v[134:137], v[108:111]
	v_mfma_f32_16x16x32_bf16 v[104:107], v[180:183], v[146:149], v[104:107]
	v_mfma_f32_16x16x32_bf16 v[100:103], v[188:191], v[134:137], v[100:103]
	v_mfma_f32_16x16x32_bf16 v[96:99], v[188:191], v[146:149], v[96:99]
	v_mfma_f32_16x16x32_bf16 v[124:127], v[168:171], v[138:141], v[124:127]
	v_mfma_f32_16x16x32_bf16 v[120:123], v[168:171], v[156:159], v[120:123]
	v_mfma_f32_16x16x32_bf16 v[116:119], v[176:179], v[138:141], v[116:119]
	v_mfma_f32_16x16x32_bf16 v[112:115], v[176:179], v[156:159], v[112:115]
	v_mfma_f32_16x16x32_bf16 v[108:111], v[184:187], v[138:141], v[108:111]
	v_mfma_f32_16x16x32_bf16 v[104:107], v[184:187], v[156:159], v[104:107]
	v_mfma_f32_16x16x32_bf16 v[100:103], v[192:195], v[138:141], v[100:103]
	v_mfma_f32_16x16x32_bf16 v[96:99], v[192:195], v[156:159], v[96:99]
	s_barrier
	s_add_i32 s34, s31, 2
	s_cmpk_lt_u32 s31, 0x56
	s_cselect_b64 s[0:1], -1, 0
	s_and_b64 vcc, s[0:1], exec
	s_cselect_b32 s0, s24, s26
	s_mulk_i32 s0, 0x1600
	s_cselect_b32 s18, 0, 0xffffffa8
	s_cselect_b32 s35, s23, s25
	s_cselect_b32 s38, s29, s28
	s_cselect_b32 s39, s27, s30
	s_ashr_i32 s1, s0, 31
	s_lshl_b64 s[0:1], s[0:1], 1
	s_add_u32 s36, s66, s0
	s_addc_u32 s37, s67, s1
	s_add_i32 s18, s34, s18
	s_lshl_b64 s[0:1], s[18:19], 7
	s_add_u32 s36, s36, s0
	v_add_u32_e32 v142, s82, v151
	s_addc_u32 s37, s37, s1
	s_mov_b32 m0, s3
	ds_read_b128 v[210:213], v142
	ds_read_b128 v[214:217], v142 offset:1024
	ds_read_b128 v[218:221], v142 offset:2048
	ds_read_b128 v[222:225], v142 offset:3072
	v_lshl_add_u64 v[142:143], s[36:37], 0, v[130:131]
	global_load_lds_dwordx4 v[142:143], off
	v_lshl_add_u64 v[142:143], v[142:143], 0, s[40:41]
	s_mov_b32 m0, s4
	s_nop 0
	global_load_lds_dwordx4 v[142:143], off
	s_barrier
	s_waitcnt lgkmcnt(0)
	s_waitcnt lgkmcnt(0)
	v_mfma_f32_16x16x32_bf16 v[92:95], v[160:163], v[210:213], v[92:95]
	v_mfma_f32_16x16x32_bf16 v[88:91], v[160:163], v[218:221], v[88:91]
	v_mfma_f32_16x16x32_bf16 v[84:87], v[172:175], v[210:213], v[84:87]
	v_mfma_f32_16x16x32_bf16 v[80:83], v[172:175], v[218:221], v[80:83]
	v_mfma_f32_16x16x32_bf16 v[76:79], v[180:183], v[210:213], v[76:79]
	v_mfma_f32_16x16x32_bf16 v[72:75], v[180:183], v[218:221], v[72:75]
	v_mfma_f32_16x16x32_bf16 v[68:71], v[188:191], v[210:213], v[68:71]
	v_mfma_f32_16x16x32_bf16 v[64:67], v[188:191], v[218:221], v[64:67]
	v_mfma_f32_16x16x32_bf16 v[92:95], v[168:171], v[214:217], v[92:95]
	v_mfma_f32_16x16x32_bf16 v[88:91], v[168:171], v[222:225], v[88:91]
	v_mfma_f32_16x16x32_bf16 v[84:87], v[176:179], v[214:217], v[84:87]
	v_mfma_f32_16x16x32_bf16 v[80:83], v[176:179], v[222:225], v[80:83]
	v_mfma_f32_16x16x32_bf16 v[76:79], v[184:187], v[214:217], v[76:79]
	v_mfma_f32_16x16x32_bf16 v[72:75], v[184:187], v[222:225], v[72:75]
	v_mfma_f32_16x16x32_bf16 v[68:71], v[192:195], v[214:217], v[68:71]
	v_mfma_f32_16x16x32_bf16 v[64:67], v[192:195], v[222:225], v[64:67]
	s_mul_hi_i32 s18, s35, 0x2c00
	s_mulk_i32 s35, 0x2c00
	s_add_u32 s35, s79, s35
	s_addc_u32 s18, s80, s18
	s_add_u32 s36, s35, s0
	s_addc_u32 s37, s18, s1
	s_mov_b32 m0, s2
	v_lshl_add_u64 v[142:143], s[36:37], 0, v[130:131]
	s_barrier
	ds_read_b128 v[160:163], v144 offset:16384
	ds_read_b128 v[168:171], v144 offset:17408
	ds_read_b128 v[172:175], v152 offset:16384
	ds_read_b128 v[176:179], v152 offset:17408
	ds_read_b128 v[180:183], v153 offset:16384
	ds_read_b128 v[184:187], v153 offset:17408
	ds_read_b128 v[188:191], v154 offset:16384
	ds_read_b128 v[192:195], v154 offset:17408
	global_load_lds_dwordx4 v[142:143], off
	v_lshl_add_u64 v[142:143], v[142:143], 0, s[40:41]
	s_mov_b32 m0, s5
	s_nop 0
	global_load_lds_dwordx4 v[142:143], off
	s_barrier
	s_waitcnt lgkmcnt(0)
	s_waitcnt lgkmcnt(0)
	v_mfma_f32_16x16x32_bf16 v[60:63], v[160:163], v[134:137], v[60:63]
	v_mfma_f32_16x16x32_bf16 v[56:59], v[160:163], v[146:149], v[56:59]
	v_mfma_f32_16x16x32_bf16 v[52:55], v[172:175], v[134:137], v[52:55]
	v_mfma_f32_16x16x32_bf16 v[48:51], v[172:175], v[146:149], v[48:51]
	v_mfma_f32_16x16x32_bf16 v[44:47], v[180:183], v[134:137], v[44:47]
	v_mfma_f32_16x16x32_bf16 v[40:43], v[180:183], v[146:149], v[40:43]
	v_mfma_f32_16x16x32_bf16 v[36:39], v[188:191], v[134:137], v[36:39]
	v_mfma_f32_16x16x32_bf16 v[32:35], v[188:191], v[146:149], v[32:35]
	v_mfma_f32_16x16x32_bf16 v[60:63], v[168:171], v[138:141], v[60:63]
	v_mfma_f32_16x16x32_bf16 v[56:59], v[168:171], v[156:159], v[56:59]
	v_mfma_f32_16x16x32_bf16 v[52:55], v[176:179], v[138:141], v[52:55]
	v_mfma_f32_16x16x32_bf16 v[48:51], v[176:179], v[156:159], v[48:51]
	v_mfma_f32_16x16x32_bf16 v[44:47], v[184:187], v[138:141], v[44:47]
	v_mfma_f32_16x16x32_bf16 v[40:43], v[184:187], v[156:159], v[40:43]
	v_mfma_f32_16x16x32_bf16 v[36:39], v[192:195], v[138:141], v[36:39]
	v_mfma_f32_16x16x32_bf16 v[32:35], v[192:195], v[156:159], v[32:35]
	s_barrier
; #define LDA(dst, b, h) _Pragma("unroll") for (int m = 0; m < 4; ++m) _Pragma("unroll") for (int k = 0; k < 2; ++k) \
;     dst[m][k] = *reinterpret_cast<const bf16x8*>((char*)SA(b, h) + lds_byte(wr * 64 + m * 16 + fr, k * 32 + fq * 8))
; #define LDB(dst, b, h) _Pragma("unroll") for (int n = 0; n < 2; ++n) _Pragma("unroll") for (int k = 0; k < 2; ++k) \
;     dst[n][k] = *reinterpret_cast<const bf16x8*>((char*)SB(b, h) + lds_byte(wc * 32 + n * 16 + fr, k * 32 + fq * 8))
; #define MMA(ai, bj, At_, Bt_) do { __builtin_amdgcn_s_setprio(1); \
;     _Pragma("unroll") for (int m = 0; m < 4; ++m) _Pragma("unroll") for (int n = 0; n < 2; ++n) _Pragma("unroll") for (int k = 0; k < 2; ++k) \
;       acc[ai][bj][m][n] = __builtin_amdgcn_mfma_f32_16x16x32_bf16(At_[m][k], Bt_[n][k], acc[ai][bj][m][n], 0, 0, 0); \
;     __builtin_amdgcn_s_setprio(0); } while (0)
; #define WAIT_V(n) asm volatile("s_waitcnt vmcnt(" #n ")" ::: "memory")
; #define WAIT_L(n) asm volatile("s_waitcnt lgkmcnt(" #n ")" ::: "memory")
; #define BAR __builtin_amdgcn_s_barrier()
; #define SCHED __builtin_amdgcn_sched_barrier(0)
; #define STAGEW(P_, BASE, cur, nxt, kt_) do { const bool _wr = (kt_) >= nt; \
;     STAGE(P_, BASE, (_wr ? (nxt) : (cur)), (_wr ? (kt_) - nt : (kt_))); } while (0)
; template <int PRE> ...
;     ...
;     STAGEW(SB(0, 1), Bt, bcol + HALF, bcol_n + HALF, t + 2);
;     WAIT_V(6); BAR; MMA(1, 1, At, B1); BAR;
;     LDB(B0, 1, 0); SCHED; LDA(At, 1, 0); STAGEW(SA(0, 1), A, brow + HALF, brow_n + HALF, t + 2);
;     WAIT_L(8); BAR; WAIT_L(0); MMA(0, 0, At, B0); BAR; SCHED;
;     LDB(B1, 1, 1); STAGEW(SB(1, 0), Bt, bcol, bcol_n, t + 3);
;     BAR; WAIT_L(0); MMA(0, 1, At, B1); BAR;
;     LDA(At, 1, 1); STAGEW(SA(1, 0), A, brow, brow_n, t + 3);
;     BAR; WAIT_L(0); MMA(1, 0, At, B0); BAR; SCHED;
;     STAGEW(SB(1, 1), Bt, bcol + HALF, bcol_n + HALF, t + 3);
	s_mul_i32 s36, s38, 0x1600
	s_ashr_i32 s37, s36, 31
	s_lshl_b64 s[36:37], s[36:37], 1
	s_add_u32 s18, s66, s36
	s_addc_u32 s35, s67, s37
	s_add_u32 s36, s18, s0
	s_addc_u32 s37, s35, s1
	s_mov_b32 m0, s10
	v_lshl_add_u64 v[134:135], s[36:37], 0, v[130:131]
	global_load_lds_dwordx4 v[134:135], off
	v_lshl_add_u64 v[134:135], v[134:135], 0, s[40:41]
	s_mov_b32 m0, s11
	s_nop 0
	global_load_lds_dwordx4 v[134:135], off
	s_waitcnt vmcnt(6)
	s_barrier
	v_mfma_f32_16x16x32_bf16 v[28:31], v[160:163], v[210:213], v[28:31]
	v_mfma_f32_16x16x32_bf16 v[24:27], v[160:163], v[218:221], v[24:27]
	v_mfma_f32_16x16x32_bf16 v[20:23], v[172:175], v[210:213], v[20:23]
	v_mfma_f32_16x16x32_bf16 v[16:19], v[172:175], v[218:221], v[16:19]
	v_mfma_f32_16x16x32_bf16 v[12:15], v[180:183], v[210:213], v[12:15]
	v_mfma_f32_16x16x32_bf16 v[8:11], v[180:183], v[218:221], v[8:11]
	v_mfma_f32_16x16x32_bf16 v[4:7], v[188:191], v[210:213], v[4:7]
	v_mfma_f32_16x16x32_bf16 v[0:3], v[188:191], v[218:221], v[0:3]
	v_mfma_f32_16x16x32_bf16 v[28:31], v[168:171], v[214:217], v[28:31]
	v_mfma_f32_16x16x32_bf16 v[24:27], v[168:171], v[222:225], v[24:27]
	v_mfma_f32_16x16x32_bf16 v[20:23], v[176:179], v[214:217], v[20:23]
	v_mfma_f32_16x16x32_bf16 v[16:19], v[176:179], v[222:225], v[16:19]
	v_mfma_f32_16x16x32_bf16 v[12:15], v[184:187], v[214:217], v[12:15]
	v_mfma_f32_16x16x32_bf16 v[8:11], v[184:187], v[222:225], v[8:11]
	v_mfma_f32_16x16x32_bf16 v[4:7], v[192:195], v[214:217], v[4:7]
	v_mfma_f32_16x16x32_bf16 v[0:3], v[192:195], v[222:225], v[0:3]
	v_add_u32_e32 v142, s83, v151
	s_barrier
	ds_read_b128 v[134:137], v142
	ds_read_b128 v[138:141], v142 offset:1024
	ds_read_b128 v[146:149], v142 offset:2048
	ds_read_b128 v[156:159], v142 offset:3072
	s_mul_hi_i32 s18, s39, 0x2c00
	s_mulk_i32 s39, 0x2c00
	s_add_u32 s35, s79, s39
	s_addc_u32 s18, s80, s18
	s_add_u32 s0, s35, s0
	s_addc_u32 s1, s18, s1
	s_mov_b32 m0, s12
	v_lshl_add_u64 v[142:143], s[0:1], 0, v[130:131]
	ds_read_b128 v[160:163], v144 offset:32768
	ds_read_b128 v[168:171], v144 offset:33792
	ds_read_b128 v[172:175], v152 offset:32768
	ds_read_b128 v[176:179], v152 offset:33792
	ds_read_b128 v[180:183], v153 offset:32768
	ds_read_b128 v[184:187], v153 offset:33792
	ds_read_b128 v[188:191], v154 offset:32768
	ds_read_b128 v[192:195], v154 offset:33792
	global_load_lds_dwordx4 v[142:143], off
	v_lshl_add_u64 v[142:143], v[142:143], 0, s[40:41]
	s_mov_b32 m0, s13
	s_nop 0
	global_load_lds_dwordx4 v[142:143], off
	s_waitcnt lgkmcnt(8)
	s_barrier
	s_waitcnt lgkmcnt(0)
	s_waitcnt lgkmcnt(0)
	v_mfma_f32_16x16x32_bf16 v[124:127], v[160:163], v[134:137], v[124:127]
	v_mfma_f32_16x16x32_bf16 v[120:123], v[160:163], v[146:149], v[120:123]
	v_mfma_f32_16x16x32_bf16 v[116:119], v[172:175], v[134:137], v[116:119]
	v_mfma_f32_16x16x32_bf16 v[112:115], v[172:175], v[146:149], v[112:115]
	v_mfma_f32_16x16x32_bf16 v[108:111], v[180:183], v[134:137], v[108:111]
	v_mfma_f32_16x16x32_bf16 v[104:107], v[180:183], v[146:149], v[104:107]
	v_mfma_f32_16x16x32_bf16 v[100:103], v[188:191], v[134:137], v[100:103]
	v_mfma_f32_16x16x32_bf16 v[96:99], v[188:191], v[146:149], v[96:99]
	v_mfma_f32_16x16x32_bf16 v[124:127], v[168:171], v[138:141], v[124:127]
	v_mfma_f32_16x16x32_bf16 v[120:123], v[168:171], v[156:159], v[120:123]
	v_mfma_f32_16x16x32_bf16 v[116:119], v[176:179], v[138:141], v[116:119]
	v_mfma_f32_16x16x32_bf16 v[112:115], v[176:179], v[156:159], v[112:115]
	v_mfma_f32_16x16x32_bf16 v[108:111], v[184:187], v[138:141], v[108:111]
	v_mfma_f32_16x16x32_bf16 v[104:107], v[184:187], v[156:159], v[104:107]
	v_mfma_f32_16x16x32_bf16 v[100:103], v[192:195], v[138:141], v[100:103]
	v_mfma_f32_16x16x32_bf16 v[96:99], v[192:195], v[156:159], v[96:99]
	s_barrier
	s_cmpk_lt_u32 s31, 0x55
	s_cselect_b32 s0, s24, s26
	s_mulk_i32 s0, 0x1600
	s_cselect_b32 s18, 0, 0xffffffa8
	s_cselect_b32 s35, s23, s25
	s_cselect_b32 s38, s29, s28
	s_ashr_i32 s1, s0, 31
	s_lshl_b64 s[0:1], s[0:1], 1
	s_add_u32 s36, s66, s0
	s_addc_u32 s37, s67, s1
	s_add_i32 s0, s18, s31
	s_add_i32 s18, s0, 3
	s_lshl_b64 s[0:1], s[18:19], 7
	s_add_u32 s36, s36, s0
	v_add_u32_e32 v142, s84, v151
	s_addc_u32 s37, s37, s1
	s_mov_b32 m0, s14
	ds_read_b128 v[210:213], v142
	ds_read_b128 v[214:217], v142 offset:1024
	ds_read_b128 v[218:221], v142 offset:2048
	ds_read_b128 v[222:225], v142 offset:3072
	v_lshl_add_u64 v[142:143], s[36:37], 0, v[130:131]
	global_load_lds_dwordx4 v[142:143], off
	v_lshl_add_u64 v[142:143], v[142:143], 0, s[40:41]
	s_mov_b32 m0, s15
	s_nop 0
	global_load_lds_dwordx4 v[142:143], off
	s_barrier
; #define LDA(dst, b, h) _Pragma("unroll") for (int m = 0; m < 4; ++m) _Pragma("unroll") for (int k = 0; k < 2; ++k) \
;     dst[m][k] = *reinterpret_cast<const bf16x8*>((char*)SA(b, h) + lds_byte(wr * 64 + m * 16 + fr, k * 32 + fq * 8))
; #define LDB(dst, b, h) _Pragma("unroll") for (int n = 0; n < 2; ++n) _Pragma("unroll") for (int k = 0; k < 2; ++k) \
;     dst[n][k] = *reinterpret_cast<const bf16x8*>((char*)SB(b, h) + lds_byte(wc * 32 + n * 16 + fr, k * 32 + fq * 8))
; #define MMA(ai, bj, At_, Bt_) do { __builtin_amdgcn_s_setprio(1); \
;     _Pragma("unroll") for (int m = 0; m < 4; ++m) _Pragma("unroll") for (int n = 0; n < 2; ++n) _Pragma("unroll") for (int k = 0; k < 2; ++k) \
;       acc[ai][bj][m][n] = __builtin_amdgcn_mfma_f32_16x16x32_bf16(At_[m][k], Bt_[n][k], acc[ai][bj][m][n], 0, 0, 0); \
;     __builtin_amdgcn_s_setprio(0); } while (0)
; #define WAIT_V(n) asm volatile("s_waitcnt vmcnt(" #n ")" ::: "memory")
; #define WAIT_L(n) asm volatile("s_waitcnt lgkmcnt(" #n ")" ::: "memory")
; #define BAR __builtin_amdgcn_s_barrier()
; #define SCHED __builtin_amdgcn_sched_barrier(0)
; #define STAGEW(P_, BASE, cur, nxt, kt_) do { const bool _wr = (kt_) >= nt; \
;     STAGE(P_, BASE, (_wr ? (nxt) : (cur)), (_wr ? (kt_) - nt : (kt_))); } while (0)
; template <int PRE> ...
;     ...
;     LDB(B1, 1, 1); STAGEW(SB(1, 0), Bt, bcol, bcol_n, t + 3);
;     BAR; WAIT_L(0); MMA(0, 1, At, B1); BAR;
;     LDA(At, 1, 1); STAGEW(SA(1, 0), A, brow, brow_n, t + 3);
;     BAR; WAIT_L(0); MMA(1, 0, At, B0); BAR; SCHED;
;     STAGEW(SB(1, 1), Bt, bcol + HALF, bcol_n + HALF, t + 3);
;     WAIT_V(6); BAR; MMA(1, 1, At, B1); BAR;
;   }
;   if (wr == 0) BAR;
	s_waitcnt lgkmcnt(0)
	s_waitcnt lgkmcnt(0)
	v_mfma_f32_16x16x32_bf16 v[92:95], v[160:163], v[210:213], v[92:95]
	v_mfma_f32_16x16x32_bf16 v[88:91], v[160:163], v[218:221], v[88:91]
	v_mfma_f32_16x16x32_bf16 v[84:87], v[172:175], v[210:213], v[84:87]
	v_mfma_f32_16x16x32_bf16 v[80:83], v[172:175], v[218:221], v[80:83]
	v_mfma_f32_16x16x32_bf16 v[76:79], v[180:183], v[210:213], v[76:79]
	v_mfma_f32_16x16x32_bf16 v[72:75], v[180:183], v[218:221], v[72:75]
	v_mfma_f32_16x16x32_bf16 v[68:71], v[188:191], v[210:213], v[68:71]
	v_mfma_f32_16x16x32_bf16 v[64:67], v[188:191], v[218:221], v[64:67]
	v_mfma_f32_16x16x32_bf16 v[92:95], v[168:171], v[214:217], v[92:95]
	v_mfma_f32_16x16x32_bf16 v[88:91], v[168:171], v[222:225], v[88:91]
	v_mfma_f32_16x16x32_bf16 v[84:87], v[176:179], v[214:217], v[84:87]
	v_mfma_f32_16x16x32_bf16 v[80:83], v[176:179], v[222:225], v[80:83]
	v_mfma_f32_16x16x32_bf16 v[76:79], v[184:187], v[214:217], v[76:79]
	v_mfma_f32_16x16x32_bf16 v[72:75], v[184:187], v[222:225], v[72:75]
	v_mfma_f32_16x16x32_bf16 v[68:71], v[192:195], v[214:217], v[68:71]
	v_mfma_f32_16x16x32_bf16 v[64:67], v[192:195], v[222:225], v[64:67]
	s_mul_hi_i32 s18, s35, 0x2c00
	s_mulk_i32 s35, 0x2c00
	s_add_u32 s31, s79, s35
	s_addc_u32 s18, s80, s18
	s_add_u32 s36, s31, s0
	s_addc_u32 s37, s18, s1
	s_mov_b32 m0, s16
	v_lshl_add_u64 v[142:143], s[36:37], 0, v[130:131]
	s_barrier
	ds_read_b128 v[160:163], v144 offset:49152
	ds_read_b128 v[168:171], v144 offset:50176
	ds_read_b128 v[172:175], v152 offset:49152
	ds_read_b128 v[176:179], v152 offset:50176
	ds_read_b128 v[180:183], v153 offset:49152
	ds_read_b128 v[184:187], v153 offset:50176
	ds_read_b128 v[188:191], v154 offset:49152
	ds_read_b128 v[192:195], v154 offset:50176
	global_load_lds_dwordx4 v[142:143], off
	v_lshl_add_u64 v[142:143], v[142:143], 0, s[40:41]
	s_mov_b32 m0, s17
	s_nop 0
	global_load_lds_dwordx4 v[142:143], off
	s_barrier
	s_waitcnt lgkmcnt(0)
	s_waitcnt lgkmcnt(0)
	v_mfma_f32_16x16x32_bf16 v[60:63], v[160:163], v[134:137], v[60:63]
	v_mfma_f32_16x16x32_bf16 v[56:59], v[160:163], v[146:149], v[56:59]
	v_mfma_f32_16x16x32_bf16 v[52:55], v[172:175], v[134:137], v[52:55]
	v_mfma_f32_16x16x32_bf16 v[48:51], v[172:175], v[146:149], v[48:51]
	v_mfma_f32_16x16x32_bf16 v[44:47], v[180:183], v[134:137], v[44:47]
	v_mfma_f32_16x16x32_bf16 v[40:43], v[180:183], v[146:149], v[40:43]
	v_mfma_f32_16x16x32_bf16 v[36:39], v[188:191], v[134:137], v[36:39]
	v_mfma_f32_16x16x32_bf16 v[32:35], v[188:191], v[146:149], v[32:35]
	v_mfma_f32_16x16x32_bf16 v[60:63], v[168:171], v[138:141], v[60:63]
	v_mfma_f32_16x16x32_bf16 v[56:59], v[168:171], v[156:159], v[56:59]
	v_mfma_f32_16x16x32_bf16 v[52:55], v[176:179], v[138:141], v[52:55]
	v_mfma_f32_16x16x32_bf16 v[48:51], v[176:179], v[156:159], v[48:51]
	v_mfma_f32_16x16x32_bf16 v[44:47], v[184:187], v[138:141], v[44:47]
	v_mfma_f32_16x16x32_bf16 v[40:43], v[184:187], v[156:159], v[40:43]
	v_mfma_f32_16x16x32_bf16 v[36:39], v[192:195], v[138:141], v[36:39]
	v_mfma_f32_16x16x32_bf16 v[32:35], v[192:195], v[156:159], v[32:35]
	s_barrier
	s_mul_i32 s36, s38, 0x1600
	s_ashr_i32 s37, s36, 31
	s_lshl_b64 s[36:37], s[36:37], 1
	s_add_u32 s18, s66, s36
	s_addc_u32 s31, s67, s37
	s_add_u32 s0, s18, s0
	s_addc_u32 s1, s31, s1
	s_mov_b32 m0, s20
	v_lshl_add_u64 v[134:135], s[0:1], 0, v[130:131]
	global_load_lds_dwordx4 v[134:135], off
	v_lshl_add_u64 v[134:135], v[134:135], 0, s[40:41]
	s_mov_b32 m0, s21
	s_nop 0
	global_load_lds_dwordx4 v[134:135], off
	s_waitcnt vmcnt(6)
	s_barrier
	v_mfma_f32_16x16x32_bf16 v[28:31], v[160:163], v[210:213], v[28:31]
	v_mfma_f32_16x16x32_bf16 v[24:27], v[160:163], v[218:221], v[24:27]
	v_mfma_f32_16x16x32_bf16 v[20:23], v[172:175], v[210:213], v[20:23]
	v_mfma_f32_16x16x32_bf16 v[16:19], v[172:175], v[218:221], v[16:19]
	v_mfma_f32_16x16x32_bf16 v[12:15], v[180:183], v[210:213], v[12:15]
	v_mfma_f32_16x16x32_bf16 v[8:11], v[180:183], v[218:221], v[8:11]
	v_mfma_f32_16x16x32_bf16 v[4:7], v[188:191], v[210:213], v[4:7]
	v_mfma_f32_16x16x32_bf16 v[0:3], v[188:191], v[218:221], v[0:3]
	v_mfma_f32_16x16x32_bf16 v[28:31], v[168:171], v[214:217], v[28:31]
	v_mfma_f32_16x16x32_bf16 v[24:27], v[168:171], v[222:225], v[24:27]
	v_mfma_f32_16x16x32_bf16 v[20:23], v[176:179], v[214:217], v[20:23]
	v_mfma_f32_16x16x32_bf16 v[16:19], v[176:179], v[222:225], v[16:19]
	v_mfma_f32_16x16x32_bf16 v[12:15], v[184:187], v[214:217], v[12:15]
	v_mfma_f32_16x16x32_bf16 v[8:11], v[184:187], v[222:225], v[8:11]
	v_mfma_f32_16x16x32_bf16 v[4:7], v[192:195], v[214:217], v[4:7]
	v_mfma_f32_16x16x32_bf16 v[0:3], v[192:195], v[222:225], v[0:3]
	v_lshl_add_u64 v[128:129], v[128:129], 0, s[46:47]
	s_mov_b32 s31, s34
	s_barrier
	s_cbranch_vccnz .LBB0_1083
	s_andn2_b64 vcc, exec, s[58:59]
	s_cbranch_vccnz .LBB0_1086
	s_barrier
